# EpiNormResNorm step 1: base quads prefetched two row-groups ahead by LDS-DMA into a per-wave 3-slot ring, original serialized loads become ds_read_b128 (both epilogue copies)
# speedup vs baseline: 1.0179x; 1.0139x over previous
;     __device__ __forceinline__ void fused(f32x4 (&acc)[2][2][4][2], const Unit& u, int wr, int wc, int fr, int fq, PG8_LAS unsigned char* lds, int wid, int lane) const {
;     ...
;         const int col0 = u.pn * BM + wc * 32 + 4 * fq;
;         f32x4 gv[2][2];
; #pragma unroll
;         for (int bj = 0; bj < 2; ++bj)
; #pragma unroll
;             for (int n = 0; n < 2; ++n) gv[bj][n] = *(const f32x4*)(g1 + col0 + bj * HALF + n * 16);
; #pragma unroll
;         for (int ai = 0; ai < 2; ++ai)
; #pragma unroll
;             for (int m = 0; m < 4; ++m) { const int r = ai * HALF + wr * 64 + m * 16 + fr; const size_t off = (size_t)(u.pm * BM + r) * 1024 + col0;
;                 float s0 = 0.f, s1 = 0.f, s2 = 0.f, s3 = 0.f;
; #pragma unroll
;                 for (int bj = 0; bj < 2; ++bj)
; #pragma unroll
;                     for (int n = 0; n < 2; ++n) { const f32x4 bs = *(const f32x4*)(base + off + bj * HALF + n * 16), a = acc[ai][bj][m][n], ag = a * gv[bj][n];
;                         s0 += (a[0] * a[0] + a[1] * a[1]) + (a[2] * a[2] + a[3] * a[3]); s1 += (bs[0] * bs[0] + bs[1] * bs[1]) + (bs[2] * bs[2] + bs[3] * bs[3]);
;                         s2 += (bs[0] * ag[0] + bs[1] * ag[1]) + (bs[2] * ag[2] + bs[3] * ag[3]); s3 += (ag[0] * ag[0] + ag[1] * ag[1]) + (ag[2] * ag[2] + ag[3] * ag[3]); }
.LBB0_831:
	s_ashr_i32 s17, s16, 31
	s_lshl_b64 s[4:5], s[16:17], 14
	s_add_u32 s28, s28, s4
	s_addc_u32 s29, s29, s5
	s_lshl_b32 s4, s25, 5
	s_lshl_b32 s5, s24, 8
	s_or_b32 s4, s5, s4
	v_lshrrev_b32_e32 v33, 2, v195
	v_and_or_b32 v34, v33, 12, s4
	v_ashrrev_i32_e32 v35, 31, v34
	v_lshlrev_b64 v[148:149], 2, v[34:35]
	v_lshl_add_u64 v[92:93], s[28:29], 0, v[148:149]
	s_mov_b64 s[4:5], 0x1000
	v_lshl_add_u64 v[94:95], v[92:93], 0, s[4:5]
	s_movk_i32 s4, 0x1000
	v_add_co_u32_e32 v92, vcc, s4, v92
	v_and_b32_e32 v150, 64, v233
	s_nop 0
	v_addc_co_u32_e32 v93, vcc, 0, v93, vcc
	v_xor_b32_e32 v33, 16, v233
	v_add_u32_e32 v150, 64, v150
	s_lshl_b32 s17, s18, 8
	v_cmp_lt_i32_e32 vcc, v33, v150
	v_add_u32_e32 v166, s17, v237
	v_ashrrev_i32_e32 v167, 31, v166
	v_cndmask_b32_e32 v33, v233, v33, vcc
	v_lshlrev_b32_e32 v240, 2, v33
	v_xor_b32_e32 v33, 32, v233
	v_cmp_lt_i32_e32 vcc, v33, v150
	v_lshlrev_b64 v[150:151], 12, v[166:167]
	v_lshl_add_u64 v[150:151], s[26:27], 0, v[150:151]
	v_lshl_add_u64 v[164:165], v[150:151], 0, v[148:149]
	s_barrier
	global_load_dwordx4 v[116:119], v[92:93], off
	global_load_dwordx4 v[104:107], v[94:95], off offset:64
	global_load_dwordx4 v[100:103], v[94:95], off offset:512
	s_nop 0
	global_load_dwordx4 v[92:95], v[94:95], off offset:576
	v_pk_mul_f32 v[152:153], v[146:147], v[146:147]
	v_readfirstlane_b32 s72, v228
	s_nop 3
	s_lshr_b32 s72, s72, 6
	s_mul_i32 s72, s72, 0x3000
	s_add_i32 s72, s72, 0x5000
	s_mov_b64 s[98:99], 0x0
	v_lshl_add_u64 v[160:161], v[164:165], 0, s[98:99]
	s_add_i32 m0, s72, 0x0
	s_nop 0
	global_load_lds_dwordx4 v[160:161], off
	s_mov_b64 s[98:99], 0x40
	v_lshl_add_u64 v[160:161], v[164:165], 0, s[98:99]
	s_add_i32 m0, s72, 0x400
	s_nop 0
	global_load_lds_dwordx4 v[160:161], off
	s_mov_b64 s[98:99], 0x200
	v_lshl_add_u64 v[160:161], v[164:165], 0, s[98:99]
	s_add_i32 m0, s72, 0x800
	s_nop 0
	global_load_lds_dwordx4 v[160:161], off
	s_mov_b64 s[98:99], 0x240
	v_lshl_add_u64 v[160:161], v[164:165], 0, s[98:99]
	s_add_i32 m0, s72, 0xc00
	s_nop 0
	global_load_lds_dwordx4 v[160:161], off
	s_mov_b64 s[98:99], 0x10000
	v_lshl_add_u64 v[160:161], v[164:165], 0, s[98:99]
	s_add_i32 m0, s72, 0x1000
	s_nop 0
	global_load_lds_dwordx4 v[160:161], off
	s_mov_b64 s[98:99], 0x10040
	v_lshl_add_u64 v[160:161], v[164:165], 0, s[98:99]
	s_add_i32 m0, s72, 0x1400
	s_nop 0
	global_load_lds_dwordx4 v[160:161], off
	s_mov_b64 s[98:99], 0x10200
	v_lshl_add_u64 v[160:161], v[164:165], 0, s[98:99]
	s_add_i32 m0, s72, 0x1800
	s_nop 0
	global_load_lds_dwordx4 v[160:161], off
	s_mov_b64 s[98:99], 0x10240
	v_lshl_add_u64 v[160:161], v[164:165], 0, s[98:99]
	s_add_i32 m0, s72, 0x1c00
	s_nop 0
	global_load_lds_dwordx4 v[160:161], off
	s_mov_b64 s[98:99], 0x20000
	v_lshl_add_u64 v[160:161], v[164:165], 0, s[98:99]
	s_add_i32 m0, s72, 0x2000
	s_nop 0
	global_load_lds_dwordx4 v[160:161], off
	s_mov_b64 s[98:99], 0x20040
	v_lshl_add_u64 v[160:161], v[164:165], 0, s[98:99]
	s_add_i32 m0, s72, 0x2400
	s_nop 0
	global_load_lds_dwordx4 v[160:161], off
	s_mov_b64 s[98:99], 0x20200
	v_lshl_add_u64 v[160:161], v[164:165], 0, s[98:99]
	s_add_i32 m0, s72, 0x2800
	s_nop 0
	global_load_lds_dwordx4 v[160:161], off
	s_mov_b64 s[98:99], 0x20240
	v_lshl_add_u64 v[160:161], v[164:165], 0, s[98:99]
	s_add_i32 m0, s72, 0x2c00
	s_nop 0
	global_load_lds_dwordx4 v[160:161], off
	s_add_i32 s98, s72, 0x0
	s_waitcnt vmcnt(8)
	v_and_b32_e32 v148, 63, v228
	v_lshl_add_u32 v148, v148, 4, s98
	ds_read_b128 v[148:151], v148
	v_pk_mul_f32 v[154:155], v[144:145], v[144:145]
	v_pk_mul_f32 v[158:159], v[140:141], v[140:141]
	v_pk_mov_b32 v[156:157], v[154:155], v[152:153] op_sel:[1,0]
	v_mov_b32_e32 v155, v153
	v_pk_add_f32 v[172:173], v[156:157], v[154:155]
	v_cndmask_b32_e32 v33, v233, v33, vcc
	v_pk_add_f32 v[172:173], v[172:173], v[172:173] op_sel:[0,1] op_sel_hi:[1,0]
	v_lshlrev_b32_e32 v239, 2, v33
	v_and_b32_e32 v238, 63, v195
	s_lshl_b32 s4, s25, 4
	v_cmp_gt_u32_e32 vcc, 16, v238
	s_add_i32 s19, s4, 0
	s_waitcnt lgkmcnt(0)
	v_pk_mul_f32 v[170:171], v[144:145], v[116:117]
	v_pk_mul_f32 v[176:177], v[142:143], v[106:107]
	v_pk_mul_f32 v[178:179], v[140:141], v[104:105]
	v_pk_mul_f32 v[168:169], v[146:147], v[118:119]
	v_mul_f32_e32 v193, v178, v178
	v_pk_mul_f32 v[152:153], v[150:151], v[150:151]
	v_pk_mul_f32 v[154:155], v[148:149], v[148:149]
	v_mul_f32_e32 v33, v179, v179
	v_pk_mov_b32 v[156:157], v[154:155], v[152:153] op_sel:[1,0]
	v_mov_b32_e32 v155, v153
	v_pk_add_f32 v[152:153], v[156:157], v[154:155]
	v_pk_mul_f32 v[156:157], v[142:143], v[142:143]
	v_pk_add_f32 v[190:191], v[152:153], v[152:153] op_sel_hi:[0,1]
	v_and_b32_e32 v152, 63, v228
	v_lshl_add_u32 v152, v152, 4, s98
	ds_read_b128 v[152:155], v152 offset:1024
	v_pk_mov_b32 v[160:161], v[158:159], v[156:157] op_sel:[1,0]
	v_mov_b32_e32 v159, v157
	v_pk_add_f32 v[180:181], v[160:161], v[158:159]
	v_mul_f32_e32 v190, v132, v132
	v_pk_add_f32 v[180:181], v[180:181], v[180:181] op_sel:[0,1] op_sel_hi:[1,0]
	v_pk_mul_f32 v[184:185], v[136:137], v[100:101]
	v_pk_mul_f32 v[182:183], v[138:139], v[102:103]
	v_pk_mul_f32 v[188:189], v[132:133], v[92:93]
	v_pk_mul_f32 v[186:187], v[134:135], v[94:95]
	s_waitcnt lgkmcnt(0)
	v_pk_mul_f32 v[156:157], v[154:155], v[154:155]
	v_pk_mul_f32 v[158:159], v[152:153], v[152:153]
	s_nop 0
	v_pk_mov_b32 v[160:161], v[158:159], v[156:157] op_sel:[1,0]
	v_mov_b32_e32 v159, v157
	v_pk_add_f32 v[156:157], v[160:161], v[158:159]
	s_nop 0
	v_pk_add_f32 v[204:205], v[156:157], v[156:157] op_sel_hi:[0,1]
	v_mul_f32_e32 v156, v176, v176
	v_pk_fma_f32 v[174:175], v[176:177], v[176:177], v[156:157] op_sel_hi:[1,1,0]
	v_and_b32_e32 v156, 63, v228
	v_lshl_add_u32 v156, v156, 4, s98
	ds_read_b128 v[156:159], v156 offset:2048
	v_mul_f32_e32 v204, v133, v133
	v_pk_add_f32 v[190:191], v[190:191], v[204:205]
	v_mul_f32_e32 v174, v137, v137
	s_waitcnt lgkmcnt(0)
;     __device__ __forceinline__ void fused(f32x4 (&acc)[2][2][4][2], const Unit& u, int wr, int wc, int fr, int fq, PG8_LAS unsigned char* lds, int wid, int lane) const {
;     ...
;                     for (int n = 0; n < 2; ++n) { const f32x4 bs = *(const f32x4*)(base + off + bj * HALF + n * 16), a = acc[ai][bj][m][n], ag = a * gv[bj][n];
;                         s0 += (a[0] * a[0] + a[1] * a[1]) + (a[2] * a[2] + a[3] * a[3]); s1 += (bs[0] * bs[0] + bs[1] * bs[1]) + (bs[2] * bs[2] + bs[3] * bs[3]);
;                         s2 += (bs[0] * ag[0] + bs[1] * ag[1]) + (bs[2] * ag[2] + bs[3] * ag[3]); s3 += (ag[0] * ag[0] + ag[1] * ag[1]) + (ag[2] * ag[2] + ag[3] * ag[3]); }
;                 s0 += __shfl_xor(s0, 16); s0 += __shfl_xor(s0, 32); s1 += __shfl_xor(s1, 16); s1 += __shfl_xor(s1, 32);
;                 s2 += __shfl_xor(s2, 16); s2 += __shfl_xor(s2, 32); s3 += __shfl_xor(s3, 16); s3 += __shfl_xor(s3, 32);
;                 if (fq == 0) P[r * 4 + wc] = (f32x4){s0, s1, s2, s3};
	v_mul_f32_e32 v160, v156, v156
	v_pk_fma_f32 v[206:207], v[156:157], v[156:157], v[160:161] op_sel_hi:[1,1,0]
	v_mul_f32_e32 v160, v158, v158
	v_pk_fma_f32 v[208:209], v[158:159], v[158:159], v[160:161] op_sel_hi:[1,1,0]
	v_and_b32_e32 v160, 63, v228
	v_lshl_add_u32 v160, v160, 4, s98
	ds_read_b128 v[160:163], v160 offset:3072
	v_mul_f32_e32 v206, v134, v134
	v_mul_f32_e32 v208, v135, v135
	v_pk_add_f32 v[204:205], v[206:207], v[208:209]
	s_waitcnt lgkmcnt(0)
	v_mul_f32_e32 v210, v160, v160
	v_pk_add_f32 v[190:191], v[190:191], v[204:205]
	v_pk_fma_f32 v[204:205], v[136:137], v[136:137], v[174:175] op_sel_hi:[1,1,0]
	v_mul_f32_e32 v174, v139, v139
	v_mul_f32_e32 v211, v161, v161
	v_mul_f32_e32 v212, v162, v162
	v_mul_f32_e32 v213, v163, v163
	v_pk_fma_f32 v[206:207], v[138:139], v[138:139], v[174:175] op_sel_hi:[1,1,0]
	v_mov_b32_e32 v205, v210
	v_mov_b32_e32 v207, v211
	v_mov_b32_e32 v181, v212
	v_mov_b32_e32 v173, v213
	v_pk_add_f32 v[204:205], v[204:205], v[206:207]
	v_pk_add_f32 v[172:173], v[180:181], v[172:173]
	s_nop 0
	v_pk_add_f32 v[172:173], v[204:205], v[172:173]
	v_mov_b32_e32 v204, v152
	v_pk_add_f32 v[172:173], v[190:191], v[172:173]
	v_mov_b32_e32 v190, v178
	v_mov_b32_e32 v178, v179
	v_mov_b32_e32 v179, v171
	v_mov_b32_e32 v152, v153
	v_mov_b32_e32 v153, v171
	v_mov_b32_e32 v191, v170
	v_mov_b32_e32 v205, v170
	v_pk_mul_f32 v[152:153], v[178:179], v[152:153]
	v_mov_b32_e32 v178, v176
	v_pk_fma_f32 v[152:153], v[190:191], v[204:205], v[152:153]
	v_mov_b32_e32 v190, v154
	v_mov_b32_e32 v176, v177
	v_mov_b32_e32 v177, v169
	v_mov_b32_e32 v154, v155
	v_mov_b32_e32 v155, v169
	v_mov_b32_e32 v179, v168
	v_mov_b32_e32 v191, v168
	v_pk_mul_f32 v[154:155], v[176:177], v[154:155]
	ds_bpermute_b32 v180, v240, v172
	v_pk_fma_f32 v[154:155], v[178:179], v[190:191], v[154:155]
	ds_bpermute_b32 v181, v240, v173
	v_pk_add_f32 v[152:153], v[152:153], v[154:155]
	v_mul_f32_e32 v154, v171, v149
	v_pk_fma_f32 v[148:149], v[170:171], v[148:149], v[154:155] op_sel_hi:[1,1,0]
	v_mul_f32_e32 v154, v169, v151
	v_pk_fma_f32 v[150:151], v[168:169], v[150:151], v[154:155] op_sel_hi:[1,1,0]
	v_mov_b32_e32 v149, v193
	v_mov_b32_e32 v151, v33
	v_pk_add_f32 v[148:149], v[148:149], v[150:151]
	v_mov_b32_e32 v33, v175
	v_pk_add_f32 v[148:149], v[148:149], v[32:33]
	v_pk_mov_b32 v[150:151], v[156:157], v[184:185] op_sel:[1,0]
	v_mov_b32_e32 v157, v185
	v_pk_add_f32 v[148:149], v[152:153], v[148:149]
	v_pk_mul_f32 v[152:153], v[184:185], v[156:157]
	s_waitcnt lgkmcnt(0)
	v_pk_add_f32 v[172:173], v[172:173], v[180:181]
	v_pk_fma_f32 v[150:151], v[184:185], v[150:151], v[152:153] op_sel:[1,0,0] op_sel_hi:[0,1,1]
	v_pk_mov_b32 v[152:153], v[158:159], v[182:183] op_sel:[1,0]
	v_mov_b32_e32 v159, v183
	v_pk_mul_f32 v[154:155], v[182:183], v[158:159]
	ds_bpermute_b32 v180, v239, v172
	v_pk_fma_f32 v[152:153], v[182:183], v[152:153], v[154:155] op_sel:[1,0,0] op_sel_hi:[0,1,1]
	v_pk_add_f32 v[150:151], v[150:151], v[152:153]
	ds_bpermute_b32 v181, v239, v173
	v_pk_add_f32 v[148:149], v[148:149], v[150:151]
	v_pk_mov_b32 v[150:151], v[160:161], v[188:189] op_sel:[1,0]
	v_mov_b32_e32 v161, v189
	v_pk_mul_f32 v[152:153], v[188:189], v[160:161]
	s_nop 0
	v_pk_fma_f32 v[150:151], v[188:189], v[150:151], v[152:153] op_sel:[1,0,0] op_sel_hi:[0,1,1]
	v_pk_mov_b32 v[152:153], v[162:163], v[186:187] op_sel:[1,0]
	v_mov_b32_e32 v163, v187
	v_pk_mul_f32 v[154:155], v[186:187], v[162:163]
	s_nop 0
	v_pk_fma_f32 v[152:153], v[186:187], v[152:153], v[154:155] op_sel:[1,0,0] op_sel_hi:[0,1,1]
	v_pk_add_f32 v[150:151], v[150:151], v[152:153]
	s_nop 0
	v_pk_add_f32 v[148:149], v[148:149], v[150:151]
	ds_bpermute_b32 v150, v240, v148
	ds_bpermute_b32 v151, v240, v149
	s_waitcnt lgkmcnt(0)
	v_pk_add_f32 v[148:149], v[148:149], v[150:151]
	ds_bpermute_b32 v150, v239, v148
	ds_bpermute_b32 v151, v239, v149
	s_and_saveexec_b64 s[6:7], vcc
	v_readlane_b32 s56, v255, 4
	v_readlane_b32 s58, v255, 6
	v_readlane_b32 s52, v255, 8
	v_readlane_b32 s57, v255, 5
	v_readlane_b32 s59, v255, 7
	v_readlane_b32 s53, v255, 9
	v_readlane_b32 s55, v255, 10
	s_cbranch_execz .LBB0_833
	v_add_u32_e32 v33, s19, v192
	s_waitcnt lgkmcnt(0)
	v_pk_add_f32 v[150:151], v[148:149], v[150:151]
	v_pk_add_f32 v[148:149], v[172:173], v[180:181]
	ds_write_b128 v33, v[148:151]
;     __device__ __forceinline__ void fused(f32x4 (&acc)[2][2][4][2], const Unit& u, int wr, int wc, int fr, int fq, PG8_LAS unsigned char* lds, int wid, int lane) const {
;     ...
;             for (int m = 0; m < 4; ++m) { const int r = ai * HALF + wr * 64 + m * 16 + fr; const size_t off = (size_t)(u.pm * BM + r) * 1024 + col0;
;                 float s0 = 0.f, s1 = 0.f, s2 = 0.f, s3 = 0.f;
; #pragma unroll
;                 for (int bj = 0; bj < 2; ++bj)
; #pragma unroll
;                     for (int n = 0; n < 2; ++n) { const f32x4 bs = *(const f32x4*)(base + off + bj * HALF + n * 16), a = acc[ai][bj][m][n], ag = a * gv[bj][n];
;                         s0 += (a[0] * a[0] + a[1] * a[1]) + (a[2] * a[2] + a[3] * a[3]); s1 += (bs[0] * bs[0] + bs[1] * bs[1]) + (bs[2] * bs[2] + bs[3] * bs[3]);
;                         s2 += (bs[0] * ag[0] + bs[1] * ag[1]) + (bs[2] * ag[2] + bs[3] * ag[3]); s3 += (ag[0] * ag[0] + ag[1] * ag[1]) + (ag[2] * ag[2] + ag[3] * ag[3]); }
;                 s0 += __shfl_xor(s0, 16); s0 += __shfl_xor(s0, 32); s1 += __shfl_xor(s1, 16); s1 += __shfl_xor(s1, 32);
;                 s2 += __shfl_xor(s2, 16); s2 += __shfl_xor(s2, 32); s3 += __shfl_xor(s3, 16); s3 += __shfl_xor(s3, 32);
;                 if (fq == 0) P[r * 4 + wc] = (f32x4){s0, s1, s2, s3};
.LBB0_833:
	s_or_b64 exec, exec, s[6:7]
	s_mov_b64 s[98:99], 0x30000
	v_lshl_add_u64 v[160:161], v[164:165], 0, s[98:99]
	s_add_i32 m0, s72, 0x0
	s_nop 0
	global_load_lds_dwordx4 v[160:161], off
	s_mov_b64 s[98:99], 0x30040
	v_lshl_add_u64 v[160:161], v[164:165], 0, s[98:99]
	s_add_i32 m0, s72, 0x400
	s_nop 0
	global_load_lds_dwordx4 v[160:161], off
	s_mov_b64 s[98:99], 0x30200
	v_lshl_add_u64 v[160:161], v[164:165], 0, s[98:99]
	s_add_i32 m0, s72, 0x800
	s_nop 0
	global_load_lds_dwordx4 v[160:161], off
	s_mov_b64 s[98:99], 0x30240
	v_lshl_add_u64 v[160:161], v[164:165], 0, s[98:99]
	s_add_i32 m0, s72, 0xc00
	s_nop 0
	global_load_lds_dwordx4 v[160:161], off
	v_or_b32_e32 v204, 16, v237
	v_add_u32_e32 v170, s17, v204
	v_ashrrev_i32_e32 v171, 31, v170
	v_lshlrev_b64 v[148:149], 12, v[170:171]
	v_lshl_add_u64 v[148:149], s[26:27], 0, v[148:149]
	v_lshl_add_u64 v[168:169], v[34:35], 2, v[148:149]
	s_waitcnt lgkmcnt(0)
	s_add_i32 s98, s72, 0x1000
	s_waitcnt vmcnt(8)
	v_and_b32_e32 v148, 63, v228
	v_lshl_add_u32 v148, v148, 4, s98
	ds_read_b128 v[148:151], v148
	v_and_b32_e32 v160, 63, v228
	v_lshl_add_u32 v160, v160, 4, s98
	ds_read_b128 v[160:163], v160 offset:1024
	v_pk_mul_f32 v[152:153], v[130:131], v[130:131]
	v_pk_mul_f32 v[154:155], v[128:129], v[128:129]
	v_pk_mul_f32 v[186:187], v[126:127], v[106:107]
	v_pk_mov_b32 v[156:157], v[154:155], v[152:153] op_sel:[1,0]
	v_mov_b32_e32 v155, v153
	v_pk_add_f32 v[188:189], v[156:157], v[154:155]
	v_pk_mul_f32 v[174:175], v[128:129], v[116:117]
	v_pk_add_f32 v[188:189], v[188:189], v[188:189] op_sel:[0,1] op_sel_hi:[1,0]
	v_pk_mul_f32 v[192:193], v[124:125], v[104:105]
	v_pk_mul_f32 v[172:173], v[130:131], v[118:119]
	v_mul_f32_e32 v205, v192, v192
	v_mul_f32_e32 v33, v193, v193
	v_pk_mul_f32 v[180:181], v[120:121], v[100:101]
	v_pk_mul_f32 v[178:179], v[122:123], v[102:103]
	v_pk_mul_f32 v[184:185], v[112:113], v[92:93]
	v_pk_mul_f32 v[182:183], v[114:115], v[94:95]
	s_waitcnt lgkmcnt(1)
	v_pk_mul_f32 v[152:153], v[150:151], v[150:151]
	v_pk_mul_f32 v[154:155], v[148:149], v[148:149]
	s_nop 0
	v_pk_mov_b32 v[156:157], v[154:155], v[152:153] op_sel:[1,0]
	v_mov_b32_e32 v155, v153
	v_pk_add_f32 v[152:153], v[156:157], v[154:155]
	v_pk_mul_f32 v[154:155], v[124:125], v[124:125]
	v_pk_add_f32 v[206:207], v[152:153], v[152:153] op_sel_hi:[0,1]
	v_pk_mul_f32 v[152:153], v[126:127], v[126:127]
	v_mul_f32_e32 v206, v112, v112
	v_pk_mov_b32 v[156:157], v[154:155], v[152:153] op_sel:[1,0]
	v_mov_b32_e32 v155, v153
	v_pk_add_f32 v[190:191], v[156:157], v[154:155]
	s_waitcnt lgkmcnt(0)
	v_pk_mul_f32 v[152:153], v[162:163], v[162:163]
	v_pk_mul_f32 v[154:155], v[160:161], v[160:161]
	v_pk_add_f32 v[190:191], v[190:191], v[190:191] op_sel:[0,1] op_sel_hi:[1,0]
	v_pk_mov_b32 v[156:157], v[154:155], v[152:153] op_sel:[1,0]
	v_mov_b32_e32 v155, v153
	v_pk_add_f32 v[152:153], v[156:157], v[154:155]
	s_nop 0
	v_pk_add_f32 v[208:209], v[152:153], v[152:153] op_sel_hi:[0,1]
	v_mul_f32_e32 v152, v186, v186
	v_pk_fma_f32 v[176:177], v[186:187], v[186:187], v[152:153] op_sel_hi:[1,1,0]
	v_and_b32_e32 v152, 63, v228
	v_lshl_add_u32 v152, v152, 4, s98
	ds_read_b128 v[152:155], v152 offset:2048
	v_mul_f32_e32 v208, v113, v113
	v_pk_add_f32 v[206:207], v[206:207], v[208:209]
	v_mul_f32_e32 v176, v121, v121
	s_waitcnt lgkmcnt(0)
	v_mul_f32_e32 v156, v152, v152
	v_pk_fma_f32 v[210:211], v[152:153], v[152:153], v[156:157] op_sel_hi:[1,1,0]
	v_mul_f32_e32 v156, v154, v154
	v_pk_fma_f32 v[212:213], v[154:155], v[154:155], v[156:157] op_sel_hi:[1,1,0]
	v_and_b32_e32 v156, 63, v228
	v_lshl_add_u32 v156, v156, 4, s98
	ds_read_b128 v[156:159], v156 offset:3072
	v_mul_f32_e32 v210, v114, v114
	v_mul_f32_e32 v212, v115, v115
	v_pk_add_f32 v[208:209], v[210:211], v[212:213]
	s_waitcnt lgkmcnt(0)
	v_mul_f32_e32 v214, v156, v156
	v_pk_add_f32 v[206:207], v[206:207], v[208:209]
	v_pk_fma_f32 v[208:209], v[120:121], v[120:121], v[176:177] op_sel_hi:[1,1,0]
	v_mul_f32_e32 v176, v123, v123
	v_mul_f32_e32 v215, v157, v157
	v_mul_f32_e32 v216, v158, v158
	v_mul_f32_e32 v217, v159, v159
	v_pk_fma_f32 v[210:211], v[122:123], v[122:123], v[176:177] op_sel_hi:[1,1,0]
	v_mov_b32_e32 v209, v214
	v_mov_b32_e32 v211, v215
	v_mov_b32_e32 v191, v216
	v_mov_b32_e32 v189, v217
	v_pk_add_f32 v[208:209], v[208:209], v[210:211]
	v_pk_add_f32 v[188:189], v[190:191], v[188:189]
	s_nop 0
	v_pk_add_f32 v[188:189], v[208:209], v[188:189]
	v_mov_b32_e32 v208, v160
	v_pk_add_f32 v[188:189], v[206:207], v[188:189]
	v_mov_b32_e32 v206, v192
	v_mov_b32_e32 v192, v193
	v_mov_b32_e32 v193, v175
	v_mov_b32_e32 v160, v161
	v_mov_b32_e32 v161, v175
	v_mov_b32_e32 v207, v174
	v_mov_b32_e32 v209, v174
	v_pk_mul_f32 v[160:161], v[192:193], v[160:161]
	v_mov_b32_e32 v192, v186
	v_pk_fma_f32 v[160:161], v[206:207], v[208:209], v[160:161]
	v_mov_b32_e32 v206, v162
	v_mov_b32_e32 v186, v187
	v_mov_b32_e32 v187, v173
	v_mov_b32_e32 v162, v163
	v_mov_b32_e32 v163, v173
	v_mov_b32_e32 v193, v172
	v_mov_b32_e32 v207, v172
	v_pk_mul_f32 v[162:163], v[186:187], v[162:163]
	ds_bpermute_b32 v190, v240, v188
	v_pk_fma_f32 v[162:163], v[192:193], v[206:207], v[162:163]
	ds_bpermute_b32 v191, v240, v189
	v_pk_add_f32 v[160:161], v[160:161], v[162:163]
	v_mul_f32_e32 v162, v175, v149
	v_pk_fma_f32 v[148:149], v[174:175], v[148:149], v[162:163] op_sel_hi:[1,1,0]
	v_mul_f32_e32 v162, v173, v151
	v_pk_fma_f32 v[150:151], v[172:173], v[150:151], v[162:163] op_sel_hi:[1,1,0]
	v_mov_b32_e32 v149, v205
	v_mov_b32_e32 v151, v33
	v_pk_add_f32 v[148:149], v[148:149], v[150:151]
	v_pk_mov_b32 v[150:151], v[152:153], v[180:181] op_sel:[1,0]
	v_mov_b32_e32 v153, v181
	v_pk_mul_f32 v[152:153], v[180:181], v[152:153]
	v_mov_b32_e32 v33, v177
	v_pk_fma_f32 v[150:151], v[180:181], v[150:151], v[152:153] op_sel:[1,0,0] op_sel_hi:[0,1,1]
	v_pk_mov_b32 v[152:153], v[154:155], v[178:179] op_sel:[1,0]
	v_mov_b32_e32 v155, v179
	v_pk_mul_f32 v[154:155], v[178:179], v[154:155]
	v_pk_add_f32 v[148:149], v[148:149], v[32:33]
	v_pk_fma_f32 v[152:153], v[178:179], v[152:153], v[154:155] op_sel:[1,0,0] op_sel_hi:[0,1,1]
	v_pk_add_f32 v[148:149], v[160:161], v[148:149]
	v_pk_add_f32 v[150:151], v[150:151], v[152:153]
	s_waitcnt lgkmcnt(0)
;     __device__ __forceinline__ void fused(f32x4 (&acc)[2][2][4][2], const Unit& u, int wr, int wc, int fr, int fq, PG8_LAS unsigned char* lds, int wid, int lane) const {
;     ...
;                     for (int n = 0; n < 2; ++n) { const f32x4 bs = *(const f32x4*)(base + off + bj * HALF + n * 16), a = acc[ai][bj][m][n], ag = a * gv[bj][n];
;                         s0 += (a[0] * a[0] + a[1] * a[1]) + (a[2] * a[2] + a[3] * a[3]); s1 += (bs[0] * bs[0] + bs[1] * bs[1]) + (bs[2] * bs[2] + bs[3] * bs[3]);
;                         s2 += (bs[0] * ag[0] + bs[1] * ag[1]) + (bs[2] * ag[2] + bs[3] * ag[3]); s3 += (ag[0] * ag[0] + ag[1] * ag[1]) + (ag[2] * ag[2] + ag[3] * ag[3]); }
;                 s0 += __shfl_xor(s0, 16); s0 += __shfl_xor(s0, 32); s1 += __shfl_xor(s1, 16); s1 += __shfl_xor(s1, 32);
;                 s2 += __shfl_xor(s2, 16); s2 += __shfl_xor(s2, 32); s3 += __shfl_xor(s3, 16); s3 += __shfl_xor(s3, 32);
;                 if (fq == 0) P[r * 4 + wc] = (f32x4){s0, s1, s2, s3};
	v_pk_add_f32 v[188:189], v[188:189], v[190:191]
	v_pk_add_f32 v[148:149], v[148:149], v[150:151]
	v_pk_mov_b32 v[150:151], v[156:157], v[184:185] op_sel:[1,0]
	v_mov_b32_e32 v157, v185
	v_pk_mul_f32 v[152:153], v[184:185], v[156:157]
	ds_bpermute_b32 v190, v239, v188
	v_pk_fma_f32 v[150:151], v[184:185], v[150:151], v[152:153] op_sel:[1,0,0] op_sel_hi:[0,1,1]
	v_pk_mov_b32 v[152:153], v[158:159], v[182:183] op_sel:[1,0]
	v_mov_b32_e32 v159, v183
	v_pk_mul_f32 v[154:155], v[182:183], v[158:159]
	ds_bpermute_b32 v191, v239, v189
	v_pk_fma_f32 v[152:153], v[182:183], v[152:153], v[154:155] op_sel:[1,0,0] op_sel_hi:[0,1,1]
	v_pk_add_f32 v[150:151], v[150:151], v[152:153]
	s_nop 0
	v_pk_add_f32 v[148:149], v[148:149], v[150:151]
	ds_bpermute_b32 v150, v240, v148
	ds_bpermute_b32 v151, v240, v149
	s_waitcnt lgkmcnt(0)
	v_pk_add_f32 v[148:149], v[148:149], v[150:151]
	ds_bpermute_b32 v150, v239, v148
	ds_bpermute_b32 v151, v239, v149
	s_and_saveexec_b64 s[6:7], vcc
	s_cbranch_execz .LBB0_835
	v_lshl_add_u32 v33, v204, 6, s19
	s_waitcnt lgkmcnt(0)
	v_pk_add_f32 v[150:151], v[148:149], v[150:151]
	v_pk_add_f32 v[148:149], v[188:189], v[190:191]
	ds_write_b128 v33, v[148:151]
.LBB0_835:
	s_or_b64 exec, exec, s[6:7]
	s_mov_b64 s[98:99], 0x80000
	v_lshl_add_u64 v[160:161], v[164:165], 0, s[98:99]
	s_add_i32 m0, s72, 0x1000
	s_nop 0
	global_load_lds_dwordx4 v[160:161], off
	s_mov_b64 s[98:99], 0x80040
	v_lshl_add_u64 v[160:161], v[164:165], 0, s[98:99]
	s_add_i32 m0, s72, 0x1400
	s_nop 0
	global_load_lds_dwordx4 v[160:161], off
	s_mov_b64 s[98:99], 0x80200
	v_lshl_add_u64 v[160:161], v[164:165], 0, s[98:99]
	s_add_i32 m0, s72, 0x1800
	s_nop 0
	global_load_lds_dwordx4 v[160:161], off
	s_mov_b64 s[98:99], 0x80240
	v_lshl_add_u64 v[160:161], v[164:165], 0, s[98:99]
	s_add_i32 m0, s72, 0x1c00
	s_nop 0
	global_load_lds_dwordx4 v[160:161], off
	v_or_b32_e32 v208, 32, v237
	v_add_u32_e32 v174, s17, v208
	v_ashrrev_i32_e32 v175, 31, v174
	v_lshlrev_b64 v[148:149], 12, v[174:175]
	v_lshl_add_u64 v[148:149], s[26:27], 0, v[148:149]
	v_lshl_add_u64 v[172:173], v[34:35], 2, v[148:149]
	s_waitcnt lgkmcnt(0)
	s_add_i32 s98, s72, 0x2000
	s_waitcnt vmcnt(8)
	v_and_b32_e32 v148, 63, v228
	v_lshl_add_u32 v148, v148, 4, s98
	ds_read_b128 v[148:151], v148
	v_and_b32_e32 v160, 63, v228
	v_lshl_add_u32 v160, v160, 4, s98
	ds_read_b128 v[160:163], v160 offset:1024
	v_pk_mul_f32 v[152:153], v[110:111], v[110:111]
	v_pk_mul_f32 v[154:155], v[108:109], v[108:109]
	v_pk_mul_f32 v[190:191], v[98:99], v[106:107]
	v_pk_mov_b32 v[156:157], v[154:155], v[152:153] op_sel:[1,0]
	v_mov_b32_e32 v155, v153
	v_pk_add_f32 v[192:193], v[156:157], v[154:155]
	v_pk_mul_f32 v[178:179], v[108:109], v[116:117]
	v_pk_add_f32 v[192:193], v[192:193], v[192:193] op_sel:[0,1] op_sel_hi:[1,0]
	v_pk_mul_f32 v[206:207], v[96:97], v[104:105]
	v_pk_mul_f32 v[176:177], v[110:111], v[118:119]
	v_mul_f32_e32 v209, v206, v206
	v_mul_f32_e32 v33, v207, v207
	v_pk_mul_f32 v[184:185], v[88:89], v[100:101]
	v_pk_mul_f32 v[182:183], v[90:91], v[102:103]
	v_pk_mul_f32 v[188:189], v[84:85], v[92:93]
	v_pk_mul_f32 v[186:187], v[86:87], v[94:95]
	s_waitcnt lgkmcnt(1)
	v_pk_mul_f32 v[152:153], v[150:151], v[150:151]
	v_pk_mul_f32 v[154:155], v[148:149], v[148:149]
	s_nop 0
	v_pk_mov_b32 v[156:157], v[154:155], v[152:153] op_sel:[1,0]
	v_mov_b32_e32 v155, v153
	v_pk_add_f32 v[152:153], v[156:157], v[154:155]
	v_pk_mul_f32 v[154:155], v[96:97], v[96:97]
	v_pk_add_f32 v[210:211], v[152:153], v[152:153] op_sel_hi:[0,1]
	v_pk_mul_f32 v[152:153], v[98:99], v[98:99]
	v_mul_f32_e32 v210, v84, v84
	v_pk_mov_b32 v[156:157], v[154:155], v[152:153] op_sel:[1,0]
	v_mov_b32_e32 v155, v153
	v_pk_add_f32 v[204:205], v[156:157], v[154:155]
	s_waitcnt lgkmcnt(0)
	v_pk_mul_f32 v[152:153], v[162:163], v[162:163]
	v_pk_mul_f32 v[154:155], v[160:161], v[160:161]
	v_pk_add_f32 v[204:205], v[204:205], v[204:205] op_sel:[0,1] op_sel_hi:[1,0]
	v_pk_mov_b32 v[156:157], v[154:155], v[152:153] op_sel:[1,0]
	v_mov_b32_e32 v155, v153
	v_pk_add_f32 v[152:153], v[156:157], v[154:155]
	s_nop 0
	v_pk_add_f32 v[212:213], v[152:153], v[152:153] op_sel_hi:[0,1]
	v_mul_f32_e32 v152, v190, v190
	v_pk_fma_f32 v[180:181], v[190:191], v[190:191], v[152:153] op_sel_hi:[1,1,0]
	v_and_b32_e32 v152, 63, v228
	v_lshl_add_u32 v152, v152, 4, s98
	ds_read_b128 v[152:155], v152 offset:2048
	v_mul_f32_e32 v212, v85, v85
	v_pk_add_f32 v[210:211], v[210:211], v[212:213]
	v_mul_f32_e32 v180, v89, v89
	s_waitcnt lgkmcnt(0)
	v_mul_f32_e32 v156, v152, v152
	v_pk_fma_f32 v[214:215], v[152:153], v[152:153], v[156:157] op_sel_hi:[1,1,0]
	v_mul_f32_e32 v156, v154, v154
	v_pk_fma_f32 v[216:217], v[154:155], v[154:155], v[156:157] op_sel_hi:[1,1,0]
	v_and_b32_e32 v156, 63, v228
	v_lshl_add_u32 v156, v156, 4, s98
	ds_read_b128 v[156:159], v156 offset:3072
	v_mul_f32_e32 v214, v86, v86
	v_mul_f32_e32 v216, v87, v87
	v_pk_add_f32 v[212:213], v[214:215], v[216:217]
	s_waitcnt lgkmcnt(0)
;     __device__ __forceinline__ void fused(f32x4 (&acc)[2][2][4][2], const Unit& u, int wr, int wc, int fr, int fq, PG8_LAS unsigned char* lds, int wid, int lane) const {
;     ...
;                     for (int n = 0; n < 2; ++n) { const f32x4 bs = *(const f32x4*)(base + off + bj * HALF + n * 16), a = acc[ai][bj][m][n], ag = a * gv[bj][n];
;                         s0 += (a[0] * a[0] + a[1] * a[1]) + (a[2] * a[2] + a[3] * a[3]); s1 += (bs[0] * bs[0] + bs[1] * bs[1]) + (bs[2] * bs[2] + bs[3] * bs[3]);
;                         s2 += (bs[0] * ag[0] + bs[1] * ag[1]) + (bs[2] * ag[2] + bs[3] * ag[3]); s3 += (ag[0] * ag[0] + ag[1] * ag[1]) + (ag[2] * ag[2] + ag[3] * ag[3]); }
;                 s0 += __shfl_xor(s0, 16); s0 += __shfl_xor(s0, 32); s1 += __shfl_xor(s1, 16); s1 += __shfl_xor(s1, 32);
;                 s2 += __shfl_xor(s2, 16); s2 += __shfl_xor(s2, 32); s3 += __shfl_xor(s3, 16); s3 += __shfl_xor(s3, 32);
;                 if (fq == 0) P[r * 4 + wc] = (f32x4){s0, s1, s2, s3};
	v_mul_f32_e32 v218, v156, v156
	v_pk_add_f32 v[210:211], v[210:211], v[212:213]
	v_pk_fma_f32 v[212:213], v[88:89], v[88:89], v[180:181] op_sel_hi:[1,1,0]
	v_mul_f32_e32 v180, v91, v91
	v_mul_f32_e32 v219, v157, v157
	v_mul_f32_e32 v220, v158, v158
	v_mul_f32_e32 v221, v159, v159
	v_pk_fma_f32 v[214:215], v[90:91], v[90:91], v[180:181] op_sel_hi:[1,1,0]
	v_mov_b32_e32 v213, v218
	v_mov_b32_e32 v215, v219
	v_mov_b32_e32 v205, v220
	v_mov_b32_e32 v193, v221
	v_pk_add_f32 v[212:213], v[212:213], v[214:215]
	v_pk_add_f32 v[192:193], v[204:205], v[192:193]
	s_nop 0
	v_pk_add_f32 v[192:193], v[212:213], v[192:193]
	v_mov_b32_e32 v212, v160
	v_pk_add_f32 v[192:193], v[210:211], v[192:193]
	v_mov_b32_e32 v210, v206
	v_mov_b32_e32 v206, v207
	v_mov_b32_e32 v207, v179
	v_mov_b32_e32 v160, v161
	v_mov_b32_e32 v161, v179
	v_mov_b32_e32 v211, v178
	v_mov_b32_e32 v213, v178
	v_pk_mul_f32 v[160:161], v[206:207], v[160:161]
	v_mov_b32_e32 v206, v190
	v_pk_fma_f32 v[160:161], v[210:211], v[212:213], v[160:161]
	v_mov_b32_e32 v210, v162
	v_mov_b32_e32 v190, v191
	v_mov_b32_e32 v191, v177
	v_mov_b32_e32 v162, v163
	v_mov_b32_e32 v163, v177
	v_mov_b32_e32 v207, v176
	v_mov_b32_e32 v211, v176
	v_pk_mul_f32 v[162:163], v[190:191], v[162:163]
	ds_bpermute_b32 v204, v240, v192
	v_pk_fma_f32 v[162:163], v[206:207], v[210:211], v[162:163]
	ds_bpermute_b32 v205, v240, v193
	v_pk_add_f32 v[160:161], v[160:161], v[162:163]
	v_mul_f32_e32 v162, v179, v149
	v_pk_fma_f32 v[148:149], v[178:179], v[148:149], v[162:163] op_sel_hi:[1,1,0]
	v_mul_f32_e32 v162, v177, v151
	v_pk_fma_f32 v[150:151], v[176:177], v[150:151], v[162:163] op_sel_hi:[1,1,0]
	v_mov_b32_e32 v149, v209
	v_mov_b32_e32 v151, v33
	v_pk_add_f32 v[148:149], v[148:149], v[150:151]
	v_pk_mov_b32 v[150:151], v[152:153], v[184:185] op_sel:[1,0]
	v_mov_b32_e32 v153, v185
	v_pk_mul_f32 v[152:153], v[184:185], v[152:153]
	v_mov_b32_e32 v33, v181
	v_pk_fma_f32 v[150:151], v[184:185], v[150:151], v[152:153] op_sel:[1,0,0] op_sel_hi:[0,1,1]
	v_pk_mov_b32 v[152:153], v[154:155], v[182:183] op_sel:[1,0]
	v_mov_b32_e32 v155, v183
	v_pk_mul_f32 v[154:155], v[182:183], v[154:155]
	v_pk_add_f32 v[148:149], v[148:149], v[32:33]
	v_pk_fma_f32 v[152:153], v[182:183], v[152:153], v[154:155] op_sel:[1,0,0] op_sel_hi:[0,1,1]
	v_pk_add_f32 v[148:149], v[160:161], v[148:149]
	v_pk_add_f32 v[150:151], v[150:151], v[152:153]
	s_waitcnt lgkmcnt(0)
	v_pk_add_f32 v[192:193], v[192:193], v[204:205]
	v_pk_add_f32 v[148:149], v[148:149], v[150:151]
	v_pk_mov_b32 v[150:151], v[156:157], v[188:189] op_sel:[1,0]
	v_mov_b32_e32 v157, v189
	v_pk_mul_f32 v[152:153], v[188:189], v[156:157]
	ds_bpermute_b32 v204, v239, v192
	v_pk_fma_f32 v[150:151], v[188:189], v[150:151], v[152:153] op_sel:[1,0,0] op_sel_hi:[0,1,1]
	v_pk_mov_b32 v[152:153], v[158:159], v[186:187] op_sel:[1,0]
	v_mov_b32_e32 v159, v187
	v_pk_mul_f32 v[154:155], v[186:187], v[158:159]
	ds_bpermute_b32 v205, v239, v193
	v_pk_fma_f32 v[152:153], v[186:187], v[152:153], v[154:155] op_sel:[1,0,0] op_sel_hi:[0,1,1]
	v_pk_add_f32 v[150:151], v[150:151], v[152:153]
	s_nop 0
	v_pk_add_f32 v[148:149], v[148:149], v[150:151]
	ds_bpermute_b32 v150, v240, v148
	ds_bpermute_b32 v151, v240, v149
	s_waitcnt lgkmcnt(0)
	v_pk_add_f32 v[148:149], v[148:149], v[150:151]
	ds_bpermute_b32 v150, v239, v148
	ds_bpermute_b32 v151, v239, v149
	s_and_saveexec_b64 s[6:7], vcc
	s_cbranch_execz .LBB0_837
	v_lshl_add_u32 v33, v208, 6, s19
	s_waitcnt lgkmcnt(0)
	v_pk_add_f32 v[150:151], v[148:149], v[150:151]
	v_pk_add_f32 v[148:149], v[192:193], v[204:205]
	ds_write_b128 v33, v[148:151]
.LBB0_837:
	s_or_b64 exec, exec, s[6:7]
	s_mov_b64 s[98:99], 0x90000
	v_lshl_add_u64 v[160:161], v[164:165], 0, s[98:99]
	s_add_i32 m0, s72, 0x2000
	s_nop 0
	global_load_lds_dwordx4 v[160:161], off
	s_mov_b64 s[98:99], 0x90040
	v_lshl_add_u64 v[160:161], v[164:165], 0, s[98:99]
	s_add_i32 m0, s72, 0x2400
	s_nop 0
	global_load_lds_dwordx4 v[160:161], off
	s_mov_b64 s[98:99], 0x90200
	v_lshl_add_u64 v[160:161], v[164:165], 0, s[98:99]
	s_add_i32 m0, s72, 0x2800
	s_nop 0
	global_load_lds_dwordx4 v[160:161], off
	s_mov_b64 s[98:99], 0x90240
	v_lshl_add_u64 v[160:161], v[164:165], 0, s[98:99]
	s_add_i32 m0, s72, 0x2c00
	s_nop 0
	global_load_lds_dwordx4 v[160:161], off
	v_or_b32_e32 v212, 48, v237
	v_add_u32_e32 v178, s17, v212
	v_ashrrev_i32_e32 v179, 31, v178
	v_lshlrev_b64 v[148:149], 12, v[178:179]
	v_lshl_add_u64 v[148:149], s[26:27], 0, v[148:149]
	v_lshl_add_u64 v[176:177], v[34:35], 2, v[148:149]
	s_waitcnt lgkmcnt(0)
	s_add_i32 s98, s72, 0x0
	s_waitcnt vmcnt(8)
	v_and_b32_e32 v148, 63, v228
	v_lshl_add_u32 v148, v148, 4, s98
	ds_read_b128 v[148:151], v148
	v_and_b32_e32 v160, 63, v228
	v_lshl_add_u32 v160, v160, 4, s98
	ds_read_b128 v[160:163], v160 offset:1024
	v_pk_mul_f32 v[152:153], v[82:83], v[82:83]
	v_pk_mul_f32 v[154:155], v[80:81], v[80:81]
	v_pk_mul_f32 v[204:205], v[78:79], v[106:107]
	v_pk_mov_b32 v[156:157], v[154:155], v[152:153] op_sel:[1,0]
	v_mov_b32_e32 v155, v153
	v_pk_add_f32 v[206:207], v[156:157], v[154:155]
	v_pk_mul_f32 v[182:183], v[80:81], v[116:117]
	v_pk_add_f32 v[206:207], v[206:207], v[206:207] op_sel:[0,1] op_sel_hi:[1,0]
	v_pk_mul_f32 v[210:211], v[76:77], v[104:105]
	v_pk_mul_f32 v[180:181], v[82:83], v[118:119]
	v_mul_f32_e32 v213, v210, v210
	v_mul_f32_e32 v33, v211, v211
	v_pk_mul_f32 v[188:189], v[72:73], v[100:101]
	v_pk_mul_f32 v[186:187], v[74:75], v[102:103]
	v_pk_mul_f32 v[192:193], v[68:69], v[92:93]
	v_pk_mul_f32 v[190:191], v[70:71], v[94:95]
	s_waitcnt lgkmcnt(1)
;     __device__ __forceinline__ void fused(f32x4 (&acc)[2][2][4][2], const Unit& u, int wr, int wc, int fr, int fq, PG8_LAS unsigned char* lds, int wid, int lane) const {
;     ...
;                     for (int n = 0; n < 2; ++n) { const f32x4 bs = *(const f32x4*)(base + off + bj * HALF + n * 16), a = acc[ai][bj][m][n], ag = a * gv[bj][n];
;                         s0 += (a[0] * a[0] + a[1] * a[1]) + (a[2] * a[2] + a[3] * a[3]); s1 += (bs[0] * bs[0] + bs[1] * bs[1]) + (bs[2] * bs[2] + bs[3] * bs[3]);
;                         s2 += (bs[0] * ag[0] + bs[1] * ag[1]) + (bs[2] * ag[2] + bs[3] * ag[3]); s3 += (ag[0] * ag[0] + ag[1] * ag[1]) + (ag[2] * ag[2] + ag[3] * ag[3]); }
;                 s0 += __shfl_xor(s0, 16); s0 += __shfl_xor(s0, 32); s1 += __shfl_xor(s1, 16); s1 += __shfl_xor(s1, 32);
;                 s2 += __shfl_xor(s2, 16); s2 += __shfl_xor(s2, 32); s3 += __shfl_xor(s3, 16); s3 += __shfl_xor(s3, 32);
;                 if (fq == 0) P[r * 4 + wc] = (f32x4){s0, s1, s2, s3};
	v_pk_mul_f32 v[152:153], v[150:151], v[150:151]
	v_pk_mul_f32 v[154:155], v[148:149], v[148:149]
	s_nop 0
	v_pk_mov_b32 v[156:157], v[154:155], v[152:153] op_sel:[1,0]
	v_mov_b32_e32 v155, v153
	v_pk_add_f32 v[152:153], v[156:157], v[154:155]
	v_pk_mul_f32 v[154:155], v[76:77], v[76:77]
	v_pk_add_f32 v[214:215], v[152:153], v[152:153] op_sel_hi:[0,1]
	v_pk_mul_f32 v[152:153], v[78:79], v[78:79]
	v_mul_f32_e32 v214, v68, v68
	v_pk_mov_b32 v[156:157], v[154:155], v[152:153] op_sel:[1,0]
	v_mov_b32_e32 v155, v153
	v_pk_add_f32 v[208:209], v[156:157], v[154:155]
	s_waitcnt lgkmcnt(0)
	v_pk_mul_f32 v[152:153], v[162:163], v[162:163]
	v_pk_mul_f32 v[154:155], v[160:161], v[160:161]
	v_pk_add_f32 v[208:209], v[208:209], v[208:209] op_sel:[0,1] op_sel_hi:[1,0]
	v_pk_mov_b32 v[156:157], v[154:155], v[152:153] op_sel:[1,0]
	v_mov_b32_e32 v155, v153
	v_pk_add_f32 v[152:153], v[156:157], v[154:155]
	s_nop 0
	v_pk_add_f32 v[216:217], v[152:153], v[152:153] op_sel_hi:[0,1]
	v_mul_f32_e32 v152, v204, v204
	v_pk_fma_f32 v[184:185], v[204:205], v[204:205], v[152:153] op_sel_hi:[1,1,0]
	v_and_b32_e32 v152, 63, v228
	v_lshl_add_u32 v152, v152, 4, s98
	ds_read_b128 v[152:155], v152 offset:2048
	v_mul_f32_e32 v216, v69, v69
	v_pk_add_f32 v[214:215], v[214:215], v[216:217]
	v_mul_f32_e32 v184, v73, v73
	s_waitcnt lgkmcnt(0)
	v_mul_f32_e32 v156, v152, v152
	v_pk_fma_f32 v[218:219], v[152:153], v[152:153], v[156:157] op_sel_hi:[1,1,0]
	v_mul_f32_e32 v156, v154, v154
	v_pk_fma_f32 v[220:221], v[154:155], v[154:155], v[156:157] op_sel_hi:[1,1,0]
	v_and_b32_e32 v156, 63, v228
	v_lshl_add_u32 v156, v156, 4, s98
	ds_read_b128 v[156:159], v156 offset:3072
	v_mul_f32_e32 v218, v70, v70
	v_mul_f32_e32 v220, v71, v71
	v_pk_add_f32 v[216:217], v[218:219], v[220:221]
	s_waitcnt lgkmcnt(0)
	v_mul_f32_e32 v222, v156, v156
	v_pk_add_f32 v[214:215], v[214:215], v[216:217]
	v_pk_fma_f32 v[216:217], v[72:73], v[72:73], v[184:185] op_sel_hi:[1,1,0]
	v_mul_f32_e32 v184, v75, v75
	v_mul_f32_e32 v223, v157, v157
	v_mul_f32_e32 v224, v158, v158
	v_mul_f32_e32 v225, v159, v159
	v_pk_fma_f32 v[218:219], v[74:75], v[74:75], v[184:185] op_sel_hi:[1,1,0]
	v_mov_b32_e32 v217, v222
	v_mov_b32_e32 v219, v223
	v_mov_b32_e32 v209, v224
	v_mov_b32_e32 v207, v225
	v_pk_add_f32 v[216:217], v[216:217], v[218:219]
	v_pk_add_f32 v[206:207], v[208:209], v[206:207]
	s_nop 0
	v_pk_add_f32 v[206:207], v[216:217], v[206:207]
	v_mov_b32_e32 v216, v160
	v_pk_add_f32 v[206:207], v[214:215], v[206:207]
	v_mov_b32_e32 v214, v210
	v_mov_b32_e32 v210, v211
	v_mov_b32_e32 v211, v183
	v_mov_b32_e32 v160, v161
	v_mov_b32_e32 v161, v183
	v_mov_b32_e32 v215, v182
	v_mov_b32_e32 v217, v182
	v_pk_mul_f32 v[160:161], v[210:211], v[160:161]
	v_mov_b32_e32 v210, v204
	v_pk_fma_f32 v[160:161], v[214:215], v[216:217], v[160:161]
	v_mov_b32_e32 v214, v162
	v_mov_b32_e32 v204, v205
	v_mov_b32_e32 v205, v181
	v_mov_b32_e32 v162, v163
	v_mov_b32_e32 v163, v181
	v_mov_b32_e32 v211, v180
	v_mov_b32_e32 v215, v180
	v_pk_mul_f32 v[162:163], v[204:205], v[162:163]
	ds_bpermute_b32 v208, v240, v206
	v_pk_fma_f32 v[162:163], v[210:211], v[214:215], v[162:163]
	ds_bpermute_b32 v209, v240, v207
	v_pk_add_f32 v[160:161], v[160:161], v[162:163]
	v_mul_f32_e32 v162, v183, v149
	v_pk_fma_f32 v[148:149], v[182:183], v[148:149], v[162:163] op_sel_hi:[1,1,0]
	v_mul_f32_e32 v162, v181, v151
	v_pk_fma_f32 v[150:151], v[180:181], v[150:151], v[162:163] op_sel_hi:[1,1,0]
	v_mov_b32_e32 v149, v213
	v_mov_b32_e32 v151, v33
	v_pk_add_f32 v[148:149], v[148:149], v[150:151]
	v_pk_mov_b32 v[150:151], v[152:153], v[188:189] op_sel:[1,0]
	v_mov_b32_e32 v153, v189
	v_pk_mul_f32 v[152:153], v[188:189], v[152:153]
	v_mov_b32_e32 v33, v185
	v_pk_fma_f32 v[150:151], v[188:189], v[150:151], v[152:153] op_sel:[1,0,0] op_sel_hi:[0,1,1]
	v_pk_mov_b32 v[152:153], v[154:155], v[186:187] op_sel:[1,0]
	v_mov_b32_e32 v155, v187
	v_pk_mul_f32 v[154:155], v[186:187], v[154:155]
	v_pk_add_f32 v[148:149], v[148:149], v[32:33]
	v_pk_fma_f32 v[152:153], v[186:187], v[152:153], v[154:155] op_sel:[1,0,0] op_sel_hi:[0,1,1]
	v_pk_add_f32 v[148:149], v[160:161], v[148:149]
	v_pk_add_f32 v[150:151], v[150:151], v[152:153]
	s_waitcnt lgkmcnt(0)
	v_pk_add_f32 v[206:207], v[206:207], v[208:209]
	v_pk_add_f32 v[148:149], v[148:149], v[150:151]
	v_pk_mov_b32 v[150:151], v[156:157], v[192:193] op_sel:[1,0]
	v_mov_b32_e32 v157, v193
	v_pk_mul_f32 v[152:153], v[192:193], v[156:157]
	ds_bpermute_b32 v208, v239, v206
	v_pk_fma_f32 v[150:151], v[192:193], v[150:151], v[152:153] op_sel:[1,0,0] op_sel_hi:[0,1,1]
	v_pk_mov_b32 v[152:153], v[158:159], v[190:191] op_sel:[1,0]
	v_mov_b32_e32 v159, v191
	v_pk_mul_f32 v[154:155], v[190:191], v[158:159]
	ds_bpermute_b32 v209, v239, v207
	v_pk_fma_f32 v[152:153], v[190:191], v[152:153], v[154:155] op_sel:[1,0,0] op_sel_hi:[0,1,1]
	v_pk_add_f32 v[150:151], v[150:151], v[152:153]
	s_nop 0
	v_pk_add_f32 v[148:149], v[148:149], v[150:151]
	ds_bpermute_b32 v150, v240, v148
	ds_bpermute_b32 v151, v240, v149
	s_waitcnt lgkmcnt(0)
	v_pk_add_f32 v[148:149], v[148:149], v[150:151]
	ds_bpermute_b32 v150, v239, v148
	ds_bpermute_b32 v151, v239, v149
	s_and_saveexec_b64 s[6:7], vcc
	s_cbranch_execz .LBB0_839
	v_lshl_add_u32 v33, v212, 6, s19
	s_waitcnt lgkmcnt(0)
	v_pk_add_f32 v[150:151], v[148:149], v[150:151]
	v_pk_add_f32 v[148:149], v[206:207], v[208:209]
	ds_write_b128 v33, v[148:151]
;     __device__ __forceinline__ void fused(f32x4 (&acc)[2][2][4][2], const Unit& u, int wr, int wc, int fr, int fq, PG8_LAS unsigned char* lds, int wid, int lane) const {
;     ...
;             for (int m = 0; m < 4; ++m) { const int r = ai * HALF + wr * 64 + m * 16 + fr; const size_t off = (size_t)(u.pm * BM + r) * 1024 + col0;
;                 float s0 = 0.f, s1 = 0.f, s2 = 0.f, s3 = 0.f;
; #pragma unroll
;                 for (int bj = 0; bj < 2; ++bj)
; #pragma unroll
;                     for (int n = 0; n < 2; ++n) { const f32x4 bs = *(const f32x4*)(base + off + bj * HALF + n * 16), a = acc[ai][bj][m][n], ag = a * gv[bj][n];
;                         s0 += (a[0] * a[0] + a[1] * a[1]) + (a[2] * a[2] + a[3] * a[3]); s1 += (bs[0] * bs[0] + bs[1] * bs[1]) + (bs[2] * bs[2] + bs[3] * bs[3]);
;                         s2 += (bs[0] * ag[0] + bs[1] * ag[1]) + (bs[2] * ag[2] + bs[3] * ag[3]); s3 += (ag[0] * ag[0] + ag[1] * ag[1]) + (ag[2] * ag[2] + ag[3] * ag[3]); }
;                 s0 += __shfl_xor(s0, 16); s0 += __shfl_xor(s0, 32); s1 += __shfl_xor(s1, 16); s1 += __shfl_xor(s1, 32);
;                 s2 += __shfl_xor(s2, 16); s2 += __shfl_xor(s2, 32); s3 += __shfl_xor(s3, 16); s3 += __shfl_xor(s3, 32);
;                 if (fq == 0) P[r * 4 + wc] = (f32x4){s0, s1, s2, s3};
.LBB0_839:
	s_or_b64 exec, exec, s[6:7]
	s_mov_b64 s[98:99], 0xa0000
	v_lshl_add_u64 v[160:161], v[164:165], 0, s[98:99]
	s_add_i32 m0, s72, 0x0
	s_nop 0
	global_load_lds_dwordx4 v[160:161], off
	s_mov_b64 s[98:99], 0xa0040
	v_lshl_add_u64 v[160:161], v[164:165], 0, s[98:99]
	s_add_i32 m0, s72, 0x400
	s_nop 0
	global_load_lds_dwordx4 v[160:161], off
	s_mov_b64 s[98:99], 0xa0200
	v_lshl_add_u64 v[160:161], v[164:165], 0, s[98:99]
	s_add_i32 m0, s72, 0x800
	s_nop 0
	global_load_lds_dwordx4 v[160:161], off
	s_mov_b64 s[98:99], 0xa0240
	v_lshl_add_u64 v[160:161], v[164:165], 0, s[98:99]
	s_add_i32 m0, s72, 0xc00
	s_nop 0
	global_load_lds_dwordx4 v[160:161], off
	v_add_u32_e32 v216, 0x80, v237
	v_add_u32_e32 v182, s17, v216
	v_ashrrev_i32_e32 v183, 31, v182
	v_lshlrev_b64 v[148:149], 12, v[182:183]
	v_lshl_add_u64 v[148:149], s[26:27], 0, v[148:149]
	v_lshl_add_u64 v[180:181], v[34:35], 2, v[148:149]
	s_waitcnt lgkmcnt(0)
	s_add_i32 s98, s72, 0x1000
	s_waitcnt vmcnt(8)
	v_and_b32_e32 v148, 63, v228
	v_lshl_add_u32 v148, v148, 4, s98
	ds_read_b128 v[148:151], v148
	v_and_b32_e32 v160, 63, v228
	v_lshl_add_u32 v160, v160, 4, s98
	ds_read_b128 v[160:163], v160 offset:1024
	v_pk_mul_f32 v[152:153], v[66:67], v[66:67]
	v_pk_mul_f32 v[154:155], v[64:65], v[64:65]
	v_pk_mul_f32 v[208:209], v[62:63], v[106:107]
	v_pk_mov_b32 v[156:157], v[154:155], v[152:153] op_sel:[1,0]
	v_mov_b32_e32 v155, v153
	v_pk_add_f32 v[210:211], v[156:157], v[154:155]
	v_pk_mul_f32 v[186:187], v[64:65], v[116:117]
	v_pk_add_f32 v[210:211], v[210:211], v[210:211] op_sel:[0,1] op_sel_hi:[1,0]
	v_pk_mul_f32 v[214:215], v[60:61], v[104:105]
	v_pk_mul_f32 v[184:185], v[66:67], v[118:119]
	v_mul_f32_e32 v217, v214, v214
	v_mul_f32_e32 v33, v215, v215
	v_pk_mul_f32 v[192:193], v[56:57], v[100:101]
	v_pk_mul_f32 v[190:191], v[58:59], v[102:103]
	v_pk_mul_f32 v[206:207], v[52:53], v[92:93]
	v_pk_mul_f32 v[204:205], v[54:55], v[94:95]
	s_waitcnt lgkmcnt(1)
	v_pk_mul_f32 v[152:153], v[150:151], v[150:151]
	v_pk_mul_f32 v[154:155], v[148:149], v[148:149]
	s_nop 0
	v_pk_mov_b32 v[156:157], v[154:155], v[152:153] op_sel:[1,0]
	v_mov_b32_e32 v155, v153
	v_pk_add_f32 v[152:153], v[156:157], v[154:155]
	v_pk_mul_f32 v[154:155], v[60:61], v[60:61]
	v_pk_add_f32 v[218:219], v[152:153], v[152:153] op_sel_hi:[0,1]
	v_pk_mul_f32 v[152:153], v[62:63], v[62:63]
	v_mul_f32_e32 v218, v52, v52
	v_pk_mov_b32 v[156:157], v[154:155], v[152:153] op_sel:[1,0]
	v_mov_b32_e32 v155, v153
	v_pk_add_f32 v[212:213], v[156:157], v[154:155]
	s_waitcnt lgkmcnt(0)
	v_pk_mul_f32 v[152:153], v[162:163], v[162:163]
	v_pk_mul_f32 v[154:155], v[160:161], v[160:161]
	v_pk_add_f32 v[212:213], v[212:213], v[212:213] op_sel:[0,1] op_sel_hi:[1,0]
	v_pk_mov_b32 v[156:157], v[154:155], v[152:153] op_sel:[1,0]
	v_mov_b32_e32 v155, v153
	v_pk_add_f32 v[152:153], v[156:157], v[154:155]
	s_nop 0
	v_pk_add_f32 v[220:221], v[152:153], v[152:153] op_sel_hi:[0,1]
	v_mul_f32_e32 v152, v208, v208
	v_pk_fma_f32 v[188:189], v[208:209], v[208:209], v[152:153] op_sel_hi:[1,1,0]
	v_and_b32_e32 v152, 63, v228
	v_lshl_add_u32 v152, v152, 4, s98
	ds_read_b128 v[152:155], v152 offset:2048
	v_mul_f32_e32 v220, v53, v53
	v_pk_add_f32 v[218:219], v[218:219], v[220:221]
	v_mul_f32_e32 v188, v57, v57
	s_waitcnt lgkmcnt(0)
	v_mul_f32_e32 v156, v152, v152
	v_pk_fma_f32 v[222:223], v[152:153], v[152:153], v[156:157] op_sel_hi:[1,1,0]
	v_mul_f32_e32 v156, v154, v154
	v_pk_fma_f32 v[224:225], v[154:155], v[154:155], v[156:157] op_sel_hi:[1,1,0]
	v_and_b32_e32 v156, 63, v228
	v_lshl_add_u32 v156, v156, 4, s98
	ds_read_b128 v[156:159], v156 offset:3072
	v_mul_f32_e32 v222, v54, v54
	v_mul_f32_e32 v224, v55, v55
	v_pk_add_f32 v[220:221], v[222:223], v[224:225]
	s_waitcnt lgkmcnt(0)
	v_mul_f32_e32 v226, v156, v156
	v_pk_add_f32 v[218:219], v[218:219], v[220:221]
	v_pk_fma_f32 v[220:221], v[56:57], v[56:57], v[188:189] op_sel_hi:[1,1,0]
	v_mul_f32_e32 v188, v59, v59
	v_mul_f32_e32 v227, v157, v157
	v_mul_f32_e32 v241, v158, v158
	v_mul_f32_e32 v242, v159, v159
	v_pk_fma_f32 v[222:223], v[58:59], v[58:59], v[188:189] op_sel_hi:[1,1,0]
	v_mov_b32_e32 v221, v226
	v_mov_b32_e32 v223, v227
	v_mov_b32_e32 v213, v241
	v_mov_b32_e32 v211, v242
	v_pk_add_f32 v[220:221], v[220:221], v[222:223]
	v_pk_add_f32 v[210:211], v[212:213], v[210:211]
	s_nop 0
	v_pk_add_f32 v[210:211], v[220:221], v[210:211]
	v_mov_b32_e32 v220, v160
	v_pk_add_f32 v[210:211], v[218:219], v[210:211]
	v_mov_b32_e32 v218, v214
	v_mov_b32_e32 v214, v215
	v_mov_b32_e32 v215, v187
	v_mov_b32_e32 v160, v161
	v_mov_b32_e32 v161, v187
	v_mov_b32_e32 v219, v186
	v_mov_b32_e32 v221, v186
	v_pk_mul_f32 v[160:161], v[214:215], v[160:161]
	v_mov_b32_e32 v214, v208
	v_pk_fma_f32 v[160:161], v[218:219], v[220:221], v[160:161]
	v_mov_b32_e32 v218, v162
	v_mov_b32_e32 v208, v209
	v_mov_b32_e32 v209, v185
	v_mov_b32_e32 v162, v163
	v_mov_b32_e32 v163, v185
	v_mov_b32_e32 v215, v184
	v_mov_b32_e32 v219, v184
	v_pk_mul_f32 v[162:163], v[208:209], v[162:163]
	ds_bpermute_b32 v212, v240, v210
	v_pk_fma_f32 v[162:163], v[214:215], v[218:219], v[162:163]
	ds_bpermute_b32 v213, v240, v211
	v_pk_add_f32 v[160:161], v[160:161], v[162:163]
	v_mul_f32_e32 v162, v187, v149
	v_pk_fma_f32 v[148:149], v[186:187], v[148:149], v[162:163] op_sel_hi:[1,1,0]
	v_mul_f32_e32 v162, v185, v151
	v_pk_fma_f32 v[150:151], v[184:185], v[150:151], v[162:163] op_sel_hi:[1,1,0]
	v_mov_b32_e32 v149, v217
	v_mov_b32_e32 v151, v33
	v_pk_add_f32 v[148:149], v[148:149], v[150:151]
	v_pk_mov_b32 v[150:151], v[152:153], v[192:193] op_sel:[1,0]
	v_mov_b32_e32 v153, v193
	v_pk_mul_f32 v[152:153], v[192:193], v[152:153]
	v_mov_b32_e32 v33, v189
	v_pk_fma_f32 v[150:151], v[192:193], v[150:151], v[152:153] op_sel:[1,0,0] op_sel_hi:[0,1,1]
	v_pk_mov_b32 v[152:153], v[154:155], v[190:191] op_sel:[1,0]
	v_mov_b32_e32 v155, v191
	v_pk_mul_f32 v[154:155], v[190:191], v[154:155]
	v_pk_add_f32 v[148:149], v[148:149], v[32:33]
	v_pk_fma_f32 v[152:153], v[190:191], v[152:153], v[154:155] op_sel:[1,0,0] op_sel_hi:[0,1,1]
	v_pk_add_f32 v[148:149], v[160:161], v[148:149]
	v_pk_add_f32 v[150:151], v[150:151], v[152:153]
	s_waitcnt lgkmcnt(0)
;     __device__ __forceinline__ void fused(f32x4 (&acc)[2][2][4][2], const Unit& u, int wr, int wc, int fr, int fq, PG8_LAS unsigned char* lds, int wid, int lane) const {
;     ...
;             for (int m = 0; m < 4; ++m) { const int r = ai * HALF + wr * 64 + m * 16 + fr; const size_t off = (size_t)(u.pm * BM + r) * 1024 + col0;
;                 float s0 = 0.f, s1 = 0.f, s2 = 0.f, s3 = 0.f;
; #pragma unroll
;                 for (int bj = 0; bj < 2; ++bj)
; #pragma unroll
;                     for (int n = 0; n < 2; ++n) { const f32x4 bs = *(const f32x4*)(base + off + bj * HALF + n * 16), a = acc[ai][bj][m][n], ag = a * gv[bj][n];
;                         s0 += (a[0] * a[0] + a[1] * a[1]) + (a[2] * a[2] + a[3] * a[3]); s1 += (bs[0] * bs[0] + bs[1] * bs[1]) + (bs[2] * bs[2] + bs[3] * bs[3]);
;                         s2 += (bs[0] * ag[0] + bs[1] * ag[1]) + (bs[2] * ag[2] + bs[3] * ag[3]); s3 += (ag[0] * ag[0] + ag[1] * ag[1]) + (ag[2] * ag[2] + ag[3] * ag[3]); }
;                 s0 += __shfl_xor(s0, 16); s0 += __shfl_xor(s0, 32); s1 += __shfl_xor(s1, 16); s1 += __shfl_xor(s1, 32);
;                 s2 += __shfl_xor(s2, 16); s2 += __shfl_xor(s2, 32); s3 += __shfl_xor(s3, 16); s3 += __shfl_xor(s3, 32);
;                 if (fq == 0) P[r * 4 + wc] = (f32x4){s0, s1, s2, s3};
	v_pk_add_f32 v[210:211], v[210:211], v[212:213]
	v_pk_add_f32 v[148:149], v[148:149], v[150:151]
	v_pk_mov_b32 v[150:151], v[156:157], v[206:207] op_sel:[1,0]
	v_mov_b32_e32 v157, v207
	v_pk_mul_f32 v[152:153], v[206:207], v[156:157]
	ds_bpermute_b32 v212, v239, v210
	v_pk_fma_f32 v[150:151], v[206:207], v[150:151], v[152:153] op_sel:[1,0,0] op_sel_hi:[0,1,1]
	v_pk_mov_b32 v[152:153], v[158:159], v[204:205] op_sel:[1,0]
	v_mov_b32_e32 v159, v205
	v_pk_mul_f32 v[154:155], v[204:205], v[158:159]
	ds_bpermute_b32 v213, v239, v211
	v_pk_fma_f32 v[152:153], v[204:205], v[152:153], v[154:155] op_sel:[1,0,0] op_sel_hi:[0,1,1]
	v_pk_add_f32 v[150:151], v[150:151], v[152:153]
	s_nop 0
	v_pk_add_f32 v[148:149], v[148:149], v[150:151]
	ds_bpermute_b32 v150, v240, v148
	ds_bpermute_b32 v151, v240, v149
	s_waitcnt lgkmcnt(0)
	v_pk_add_f32 v[148:149], v[148:149], v[150:151]
	ds_bpermute_b32 v150, v239, v148
	ds_bpermute_b32 v151, v239, v149
	s_and_saveexec_b64 s[6:7], vcc
	s_cbranch_execz .LBB0_841
	v_lshl_add_u32 v33, v216, 6, s19
	s_waitcnt lgkmcnt(0)
	v_pk_add_f32 v[150:151], v[148:149], v[150:151]
	v_pk_add_f32 v[148:149], v[210:211], v[212:213]
	ds_write_b128 v33, v[148:151]
.LBB0_841:
	s_or_b64 exec, exec, s[6:7]
	s_mov_b64 s[98:99], 0xb0000
	v_lshl_add_u64 v[160:161], v[164:165], 0, s[98:99]
	s_add_i32 m0, s72, 0x1000
	s_nop 0
	global_load_lds_dwordx4 v[160:161], off
	s_mov_b64 s[98:99], 0xb0040
	v_lshl_add_u64 v[160:161], v[164:165], 0, s[98:99]
	s_add_i32 m0, s72, 0x1400
	s_nop 0
	global_load_lds_dwordx4 v[160:161], off
	s_mov_b64 s[98:99], 0xb0200
	v_lshl_add_u64 v[160:161], v[164:165], 0, s[98:99]
	s_add_i32 m0, s72, 0x1800
	s_nop 0
	global_load_lds_dwordx4 v[160:161], off
	s_mov_b64 s[98:99], 0xb0240
	v_lshl_add_u64 v[160:161], v[164:165], 0, s[98:99]
	s_add_i32 m0, s72, 0x1c00
	s_nop 0
	global_load_lds_dwordx4 v[160:161], off
	v_add_u32_e32 v220, 0x90, v237
	v_add_u32_e32 v186, s17, v220
	v_ashrrev_i32_e32 v187, 31, v186
	v_lshlrev_b64 v[148:149], 12, v[186:187]
	v_lshl_add_u64 v[148:149], s[26:27], 0, v[148:149]
	v_lshl_add_u64 v[184:185], v[34:35], 2, v[148:149]
	s_waitcnt lgkmcnt(0)
	s_add_i32 s98, s72, 0x2000
	s_waitcnt vmcnt(8)
	v_and_b32_e32 v148, 63, v228
	v_lshl_add_u32 v148, v148, 4, s98
	ds_read_b128 v[148:151], v148
	v_and_b32_e32 v160, 63, v228
	v_lshl_add_u32 v160, v160, 4, s98
	ds_read_b128 v[160:163], v160 offset:1024
	v_pk_mul_f32 v[152:153], v[50:51], v[50:51]
	v_pk_mul_f32 v[154:155], v[48:49], v[48:49]
	v_pk_mul_f32 v[212:213], v[46:47], v[106:107]
	v_pk_mov_b32 v[156:157], v[154:155], v[152:153] op_sel:[1,0]
	v_mov_b32_e32 v155, v153
	v_pk_add_f32 v[214:215], v[156:157], v[154:155]
	v_pk_mul_f32 v[190:191], v[48:49], v[116:117]
	v_pk_add_f32 v[214:215], v[214:215], v[214:215] op_sel:[0,1] op_sel_hi:[1,0]
	v_pk_mul_f32 v[218:219], v[44:45], v[104:105]
	v_pk_mul_f32 v[188:189], v[50:51], v[118:119]
	v_mul_f32_e32 v221, v218, v218
	v_mul_f32_e32 v33, v219, v219
	v_pk_mul_f32 v[206:207], v[40:41], v[100:101]
	v_pk_mul_f32 v[204:205], v[42:43], v[102:103]
	v_pk_mul_f32 v[210:211], v[36:37], v[92:93]
	v_pk_mul_f32 v[208:209], v[38:39], v[94:95]
	s_waitcnt lgkmcnt(1)
	v_pk_mul_f32 v[152:153], v[150:151], v[150:151]
	v_pk_mul_f32 v[154:155], v[148:149], v[148:149]
	s_nop 0
	v_pk_mov_b32 v[156:157], v[154:155], v[152:153] op_sel:[1,0]
	v_mov_b32_e32 v155, v153
	v_pk_add_f32 v[152:153], v[156:157], v[154:155]
	v_pk_mul_f32 v[154:155], v[44:45], v[44:45]
	v_pk_add_f32 v[222:223], v[152:153], v[152:153] op_sel_hi:[0,1]
	v_pk_mul_f32 v[152:153], v[46:47], v[46:47]
	v_mul_f32_e32 v222, v36, v36
	v_pk_mov_b32 v[156:157], v[154:155], v[152:153] op_sel:[1,0]
	v_mov_b32_e32 v155, v153
	v_pk_add_f32 v[216:217], v[156:157], v[154:155]
	s_waitcnt lgkmcnt(0)
	v_pk_mul_f32 v[152:153], v[162:163], v[162:163]
	v_pk_mul_f32 v[154:155], v[160:161], v[160:161]
	v_pk_add_f32 v[216:217], v[216:217], v[216:217] op_sel:[0,1] op_sel_hi:[1,0]
	v_pk_mov_b32 v[156:157], v[154:155], v[152:153] op_sel:[1,0]
	v_mov_b32_e32 v155, v153
	v_pk_add_f32 v[152:153], v[156:157], v[154:155]
	s_nop 0
	v_pk_add_f32 v[224:225], v[152:153], v[152:153] op_sel_hi:[0,1]
	v_mul_f32_e32 v152, v212, v212
	v_pk_fma_f32 v[192:193], v[212:213], v[212:213], v[152:153] op_sel_hi:[1,1,0]
	v_and_b32_e32 v152, 63, v228
	v_lshl_add_u32 v152, v152, 4, s98
	ds_read_b128 v[152:155], v152 offset:2048
	v_mul_f32_e32 v224, v37, v37
	v_pk_add_f32 v[222:223], v[222:223], v[224:225]
	v_mul_f32_e32 v192, v41, v41
	s_waitcnt lgkmcnt(0)
	v_mul_f32_e32 v156, v152, v152
	v_pk_fma_f32 v[226:227], v[152:153], v[152:153], v[156:157] op_sel_hi:[1,1,0]
	v_mul_f32_e32 v156, v154, v154
	v_pk_fma_f32 v[242:243], v[154:155], v[154:155], v[156:157] op_sel_hi:[1,1,0]
	v_and_b32_e32 v156, 63, v228
	v_lshl_add_u32 v156, v156, 4, s98
	ds_read_b128 v[156:159], v156 offset:3072
	v_mul_f32_e32 v226, v38, v38
	v_mul_f32_e32 v242, v39, v39
	v_pk_add_f32 v[224:225], v[226:227], v[242:243]
	s_waitcnt lgkmcnt(0)
;     __device__ __forceinline__ void fused(f32x4 (&acc)[2][2][4][2], const Unit& u, int wr, int wc, int fr, int fq, PG8_LAS unsigned char* lds, int wid, int lane) const {
;     ...
;             for (int m = 0; m < 4; ++m) { const int r = ai * HALF + wr * 64 + m * 16 + fr; const size_t off = (size_t)(u.pm * BM + r) * 1024 + col0;
;                 float s0 = 0.f, s1 = 0.f, s2 = 0.f, s3 = 0.f;
; #pragma unroll
;                 for (int bj = 0; bj < 2; ++bj)
; #pragma unroll
;                     for (int n = 0; n < 2; ++n) { const f32x4 bs = *(const f32x4*)(base + off + bj * HALF + n * 16), a = acc[ai][bj][m][n], ag = a * gv[bj][n];
;                         s0 += (a[0] * a[0] + a[1] * a[1]) + (a[2] * a[2] + a[3] * a[3]); s1 += (bs[0] * bs[0] + bs[1] * bs[1]) + (bs[2] * bs[2] + bs[3] * bs[3]);
;                         s2 += (bs[0] * ag[0] + bs[1] * ag[1]) + (bs[2] * ag[2] + bs[3] * ag[3]); s3 += (ag[0] * ag[0] + ag[1] * ag[1]) + (ag[2] * ag[2] + ag[3] * ag[3]); }
;                 s0 += __shfl_xor(s0, 16); s0 += __shfl_xor(s0, 32); s1 += __shfl_xor(s1, 16); s1 += __shfl_xor(s1, 32);
;                 s2 += __shfl_xor(s2, 16); s2 += __shfl_xor(s2, 32); s3 += __shfl_xor(s3, 16); s3 += __shfl_xor(s3, 32);
;                 if (fq == 0) P[r * 4 + wc] = (f32x4){s0, s1, s2, s3};
;                 if (m & 1) asm volatile("" ::: "memory"); }
	v_mul_f32_e32 v241, v156, v156
	v_pk_add_f32 v[222:223], v[222:223], v[224:225]
	v_pk_fma_f32 v[224:225], v[40:41], v[40:41], v[192:193] op_sel_hi:[1,1,0]
	v_mul_f32_e32 v192, v43, v43
	v_mul_f32_e32 v244, v157, v157
	v_mul_f32_e32 v245, v158, v158
	v_mul_f32_e32 v246, v159, v159
	v_pk_fma_f32 v[226:227], v[42:43], v[42:43], v[192:193] op_sel_hi:[1,1,0]
	v_mov_b32_e32 v225, v241
	v_mov_b32_e32 v227, v244
	v_mov_b32_e32 v217, v245
	v_mov_b32_e32 v215, v246
	v_pk_add_f32 v[224:225], v[224:225], v[226:227]
	v_pk_add_f32 v[214:215], v[216:217], v[214:215]
	s_nop 0
	v_pk_add_f32 v[214:215], v[224:225], v[214:215]
	v_mov_b32_e32 v224, v160
	v_pk_add_f32 v[214:215], v[222:223], v[214:215]
	v_mov_b32_e32 v222, v218
	v_mov_b32_e32 v218, v219
	v_mov_b32_e32 v219, v191
	v_mov_b32_e32 v160, v161
	v_mov_b32_e32 v161, v191
	v_mov_b32_e32 v223, v190
	v_mov_b32_e32 v225, v190
	v_pk_mul_f32 v[160:161], v[218:219], v[160:161]
	v_mov_b32_e32 v218, v212
	v_pk_fma_f32 v[160:161], v[222:223], v[224:225], v[160:161]
	v_mov_b32_e32 v222, v162
	v_mov_b32_e32 v212, v213
	v_mov_b32_e32 v213, v189
	v_mov_b32_e32 v162, v163
	v_mov_b32_e32 v163, v189
	v_mov_b32_e32 v219, v188
	v_mov_b32_e32 v223, v188
	v_pk_mul_f32 v[162:163], v[212:213], v[162:163]
	ds_bpermute_b32 v216, v240, v214
	v_pk_fma_f32 v[162:163], v[218:219], v[222:223], v[162:163]
	ds_bpermute_b32 v217, v240, v215
	v_pk_add_f32 v[160:161], v[160:161], v[162:163]
	v_mul_f32_e32 v162, v191, v149
	v_pk_fma_f32 v[148:149], v[190:191], v[148:149], v[162:163] op_sel_hi:[1,1,0]
	v_mul_f32_e32 v162, v189, v151
	v_pk_fma_f32 v[150:151], v[188:189], v[150:151], v[162:163] op_sel_hi:[1,1,0]
	v_mov_b32_e32 v149, v221
	v_mov_b32_e32 v151, v33
	v_pk_add_f32 v[148:149], v[148:149], v[150:151]
	v_pk_mov_b32 v[150:151], v[152:153], v[206:207] op_sel:[1,0]
	v_mov_b32_e32 v153, v207
	v_pk_mul_f32 v[152:153], v[206:207], v[152:153]
	v_mov_b32_e32 v33, v193
	v_pk_fma_f32 v[150:151], v[206:207], v[150:151], v[152:153] op_sel:[1,0,0] op_sel_hi:[0,1,1]
	v_pk_mov_b32 v[152:153], v[154:155], v[204:205] op_sel:[1,0]
	v_mov_b32_e32 v155, v205
	v_pk_mul_f32 v[154:155], v[204:205], v[154:155]
	v_pk_add_f32 v[148:149], v[148:149], v[32:33]
	v_pk_fma_f32 v[152:153], v[204:205], v[152:153], v[154:155] op_sel:[1,0,0] op_sel_hi:[0,1,1]
	v_pk_add_f32 v[148:149], v[160:161], v[148:149]
	v_pk_add_f32 v[150:151], v[150:151], v[152:153]
	s_waitcnt lgkmcnt(0)
	v_pk_add_f32 v[214:215], v[214:215], v[216:217]
	v_pk_add_f32 v[148:149], v[148:149], v[150:151]
	v_pk_mov_b32 v[150:151], v[156:157], v[210:211] op_sel:[1,0]
	v_mov_b32_e32 v157, v211
	v_pk_mul_f32 v[152:153], v[210:211], v[156:157]
	ds_bpermute_b32 v216, v239, v214
	v_pk_fma_f32 v[150:151], v[210:211], v[150:151], v[152:153] op_sel:[1,0,0] op_sel_hi:[0,1,1]
	v_pk_mov_b32 v[152:153], v[158:159], v[208:209] op_sel:[1,0]
	v_mov_b32_e32 v159, v209
	v_pk_mul_f32 v[154:155], v[208:209], v[158:159]
	ds_bpermute_b32 v217, v239, v215
	v_pk_fma_f32 v[152:153], v[208:209], v[152:153], v[154:155] op_sel:[1,0,0] op_sel_hi:[0,1,1]
	v_pk_add_f32 v[150:151], v[150:151], v[152:153]
	s_nop 0
	v_pk_add_f32 v[148:149], v[148:149], v[150:151]
	ds_bpermute_b32 v150, v240, v148
	ds_bpermute_b32 v151, v240, v149
	s_waitcnt lgkmcnt(0)
	v_pk_add_f32 v[148:149], v[148:149], v[150:151]
	ds_bpermute_b32 v150, v239, v148
	ds_bpermute_b32 v151, v239, v149
	s_and_saveexec_b64 s[6:7], vcc
	s_cbranch_execz .LBB0_843
	v_lshl_add_u32 v33, v220, 6, s19
	s_waitcnt lgkmcnt(0)
	v_pk_add_f32 v[150:151], v[148:149], v[150:151]
	v_pk_add_f32 v[148:149], v[214:215], v[216:217]
	ds_write_b128 v33, v[148:151]
.LBB0_843:
	s_or_b64 exec, exec, s[6:7]
	v_add_u32_e32 v224, 0xa0, v237
	v_add_u32_e32 v190, s17, v224
	v_ashrrev_i32_e32 v191, 31, v190
	v_lshlrev_b64 v[148:149], 12, v[190:191]
	v_lshl_add_u64 v[148:149], s[26:27], 0, v[148:149]
	v_lshl_add_u64 v[188:189], v[34:35], 2, v[148:149]
	s_waitcnt lgkmcnt(0)
	s_add_i32 s98, s72, 0x0
	s_waitcnt vmcnt(4)
	v_and_b32_e32 v148, 63, v228
	v_lshl_add_u32 v148, v148, 4, s98
	ds_read_b128 v[148:151], v148
	v_and_b32_e32 v160, 63, v228
	v_lshl_add_u32 v160, v160, 4, s98
	ds_read_b128 v[160:163], v160 offset:1024
	v_pk_mul_f32 v[152:153], v[30:31], v[30:31]
	v_pk_mul_f32 v[154:155], v[28:29], v[28:29]
	v_pk_mul_f32 v[216:217], v[26:27], v[106:107]
	v_pk_mov_b32 v[156:157], v[154:155], v[152:153] op_sel:[1,0]
	v_mov_b32_e32 v155, v153
	v_pk_add_f32 v[218:219], v[156:157], v[154:155]
	v_pk_mul_f32 v[204:205], v[28:29], v[116:117]
	v_pk_add_f32 v[218:219], v[218:219], v[218:219] op_sel:[0,1] op_sel_hi:[1,0]
	v_pk_mul_f32 v[222:223], v[24:25], v[104:105]
	v_pk_mul_f32 v[192:193], v[30:31], v[118:119]
	v_mul_f32_e32 v225, v222, v222
	v_mul_f32_e32 v33, v223, v223
	v_pk_mul_f32 v[210:211], v[20:21], v[100:101]
	v_pk_mul_f32 v[208:209], v[22:23], v[102:103]
	v_pk_mul_f32 v[214:215], v[16:17], v[92:93]
	v_pk_mul_f32 v[212:213], v[18:19], v[94:95]
	s_waitcnt lgkmcnt(1)
	v_pk_mul_f32 v[152:153], v[150:151], v[150:151]
	v_pk_mul_f32 v[154:155], v[148:149], v[148:149]
	s_nop 0
	v_pk_mov_b32 v[156:157], v[154:155], v[152:153] op_sel:[1,0]
	v_mov_b32_e32 v155, v153
	v_pk_add_f32 v[152:153], v[156:157], v[154:155]
	v_pk_mul_f32 v[154:155], v[24:25], v[24:25]
	v_pk_add_f32 v[226:227], v[152:153], v[152:153] op_sel_hi:[0,1]
	v_pk_mul_f32 v[152:153], v[26:27], v[26:27]
	v_mul_f32_e32 v226, v16, v16
	v_pk_mov_b32 v[156:157], v[154:155], v[152:153] op_sel:[1,0]
	v_mov_b32_e32 v155, v153
	v_pk_add_f32 v[220:221], v[156:157], v[154:155]
	s_waitcnt lgkmcnt(0)
;     __device__ __forceinline__ void fused(f32x4 (&acc)[2][2][4][2], const Unit& u, int wr, int wc, int fr, int fq, PG8_LAS unsigned char* lds, int wid, int lane) const {
;     ...
;                     for (int n = 0; n < 2; ++n) { const f32x4 bs = *(const f32x4*)(base + off + bj * HALF + n * 16), a = acc[ai][bj][m][n], ag = a * gv[bj][n];
;                         s0 += (a[0] * a[0] + a[1] * a[1]) + (a[2] * a[2] + a[3] * a[3]); s1 += (bs[0] * bs[0] + bs[1] * bs[1]) + (bs[2] * bs[2] + bs[3] * bs[3]);
;                         s2 += (bs[0] * ag[0] + bs[1] * ag[1]) + (bs[2] * ag[2] + bs[3] * ag[3]); s3 += (ag[0] * ag[0] + ag[1] * ag[1]) + (ag[2] * ag[2] + ag[3] * ag[3]); }
;                 s0 += __shfl_xor(s0, 16); s0 += __shfl_xor(s0, 32); s1 += __shfl_xor(s1, 16); s1 += __shfl_xor(s1, 32);
;                 s2 += __shfl_xor(s2, 16); s2 += __shfl_xor(s2, 32); s3 += __shfl_xor(s3, 16); s3 += __shfl_xor(s3, 32);
;                 if (fq == 0) P[r * 4 + wc] = (f32x4){s0, s1, s2, s3};
	v_pk_mul_f32 v[152:153], v[162:163], v[162:163]
	v_pk_mul_f32 v[154:155], v[160:161], v[160:161]
	v_pk_add_f32 v[220:221], v[220:221], v[220:221] op_sel:[0,1] op_sel_hi:[1,0]
	v_pk_mov_b32 v[156:157], v[154:155], v[152:153] op_sel:[1,0]
	v_mov_b32_e32 v155, v153
	v_pk_add_f32 v[152:153], v[156:157], v[154:155]
	s_nop 0
	v_pk_add_f32 v[242:243], v[152:153], v[152:153] op_sel_hi:[0,1]
	v_mul_f32_e32 v152, v216, v216
	v_pk_fma_f32 v[206:207], v[216:217], v[216:217], v[152:153] op_sel_hi:[1,1,0]
	v_and_b32_e32 v152, 63, v228
	v_lshl_add_u32 v152, v152, 4, s98
	ds_read_b128 v[152:155], v152 offset:2048
	v_mul_f32_e32 v242, v17, v17
	v_pk_add_f32 v[226:227], v[226:227], v[242:243]
	v_mul_f32_e32 v206, v21, v21
	s_waitcnt lgkmcnt(0)
	v_mul_f32_e32 v156, v152, v152
	v_pk_fma_f32 v[244:245], v[152:153], v[152:153], v[156:157] op_sel_hi:[1,1,0]
	v_mul_f32_e32 v156, v154, v154
	v_pk_fma_f32 v[246:247], v[154:155], v[154:155], v[156:157] op_sel_hi:[1,1,0]
	v_and_b32_e32 v156, 63, v228
	v_lshl_add_u32 v156, v156, 4, s98
	ds_read_b128 v[156:159], v156 offset:3072
	v_mul_f32_e32 v244, v18, v18
	v_mul_f32_e32 v246, v19, v19
	v_pk_add_f32 v[242:243], v[244:245], v[246:247]
	s_waitcnt lgkmcnt(0)
	v_mul_f32_e32 v241, v156, v156
	v_pk_add_f32 v[226:227], v[226:227], v[242:243]
	v_pk_fma_f32 v[242:243], v[20:21], v[20:21], v[206:207] op_sel_hi:[1,1,0]
	v_mul_f32_e32 v206, v23, v23
	v_mul_f32_e32 v248, v157, v157
	v_mul_f32_e32 v249, v158, v158
	v_mul_f32_e32 v250, v159, v159
	v_pk_fma_f32 v[244:245], v[22:23], v[22:23], v[206:207] op_sel_hi:[1,1,0]
	v_mov_b32_e32 v243, v241
	v_mov_b32_e32 v245, v248
	v_mov_b32_e32 v221, v249
	v_mov_b32_e32 v219, v250
	v_pk_add_f32 v[242:243], v[242:243], v[244:245]
	v_pk_add_f32 v[218:219], v[220:221], v[218:219]
	s_nop 0
	v_pk_add_f32 v[218:219], v[242:243], v[218:219]
	v_mov_b32_e32 v242, v160
	v_pk_add_f32 v[218:219], v[226:227], v[218:219]
	v_mov_b32_e32 v226, v222
	v_mov_b32_e32 v222, v223
	v_mov_b32_e32 v223, v205
	v_mov_b32_e32 v160, v161
	v_mov_b32_e32 v161, v205
	v_mov_b32_e32 v227, v204
	v_mov_b32_e32 v243, v204
	v_pk_mul_f32 v[160:161], v[222:223], v[160:161]
	v_mov_b32_e32 v222, v216
	v_pk_fma_f32 v[160:161], v[226:227], v[242:243], v[160:161]
	v_mov_b32_e32 v226, v162
	v_mov_b32_e32 v216, v217
	v_mov_b32_e32 v217, v193
	v_mov_b32_e32 v162, v163
	v_mov_b32_e32 v163, v193
	v_mov_b32_e32 v223, v192
	v_mov_b32_e32 v227, v192
	v_pk_mul_f32 v[162:163], v[216:217], v[162:163]
	ds_bpermute_b32 v220, v240, v218
	v_pk_fma_f32 v[162:163], v[222:223], v[226:227], v[162:163]
	ds_bpermute_b32 v221, v240, v219
	v_pk_add_f32 v[160:161], v[160:161], v[162:163]
	v_mul_f32_e32 v162, v205, v149
	v_pk_fma_f32 v[148:149], v[204:205], v[148:149], v[162:163] op_sel_hi:[1,1,0]
	v_mul_f32_e32 v162, v193, v151
	v_pk_fma_f32 v[150:151], v[192:193], v[150:151], v[162:163] op_sel_hi:[1,1,0]
	v_mov_b32_e32 v149, v225
	v_mov_b32_e32 v151, v33
	v_pk_add_f32 v[148:149], v[148:149], v[150:151]
	v_pk_mov_b32 v[150:151], v[152:153], v[210:211] op_sel:[1,0]
	v_mov_b32_e32 v153, v211
	v_pk_mul_f32 v[152:153], v[210:211], v[152:153]
	v_mov_b32_e32 v33, v207
	v_pk_fma_f32 v[150:151], v[210:211], v[150:151], v[152:153] op_sel:[1,0,0] op_sel_hi:[0,1,1]
	v_pk_mov_b32 v[152:153], v[154:155], v[208:209] op_sel:[1,0]
	v_mov_b32_e32 v155, v209
	v_pk_mul_f32 v[154:155], v[208:209], v[154:155]
	v_pk_add_f32 v[148:149], v[148:149], v[32:33]
	v_pk_fma_f32 v[152:153], v[208:209], v[152:153], v[154:155] op_sel:[1,0,0] op_sel_hi:[0,1,1]
	v_pk_add_f32 v[148:149], v[160:161], v[148:149]
	v_pk_add_f32 v[150:151], v[150:151], v[152:153]
	s_waitcnt lgkmcnt(0)
	v_pk_add_f32 v[218:219], v[218:219], v[220:221]
	v_pk_add_f32 v[148:149], v[148:149], v[150:151]
	v_pk_mov_b32 v[150:151], v[156:157], v[214:215] op_sel:[1,0]
	v_mov_b32_e32 v157, v215
	v_pk_mul_f32 v[152:153], v[214:215], v[156:157]
	ds_bpermute_b32 v220, v239, v218
	v_pk_fma_f32 v[150:151], v[214:215], v[150:151], v[152:153] op_sel:[1,0,0] op_sel_hi:[0,1,1]
	v_pk_mov_b32 v[152:153], v[158:159], v[212:213] op_sel:[1,0]
	v_mov_b32_e32 v159, v213
	v_pk_mul_f32 v[154:155], v[212:213], v[158:159]
	ds_bpermute_b32 v221, v239, v219
	v_pk_fma_f32 v[152:153], v[212:213], v[152:153], v[154:155] op_sel:[1,0,0] op_sel_hi:[0,1,1]
	v_pk_add_f32 v[150:151], v[150:151], v[152:153]
	s_nop 0
	v_pk_add_f32 v[148:149], v[148:149], v[150:151]
	ds_bpermute_b32 v150, v240, v148
	ds_bpermute_b32 v151, v240, v149
	s_waitcnt lgkmcnt(0)
	v_pk_add_f32 v[148:149], v[148:149], v[150:151]
	ds_bpermute_b32 v150, v239, v148
	ds_bpermute_b32 v151, v239, v149
	s_and_saveexec_b64 s[6:7], vcc
	s_cbranch_execz .LBB0_845
	v_lshl_add_u32 v33, v224, 6, s19
	s_waitcnt lgkmcnt(0)
	v_pk_add_f32 v[150:151], v[148:149], v[150:151]
	v_pk_add_f32 v[148:149], v[218:219], v[220:221]
	ds_write_b128 v33, v[148:151]
;     __device__ __forceinline__ void fused(f32x4 (&acc)[2][2][4][2], const Unit& u, int wr, int wc, int fr, int fq, PG8_LAS unsigned char* lds, int wid, int lane) const {
;     ...
;             for (int m = 0; m < 4; ++m) { const int r = ai * HALF + wr * 64 + m * 16 + fr; const size_t off = (size_t)(u.pm * BM + r) * 1024 + col0;
;                 float s0 = 0.f, s1 = 0.f, s2 = 0.f, s3 = 0.f;
; #pragma unroll
;                 for (int bj = 0; bj < 2; ++bj)
; #pragma unroll
;                     for (int n = 0; n < 2; ++n) { const f32x4 bs = *(const f32x4*)(base + off + bj * HALF + n * 16), a = acc[ai][bj][m][n], ag = a * gv[bj][n];
;                         s0 += (a[0] * a[0] + a[1] * a[1]) + (a[2] * a[2] + a[3] * a[3]); s1 += (bs[0] * bs[0] + bs[1] * bs[1]) + (bs[2] * bs[2] + bs[3] * bs[3]);
;                         s2 += (bs[0] * ag[0] + bs[1] * ag[1]) + (bs[2] * ag[2] + bs[3] * ag[3]); s3 += (ag[0] * ag[0] + ag[1] * ag[1]) + (ag[2] * ag[2] + ag[3] * ag[3]); }
;                 s0 += __shfl_xor(s0, 16); s0 += __shfl_xor(s0, 32); s1 += __shfl_xor(s1, 16); s1 += __shfl_xor(s1, 32);
;                 s2 += __shfl_xor(s2, 16); s2 += __shfl_xor(s2, 32); s3 += __shfl_xor(s3, 16); s3 += __shfl_xor(s3, 32);
;                 if (fq == 0) P[r * 4 + wc] = (f32x4){s0, s1, s2, s3};
;                 if (m & 1) asm volatile("" ::: "memory"); }
.LBB0_845:
	s_or_b64 exec, exec, s[6:7]
	v_add_u32_e32 v241, 0xb0, v237
	v_add_u32_e32 v204, s17, v241
	v_ashrrev_i32_e32 v205, 31, v204
	v_lshlrev_b64 v[148:149], 12, v[204:205]
	v_lshl_add_u64 v[148:149], s[26:27], 0, v[148:149]
	v_lshl_add_u64 v[192:193], v[34:35], 2, v[148:149]
	s_waitcnt lgkmcnt(0)
	s_add_i32 s98, s72, 0x1000
	s_waitcnt vmcnt(0)
	v_and_b32_e32 v148, 63, v228
	v_lshl_add_u32 v148, v148, 4, s98
	ds_read_b128 v[148:151], v148
	v_and_b32_e32 v160, 63, v228
	v_lshl_add_u32 v160, v160, 4, s98
	ds_read_b128 v[160:163], v160 offset:1024
	v_pk_mul_f32 v[152:153], v[14:15], v[14:15]
	v_pk_mul_f32 v[154:155], v[12:13], v[12:13]
	v_pk_mul_f32 v[220:221], v[10:11], v[106:107]
	v_pk_mov_b32 v[156:157], v[154:155], v[152:153] op_sel:[1,0]
	v_mov_b32_e32 v155, v153
	v_pk_add_f32 v[222:223], v[156:157], v[154:155]
	v_pk_mul_f32 v[208:209], v[12:13], v[116:117]
	v_pk_add_f32 v[222:223], v[222:223], v[222:223] op_sel:[0,1] op_sel_hi:[1,0]
	v_pk_mul_f32 v[226:227], v[8:9], v[104:105]
	v_pk_mul_f32 v[206:207], v[14:15], v[118:119]
	v_mul_f32_e32 v242, v226, v226
	v_mul_f32_e32 v33, v227, v227
	v_pk_mul_f32 v[214:215], v[4:5], v[100:101]
	v_pk_mul_f32 v[212:213], v[6:7], v[102:103]
	v_pk_mul_f32 v[218:219], v[0:1], v[92:93]
	v_pk_mul_f32 v[216:217], v[2:3], v[94:95]
	s_waitcnt lgkmcnt(1)
	v_pk_mul_f32 v[152:153], v[150:151], v[150:151]
	v_pk_mul_f32 v[154:155], v[148:149], v[148:149]
	s_nop 0
	v_pk_mov_b32 v[156:157], v[154:155], v[152:153] op_sel:[1,0]
	v_mov_b32_e32 v155, v153
	v_pk_add_f32 v[152:153], v[156:157], v[154:155]
	v_pk_mul_f32 v[154:155], v[8:9], v[8:9]
	v_pk_add_f32 v[244:245], v[152:153], v[152:153] op_sel_hi:[0,1]
	v_pk_mul_f32 v[152:153], v[10:11], v[10:11]
	v_mul_f32_e32 v244, v0, v0
	v_pk_mov_b32 v[156:157], v[154:155], v[152:153] op_sel:[1,0]
	v_mov_b32_e32 v155, v153
	v_pk_add_f32 v[224:225], v[156:157], v[154:155]
	s_waitcnt lgkmcnt(0)
	v_pk_mul_f32 v[152:153], v[162:163], v[162:163]
	v_pk_mul_f32 v[154:155], v[160:161], v[160:161]
	v_pk_add_f32 v[224:225], v[224:225], v[224:225] op_sel:[0,1] op_sel_hi:[1,0]
	v_pk_mov_b32 v[156:157], v[154:155], v[152:153] op_sel:[1,0]
	v_mov_b32_e32 v155, v153
	v_pk_add_f32 v[152:153], v[156:157], v[154:155]
	s_nop 0
	v_pk_add_f32 v[246:247], v[152:153], v[152:153] op_sel_hi:[0,1]
	v_mul_f32_e32 v152, v220, v220
	v_pk_fma_f32 v[210:211], v[220:221], v[220:221], v[152:153] op_sel_hi:[1,1,0]
	v_and_b32_e32 v152, 63, v228
	v_lshl_add_u32 v152, v152, 4, s98
	ds_read_b128 v[152:155], v152 offset:2048
	v_mul_f32_e32 v246, v1, v1
	v_pk_add_f32 v[244:245], v[244:245], v[246:247]
	v_mul_f32_e32 v210, v5, v5
	s_waitcnt lgkmcnt(0)
	v_mul_f32_e32 v156, v152, v152
	v_pk_fma_f32 v[248:249], v[152:153], v[152:153], v[156:157] op_sel_hi:[1,1,0]
	v_mul_f32_e32 v156, v154, v154
	v_pk_fma_f32 v[250:251], v[154:155], v[154:155], v[156:157] op_sel_hi:[1,1,0]
	v_and_b32_e32 v156, 63, v228
	v_lshl_add_u32 v156, v156, 4, s98
	ds_read_b128 v[156:159], v156 offset:3072
	v_mul_f32_e32 v248, v2, v2
	v_mul_f32_e32 v250, v3, v3
	v_pk_add_f32 v[246:247], v[248:249], v[250:251]
	s_waitcnt lgkmcnt(0)
	v_mul_f32_e32 v243, v156, v156
	v_pk_add_f32 v[244:245], v[244:245], v[246:247]
	v_pk_fma_f32 v[246:247], v[4:5], v[4:5], v[210:211] op_sel_hi:[1,1,0]
	v_mul_f32_e32 v210, v7, v7
	v_mul_f32_e32 v252, v157, v157
	v_mul_f32_e32 v253, v158, v158
	v_mul_f32_e32 v230, v159, v159
	v_pk_fma_f32 v[248:249], v[6:7], v[6:7], v[210:211] op_sel_hi:[1,1,0]
	v_mov_b32_e32 v247, v243
	v_mov_b32_e32 v249, v252
	v_mov_b32_e32 v225, v253
	v_mov_b32_e32 v223, v230
	v_pk_add_f32 v[246:247], v[246:247], v[248:249]
	v_pk_add_f32 v[222:223], v[224:225], v[222:223]
	s_nop 0
	v_pk_add_f32 v[222:223], v[246:247], v[222:223]
	v_mov_b32_e32 v246, v160
	v_pk_add_f32 v[222:223], v[244:245], v[222:223]
	v_mov_b32_e32 v244, v226
	v_mov_b32_e32 v226, v227
	v_mov_b32_e32 v227, v209
	v_mov_b32_e32 v160, v161
	v_mov_b32_e32 v161, v209
	v_mov_b32_e32 v245, v208
	v_mov_b32_e32 v247, v208
	v_pk_mul_f32 v[160:161], v[226:227], v[160:161]
	v_mov_b32_e32 v226, v220
	v_pk_fma_f32 v[160:161], v[244:245], v[246:247], v[160:161]
	v_mov_b32_e32 v244, v162
	v_mov_b32_e32 v220, v221
	v_mov_b32_e32 v221, v207
	v_mov_b32_e32 v162, v163
	v_mov_b32_e32 v163, v207
	v_mov_b32_e32 v227, v206
	v_mov_b32_e32 v245, v206
	v_pk_mul_f32 v[162:163], v[220:221], v[162:163]
	ds_bpermute_b32 v224, v240, v222
	v_pk_fma_f32 v[162:163], v[226:227], v[244:245], v[162:163]
	ds_bpermute_b32 v225, v240, v223
	v_pk_add_f32 v[160:161], v[160:161], v[162:163]
	v_mul_f32_e32 v162, v209, v149
	v_pk_fma_f32 v[148:149], v[208:209], v[148:149], v[162:163] op_sel_hi:[1,1,0]
	v_mul_f32_e32 v162, v207, v151
	v_pk_fma_f32 v[150:151], v[206:207], v[150:151], v[162:163] op_sel_hi:[1,1,0]
	v_mov_b32_e32 v149, v242
	v_mov_b32_e32 v151, v33
	v_pk_add_f32 v[148:149], v[148:149], v[150:151]
	v_pk_mov_b32 v[150:151], v[152:153], v[214:215] op_sel:[1,0]
	v_mov_b32_e32 v153, v215
	v_pk_mul_f32 v[152:153], v[214:215], v[152:153]
	v_mov_b32_e32 v33, v211
	v_pk_fma_f32 v[150:151], v[214:215], v[150:151], v[152:153] op_sel:[1,0,0] op_sel_hi:[0,1,1]
	v_pk_mov_b32 v[152:153], v[154:155], v[212:213] op_sel:[1,0]
	v_mov_b32_e32 v155, v213
	v_pk_mul_f32 v[154:155], v[212:213], v[154:155]
	v_pk_add_f32 v[148:149], v[148:149], v[32:33]
	v_pk_fma_f32 v[152:153], v[212:213], v[152:153], v[154:155] op_sel:[1,0,0] op_sel_hi:[0,1,1]
	v_pk_add_f32 v[148:149], v[160:161], v[148:149]
	v_pk_add_f32 v[150:151], v[150:151], v[152:153]
	s_waitcnt lgkmcnt(0)
	v_pk_add_f32 v[222:223], v[222:223], v[224:225]
	v_pk_add_f32 v[148:149], v[148:149], v[150:151]
	v_pk_mov_b32 v[150:151], v[156:157], v[218:219] op_sel:[1,0]
	v_mov_b32_e32 v157, v219
	v_pk_mul_f32 v[152:153], v[218:219], v[156:157]
	ds_bpermute_b32 v224, v239, v222
	v_pk_fma_f32 v[150:151], v[218:219], v[150:151], v[152:153] op_sel:[1,0,0] op_sel_hi:[0,1,1]
	v_pk_mov_b32 v[152:153], v[158:159], v[216:217] op_sel:[1,0]
	v_mov_b32_e32 v159, v217
	v_pk_mul_f32 v[154:155], v[216:217], v[158:159]
	ds_bpermute_b32 v225, v239, v223
	v_pk_fma_f32 v[152:153], v[216:217], v[152:153], v[154:155] op_sel:[1,0,0] op_sel_hi:[0,1,1]
	v_pk_add_f32 v[150:151], v[150:151], v[152:153]
	s_nop 0
	v_pk_add_f32 v[148:149], v[148:149], v[150:151]
	ds_bpermute_b32 v150, v240, v148
	ds_bpermute_b32 v151, v240, v149
	s_waitcnt lgkmcnt(0)
	v_pk_add_f32 v[148:149], v[148:149], v[150:151]
	ds_bpermute_b32 v150, v239, v148
	ds_bpermute_b32 v151, v239, v149
	s_and_saveexec_b64 s[6:7], vcc
	s_cbranch_execz .LBB0_847
	v_lshl_add_u32 v33, v241, 6, s19
	s_waitcnt lgkmcnt(0)
	v_pk_add_f32 v[150:151], v[148:149], v[150:151]
	v_pk_add_f32 v[148:149], v[222:223], v[224:225]
	ds_write_b128 v33, v[148:151]

;     __device__ __forceinline__ void fused(f32x4 (&acc)[2][2][4][2], const Unit& u, int wr, int wc, int fr, int fq, PG8_LAS unsigned char* lds, int wid, int lane) const {
;     ...
;         const int col0 = u.pn * BM + wc * 32 + 4 * fq;
;         f32x4 gv[2][2];
; #pragma unroll
;         for (int bj = 0; bj < 2; ++bj)
; #pragma unroll
;             for (int n = 0; n < 2; ++n) gv[bj][n] = *(const f32x4*)(g1 + col0 + bj * HALF + n * 16);
; #pragma unroll
;         for (int ai = 0; ai < 2; ++ai)
; #pragma unroll
;             for (int m = 0; m < 4; ++m) { const int r = ai * HALF + wr * 64 + m * 16 + fr; const size_t off = (size_t)(u.pm * BM + r) * 1024 + col0;
;                 float s0 = 0.f, s1 = 0.f, s2 = 0.f, s3 = 0.f;
; #pragma unroll
;                 for (int bj = 0; bj < 2; ++bj)
; #pragma unroll
;                     for (int n = 0; n < 2; ++n) { const f32x4 bs = *(const f32x4*)(base + off + bj * HALF + n * 16), a = acc[ai][bj][m][n], ag = a * gv[bj][n];
;                         s0 += (a[0] * a[0] + a[1] * a[1]) + (a[2] * a[2] + a[3] * a[3]); s1 += (bs[0] * bs[0] + bs[1] * bs[1]) + (bs[2] * bs[2] + bs[3] * bs[3]);
;                         s2 += (bs[0] * ag[0] + bs[1] * ag[1]) + (bs[2] * ag[2] + bs[3] * ag[3]); s3 += (ag[0] * ag[0] + ag[1] * ag[1]) + (ag[2] * ag[2] + ag[3] * ag[3]); }
.LBB0_1088:
	s_ashr_i32 s17, s16, 31
	s_lshl_b64 s[4:5], s[16:17], 14
	s_add_u32 s42, s26, s4
	s_addc_u32 s43, s27, s5
	s_lshl_b32 s4, s29, 5
	s_lshl_b32 s5, s28, 8
	s_or_b32 s4, s5, s4
	v_lshrrev_b32_e32 v33, 2, v195
	v_and_or_b32 v34, v33, 12, s4
	v_ashrrev_i32_e32 v35, 31, v34
	v_lshlrev_b64 v[148:149], 2, v[34:35]
	v_lshl_add_u64 v[132:133], s[42:43], 0, v[148:149]
	s_mov_b64 s[4:5], 0x3000
	v_lshl_add_u64 v[134:135], v[132:133], 0, s[4:5]
	v_add_co_u32_e32 v132, vcc, s2, v132
	v_and_b32_e32 v150, 64, v233
	s_nop 0
	v_addc_co_u32_e32 v133, vcc, 0, v133, vcc
	v_xor_b32_e32 v33, 16, v233
	v_add_u32_e32 v150, 64, v150
	s_lshl_b32 s17, s90, 8
	v_cmp_lt_i32_e32 vcc, v33, v150
	v_add_u32_e32 v166, s17, v237
	v_ashrrev_i32_e32 v167, 31, v166
	v_cndmask_b32_e32 v33, v233, v33, vcc
	v_lshlrev_b32_e32 v240, 2, v33
	v_xor_b32_e32 v33, 32, v233
	v_cmp_lt_i32_e32 vcc, v33, v150
	v_lshlrev_b64 v[150:151], 12, v[166:167]
	v_lshl_add_u64 v[150:151], s[30:31], 0, v[150:151]
	v_lshl_add_u64 v[164:165], v[150:151], 0, v[148:149]
	s_barrier
	global_load_dwordx4 v[144:147], v[132:133], off
	global_load_dwordx4 v[140:143], v[134:135], off offset:64
	global_load_dwordx4 v[136:139], v[134:135], off offset:512
	s_nop 0
	global_load_dwordx4 v[132:135], v[134:135], off offset:576
	v_pk_mul_f32 v[152:153], v[130:131], v[130:131]
	v_readfirstlane_b32 s72, v228
	s_nop 3
	s_lshr_b32 s72, s72, 6
	s_mul_i32 s72, s72, 0x3000
	s_add_i32 s72, s72, 0x5000
	s_mov_b64 s[98:99], 0x0
	v_lshl_add_u64 v[160:161], v[164:165], 0, s[98:99]
	s_add_i32 m0, s72, 0x0
	s_nop 0
	global_load_lds_dwordx4 v[160:161], off
	s_mov_b64 s[98:99], 0x40
	v_lshl_add_u64 v[160:161], v[164:165], 0, s[98:99]
	s_add_i32 m0, s72, 0x400
	s_nop 0
	global_load_lds_dwordx4 v[160:161], off
	s_mov_b64 s[98:99], 0x200
	v_lshl_add_u64 v[160:161], v[164:165], 0, s[98:99]
	s_add_i32 m0, s72, 0x800
	s_nop 0
	global_load_lds_dwordx4 v[160:161], off
	s_mov_b64 s[98:99], 0x240
	v_lshl_add_u64 v[160:161], v[164:165], 0, s[98:99]
	s_add_i32 m0, s72, 0xc00
	s_nop 0
	global_load_lds_dwordx4 v[160:161], off
	s_mov_b64 s[98:99], 0x10000
	v_lshl_add_u64 v[160:161], v[164:165], 0, s[98:99]
	s_add_i32 m0, s72, 0x1000
	s_nop 0
	global_load_lds_dwordx4 v[160:161], off
	s_mov_b64 s[98:99], 0x10040
	v_lshl_add_u64 v[160:161], v[164:165], 0, s[98:99]
	s_add_i32 m0, s72, 0x1400
	s_nop 0
	global_load_lds_dwordx4 v[160:161], off
	s_mov_b64 s[98:99], 0x10200
	v_lshl_add_u64 v[160:161], v[164:165], 0, s[98:99]
	s_add_i32 m0, s72, 0x1800
	s_nop 0
	global_load_lds_dwordx4 v[160:161], off
	s_mov_b64 s[98:99], 0x10240
	v_lshl_add_u64 v[160:161], v[164:165], 0, s[98:99]
	s_add_i32 m0, s72, 0x1c00
	s_nop 0
	global_load_lds_dwordx4 v[160:161], off
	s_mov_b64 s[98:99], 0x20000
	v_lshl_add_u64 v[160:161], v[164:165], 0, s[98:99]
	s_add_i32 m0, s72, 0x2000
	s_nop 0
	global_load_lds_dwordx4 v[160:161], off
	s_mov_b64 s[98:99], 0x20040
	v_lshl_add_u64 v[160:161], v[164:165], 0, s[98:99]
	s_add_i32 m0, s72, 0x2400
	s_nop 0
	global_load_lds_dwordx4 v[160:161], off
	s_mov_b64 s[98:99], 0x20200
	v_lshl_add_u64 v[160:161], v[164:165], 0, s[98:99]
	s_add_i32 m0, s72, 0x2800
	s_nop 0
	global_load_lds_dwordx4 v[160:161], off
	s_mov_b64 s[98:99], 0x20240
	v_lshl_add_u64 v[160:161], v[164:165], 0, s[98:99]
	s_add_i32 m0, s72, 0x2c00
	s_nop 0
	global_load_lds_dwordx4 v[160:161], off
	s_add_i32 s98, s72, 0x0
	s_waitcnt vmcnt(8)
	v_and_b32_e32 v148, 63, v228
	v_lshl_add_u32 v148, v148, 4, s98
	ds_read_b128 v[148:151], v148
	v_pk_mul_f32 v[154:155], v[128:129], v[128:129]
	v_pk_mul_f32 v[158:159], v[124:125], v[124:125]
	v_pk_mov_b32 v[156:157], v[154:155], v[152:153] op_sel:[1,0]
	v_mov_b32_e32 v155, v153
	v_pk_add_f32 v[172:173], v[156:157], v[154:155]
	v_cndmask_b32_e32 v33, v233, v33, vcc
	v_pk_add_f32 v[172:173], v[172:173], v[172:173] op_sel:[0,1] op_sel_hi:[1,0]
	v_lshlrev_b32_e32 v239, 2, v33
	v_and_b32_e32 v238, 63, v195
	s_lshl_b32 s4, s29, 4
	v_cmp_gt_u32_e32 vcc, 16, v238
	s_add_i32 s29, s4, 0
	s_waitcnt lgkmcnt(0)
	v_pk_mul_f32 v[170:171], v[128:129], v[144:145]
	v_pk_mul_f32 v[176:177], v[126:127], v[142:143]
	v_pk_mul_f32 v[178:179], v[124:125], v[140:141]
	v_pk_mul_f32 v[168:169], v[130:131], v[146:147]
	v_mul_f32_e32 v193, v178, v178
	v_pk_mul_f32 v[152:153], v[150:151], v[150:151]
	v_pk_mul_f32 v[154:155], v[148:149], v[148:149]
	v_mul_f32_e32 v33, v179, v179
	v_pk_mov_b32 v[156:157], v[154:155], v[152:153] op_sel:[1,0]
	v_mov_b32_e32 v155, v153
	v_pk_add_f32 v[152:153], v[156:157], v[154:155]
	v_pk_mul_f32 v[156:157], v[126:127], v[126:127]
	v_pk_add_f32 v[190:191], v[152:153], v[152:153] op_sel_hi:[0,1]
	v_and_b32_e32 v152, 63, v228
	v_lshl_add_u32 v152, v152, 4, s98
	ds_read_b128 v[152:155], v152 offset:1024
	v_pk_mov_b32 v[160:161], v[158:159], v[156:157] op_sel:[1,0]
	v_mov_b32_e32 v159, v157
	v_pk_add_f32 v[180:181], v[160:161], v[158:159]
	v_mul_f32_e32 v190, v116, v116
	v_pk_add_f32 v[180:181], v[180:181], v[180:181] op_sel:[0,1] op_sel_hi:[1,0]
	v_pk_mul_f32 v[184:185], v[120:121], v[136:137]
	v_pk_mul_f32 v[182:183], v[122:123], v[138:139]
	v_pk_mul_f32 v[188:189], v[116:117], v[132:133]
	v_pk_mul_f32 v[186:187], v[118:119], v[134:135]
	s_waitcnt lgkmcnt(0)
	v_pk_mul_f32 v[156:157], v[154:155], v[154:155]
	v_pk_mul_f32 v[158:159], v[152:153], v[152:153]
	s_nop 0
	v_pk_mov_b32 v[160:161], v[158:159], v[156:157] op_sel:[1,0]
	v_mov_b32_e32 v159, v157
	v_pk_add_f32 v[156:157], v[160:161], v[158:159]
	s_nop 0
	v_pk_add_f32 v[204:205], v[156:157], v[156:157] op_sel_hi:[0,1]
	v_mul_f32_e32 v156, v176, v176
	v_pk_fma_f32 v[174:175], v[176:177], v[176:177], v[156:157] op_sel_hi:[1,1,0]
	v_and_b32_e32 v156, 63, v228
	v_lshl_add_u32 v156, v156, 4, s98
	ds_read_b128 v[156:159], v156 offset:2048
	v_mul_f32_e32 v204, v117, v117
	v_pk_add_f32 v[190:191], v[190:191], v[204:205]
	v_mul_f32_e32 v174, v121, v121
	s_waitcnt lgkmcnt(0)
;     __device__ __forceinline__ void fused(f32x4 (&acc)[2][2][4][2], const Unit& u, int wr, int wc, int fr, int fq, PG8_LAS unsigned char* lds, int wid, int lane) const {
;     ...
;                     for (int n = 0; n < 2; ++n) { const f32x4 bs = *(const f32x4*)(base + off + bj * HALF + n * 16), a = acc[ai][bj][m][n], ag = a * gv[bj][n];
;                         s0 += (a[0] * a[0] + a[1] * a[1]) + (a[2] * a[2] + a[3] * a[3]); s1 += (bs[0] * bs[0] + bs[1] * bs[1]) + (bs[2] * bs[2] + bs[3] * bs[3]);
;                         s2 += (bs[0] * ag[0] + bs[1] * ag[1]) + (bs[2] * ag[2] + bs[3] * ag[3]); s3 += (ag[0] * ag[0] + ag[1] * ag[1]) + (ag[2] * ag[2] + ag[3] * ag[3]); }
;                 s0 += __shfl_xor(s0, 16); s0 += __shfl_xor(s0, 32); s1 += __shfl_xor(s1, 16); s1 += __shfl_xor(s1, 32);
;                 s2 += __shfl_xor(s2, 16); s2 += __shfl_xor(s2, 32); s3 += __shfl_xor(s3, 16); s3 += __shfl_xor(s3, 32);
;                 if (fq == 0) P[r * 4 + wc] = (f32x4){s0, s1, s2, s3};
	v_mul_f32_e32 v160, v156, v156
	v_pk_fma_f32 v[206:207], v[156:157], v[156:157], v[160:161] op_sel_hi:[1,1,0]
	v_mul_f32_e32 v160, v158, v158
	v_pk_fma_f32 v[208:209], v[158:159], v[158:159], v[160:161] op_sel_hi:[1,1,0]
	v_and_b32_e32 v160, 63, v228
	v_lshl_add_u32 v160, v160, 4, s98
	ds_read_b128 v[160:163], v160 offset:3072
	v_mul_f32_e32 v206, v118, v118
	v_mul_f32_e32 v208, v119, v119
	v_pk_add_f32 v[204:205], v[206:207], v[208:209]
	s_waitcnt lgkmcnt(0)
	v_mul_f32_e32 v210, v160, v160
	v_pk_add_f32 v[190:191], v[190:191], v[204:205]
	v_pk_fma_f32 v[204:205], v[120:121], v[120:121], v[174:175] op_sel_hi:[1,1,0]
	v_mul_f32_e32 v174, v123, v123
	v_mul_f32_e32 v211, v161, v161
	v_mul_f32_e32 v212, v162, v162
	v_mul_f32_e32 v213, v163, v163
	v_pk_fma_f32 v[206:207], v[122:123], v[122:123], v[174:175] op_sel_hi:[1,1,0]
	v_mov_b32_e32 v205, v210
	v_mov_b32_e32 v207, v211
	v_mov_b32_e32 v181, v212
	v_mov_b32_e32 v173, v213
	v_pk_add_f32 v[204:205], v[204:205], v[206:207]
	v_pk_add_f32 v[172:173], v[180:181], v[172:173]
	s_nop 0
	v_pk_add_f32 v[172:173], v[204:205], v[172:173]
	v_mov_b32_e32 v204, v152
	v_pk_add_f32 v[172:173], v[190:191], v[172:173]
	v_mov_b32_e32 v190, v178
	v_mov_b32_e32 v178, v179
	v_mov_b32_e32 v179, v171
	v_mov_b32_e32 v152, v153
	v_mov_b32_e32 v153, v171
	v_mov_b32_e32 v191, v170
	v_mov_b32_e32 v205, v170
	v_pk_mul_f32 v[152:153], v[178:179], v[152:153]
	v_mov_b32_e32 v178, v176
	v_pk_fma_f32 v[152:153], v[190:191], v[204:205], v[152:153]
	v_mov_b32_e32 v190, v154
	v_mov_b32_e32 v176, v177
	v_mov_b32_e32 v177, v169
	v_mov_b32_e32 v154, v155
	v_mov_b32_e32 v155, v169
	v_mov_b32_e32 v179, v168
	v_mov_b32_e32 v191, v168
	v_pk_mul_f32 v[154:155], v[176:177], v[154:155]
	ds_bpermute_b32 v180, v240, v172
	v_pk_fma_f32 v[154:155], v[178:179], v[190:191], v[154:155]
	ds_bpermute_b32 v181, v240, v173
	v_pk_add_f32 v[152:153], v[152:153], v[154:155]
	v_mul_f32_e32 v154, v171, v149
	v_pk_fma_f32 v[148:149], v[170:171], v[148:149], v[154:155] op_sel_hi:[1,1,0]
	v_mul_f32_e32 v154, v169, v151
	v_pk_fma_f32 v[150:151], v[168:169], v[150:151], v[154:155] op_sel_hi:[1,1,0]
	v_mov_b32_e32 v149, v193
	v_mov_b32_e32 v151, v33
	v_pk_add_f32 v[148:149], v[148:149], v[150:151]
	v_mov_b32_e32 v33, v175
	v_pk_add_f32 v[148:149], v[148:149], v[32:33]
	v_pk_mov_b32 v[150:151], v[156:157], v[184:185] op_sel:[1,0]
	v_mov_b32_e32 v157, v185
	v_pk_add_f32 v[148:149], v[152:153], v[148:149]
	v_pk_mul_f32 v[152:153], v[184:185], v[156:157]
	s_waitcnt lgkmcnt(0)
	v_pk_add_f32 v[172:173], v[172:173], v[180:181]
	v_pk_fma_f32 v[150:151], v[184:185], v[150:151], v[152:153] op_sel:[1,0,0] op_sel_hi:[0,1,1]
	v_pk_mov_b32 v[152:153], v[158:159], v[182:183] op_sel:[1,0]
	v_mov_b32_e32 v159, v183
	v_pk_mul_f32 v[154:155], v[182:183], v[158:159]
	ds_bpermute_b32 v180, v239, v172
	v_pk_fma_f32 v[152:153], v[182:183], v[152:153], v[154:155] op_sel:[1,0,0] op_sel_hi:[0,1,1]
	v_pk_add_f32 v[150:151], v[150:151], v[152:153]
	ds_bpermute_b32 v181, v239, v173
	v_pk_add_f32 v[148:149], v[148:149], v[150:151]
	v_pk_mov_b32 v[150:151], v[160:161], v[188:189] op_sel:[1,0]
	v_mov_b32_e32 v161, v189
	v_pk_mul_f32 v[152:153], v[188:189], v[160:161]
	s_nop 0
	v_pk_fma_f32 v[150:151], v[188:189], v[150:151], v[152:153] op_sel:[1,0,0] op_sel_hi:[0,1,1]
	v_pk_mov_b32 v[152:153], v[162:163], v[186:187] op_sel:[1,0]
	v_mov_b32_e32 v163, v187
	v_pk_mul_f32 v[154:155], v[186:187], v[162:163]
	s_nop 0
	v_pk_fma_f32 v[152:153], v[186:187], v[152:153], v[154:155] op_sel:[1,0,0] op_sel_hi:[0,1,1]
	v_pk_add_f32 v[150:151], v[150:151], v[152:153]
	s_nop 0
	v_pk_add_f32 v[148:149], v[148:149], v[150:151]
	ds_bpermute_b32 v150, v240, v148
	ds_bpermute_b32 v151, v240, v149
	s_waitcnt lgkmcnt(0)
	v_pk_add_f32 v[148:149], v[148:149], v[150:151]
	ds_bpermute_b32 v150, v239, v148
	ds_bpermute_b32 v151, v239, v149
	s_and_saveexec_b64 s[6:7], vcc
	v_readlane_b32 s56, v255, 4
	v_readlane_b32 s58, v255, 6
	v_readlane_b32 s52, v255, 8
	v_readlane_b32 s57, v255, 5
	v_readlane_b32 s59, v255, 7
	v_readlane_b32 s53, v255, 9
	v_readlane_b32 s55, v255, 10
	s_cbranch_execz .LBB0_1090
	v_add_u32_e32 v33, s29, v192
	s_waitcnt lgkmcnt(0)
	v_pk_add_f32 v[150:151], v[148:149], v[150:151]
	v_pk_add_f32 v[148:149], v[172:173], v[180:181]
	ds_write_b128 v33, v[148:151]
;     __device__ __forceinline__ void fused(f32x4 (&acc)[2][2][4][2], const Unit& u, int wr, int wc, int fr, int fq, PG8_LAS unsigned char* lds, int wid, int lane) const {
;     ...
;             for (int m = 0; m < 4; ++m) { const int r = ai * HALF + wr * 64 + m * 16 + fr; const size_t off = (size_t)(u.pm * BM + r) * 1024 + col0;
;                 float s0 = 0.f, s1 = 0.f, s2 = 0.f, s3 = 0.f;
; #pragma unroll
;                 for (int bj = 0; bj < 2; ++bj)
; #pragma unroll
;                     for (int n = 0; n < 2; ++n) { const f32x4 bs = *(const f32x4*)(base + off + bj * HALF + n * 16), a = acc[ai][bj][m][n], ag = a * gv[bj][n];
;                         s0 += (a[0] * a[0] + a[1] * a[1]) + (a[2] * a[2] + a[3] * a[3]); s1 += (bs[0] * bs[0] + bs[1] * bs[1]) + (bs[2] * bs[2] + bs[3] * bs[3]);
;                         s2 += (bs[0] * ag[0] + bs[1] * ag[1]) + (bs[2] * ag[2] + bs[3] * ag[3]); s3 += (ag[0] * ag[0] + ag[1] * ag[1]) + (ag[2] * ag[2] + ag[3] * ag[3]); }
;                 s0 += __shfl_xor(s0, 16); s0 += __shfl_xor(s0, 32); s1 += __shfl_xor(s1, 16); s1 += __shfl_xor(s1, 32);
;                 s2 += __shfl_xor(s2, 16); s2 += __shfl_xor(s2, 32); s3 += __shfl_xor(s3, 16); s3 += __shfl_xor(s3, 32);
;                 if (fq == 0) P[r * 4 + wc] = (f32x4){s0, s1, s2, s3};
.LBB0_1090:
	s_or_b64 exec, exec, s[6:7]
	s_mov_b64 s[98:99], 0x30000
	v_lshl_add_u64 v[160:161], v[164:165], 0, s[98:99]
	s_add_i32 m0, s72, 0x0
	s_nop 0
	global_load_lds_dwordx4 v[160:161], off
	s_mov_b64 s[98:99], 0x30040
	v_lshl_add_u64 v[160:161], v[164:165], 0, s[98:99]
	s_add_i32 m0, s72, 0x400
	s_nop 0
	global_load_lds_dwordx4 v[160:161], off
	s_mov_b64 s[98:99], 0x30200
	v_lshl_add_u64 v[160:161], v[164:165], 0, s[98:99]
	s_add_i32 m0, s72, 0x800
	s_nop 0
	global_load_lds_dwordx4 v[160:161], off
	s_mov_b64 s[98:99], 0x30240
	v_lshl_add_u64 v[160:161], v[164:165], 0, s[98:99]
	s_add_i32 m0, s72, 0xc00
	s_nop 0
	global_load_lds_dwordx4 v[160:161], off
	v_or_b32_e32 v204, 16, v237
	v_add_u32_e32 v170, s17, v204
	v_ashrrev_i32_e32 v171, 31, v170
	v_lshlrev_b64 v[148:149], 12, v[170:171]
	v_lshl_add_u64 v[148:149], s[30:31], 0, v[148:149]
	v_lshl_add_u64 v[168:169], v[34:35], 2, v[148:149]
	s_waitcnt lgkmcnt(0)
	s_add_i32 s98, s72, 0x1000
	s_waitcnt vmcnt(8)
	v_and_b32_e32 v148, 63, v228
	v_lshl_add_u32 v148, v148, 4, s98
	ds_read_b128 v[148:151], v148
	v_and_b32_e32 v160, 63, v228
	v_lshl_add_u32 v160, v160, 4, s98
	ds_read_b128 v[160:163], v160 offset:1024
	v_pk_mul_f32 v[152:153], v[114:115], v[114:115]
	v_pk_mul_f32 v[154:155], v[112:113], v[112:113]
	v_pk_mul_f32 v[186:187], v[110:111], v[142:143]
	v_pk_mov_b32 v[156:157], v[154:155], v[152:153] op_sel:[1,0]
	v_mov_b32_e32 v155, v153
	v_pk_add_f32 v[188:189], v[156:157], v[154:155]
	v_pk_mul_f32 v[174:175], v[112:113], v[144:145]
	v_pk_add_f32 v[188:189], v[188:189], v[188:189] op_sel:[0,1] op_sel_hi:[1,0]
	v_pk_mul_f32 v[192:193], v[108:109], v[140:141]
	v_pk_mul_f32 v[172:173], v[114:115], v[146:147]
	v_mul_f32_e32 v205, v192, v192
	v_mul_f32_e32 v33, v193, v193
	v_pk_mul_f32 v[180:181], v[104:105], v[136:137]
	v_pk_mul_f32 v[178:179], v[106:107], v[138:139]
	v_pk_mul_f32 v[184:185], v[100:101], v[132:133]
	v_pk_mul_f32 v[182:183], v[102:103], v[134:135]
	s_waitcnt lgkmcnt(1)
	v_pk_mul_f32 v[152:153], v[150:151], v[150:151]
	v_pk_mul_f32 v[154:155], v[148:149], v[148:149]
	s_nop 0
	v_pk_mov_b32 v[156:157], v[154:155], v[152:153] op_sel:[1,0]
	v_mov_b32_e32 v155, v153
	v_pk_add_f32 v[152:153], v[156:157], v[154:155]
	v_pk_mul_f32 v[154:155], v[108:109], v[108:109]
	v_pk_add_f32 v[206:207], v[152:153], v[152:153] op_sel_hi:[0,1]
	v_pk_mul_f32 v[152:153], v[110:111], v[110:111]
	v_mul_f32_e32 v206, v100, v100
	v_pk_mov_b32 v[156:157], v[154:155], v[152:153] op_sel:[1,0]
	v_mov_b32_e32 v155, v153
	v_pk_add_f32 v[190:191], v[156:157], v[154:155]
	s_waitcnt lgkmcnt(0)
	v_pk_mul_f32 v[152:153], v[162:163], v[162:163]
	v_pk_mul_f32 v[154:155], v[160:161], v[160:161]
	v_pk_add_f32 v[190:191], v[190:191], v[190:191] op_sel:[0,1] op_sel_hi:[1,0]
	v_pk_mov_b32 v[156:157], v[154:155], v[152:153] op_sel:[1,0]
	v_mov_b32_e32 v155, v153
	v_pk_add_f32 v[152:153], v[156:157], v[154:155]
	s_nop 0
	v_pk_add_f32 v[208:209], v[152:153], v[152:153] op_sel_hi:[0,1]
	v_mul_f32_e32 v152, v186, v186
	v_pk_fma_f32 v[176:177], v[186:187], v[186:187], v[152:153] op_sel_hi:[1,1,0]
	v_and_b32_e32 v152, 63, v228
	v_lshl_add_u32 v152, v152, 4, s98
	ds_read_b128 v[152:155], v152 offset:2048
	v_mul_f32_e32 v208, v101, v101
	v_pk_add_f32 v[206:207], v[206:207], v[208:209]
	v_mul_f32_e32 v176, v105, v105
	s_waitcnt lgkmcnt(0)
	v_mul_f32_e32 v156, v152, v152
	v_pk_fma_f32 v[210:211], v[152:153], v[152:153], v[156:157] op_sel_hi:[1,1,0]
	v_mul_f32_e32 v156, v154, v154
	v_pk_fma_f32 v[212:213], v[154:155], v[154:155], v[156:157] op_sel_hi:[1,1,0]
	v_and_b32_e32 v156, 63, v228
	v_lshl_add_u32 v156, v156, 4, s98
	ds_read_b128 v[156:159], v156 offset:3072
	v_mul_f32_e32 v210, v102, v102
	v_mul_f32_e32 v212, v103, v103
	v_pk_add_f32 v[208:209], v[210:211], v[212:213]
	s_waitcnt lgkmcnt(0)
	v_mul_f32_e32 v214, v156, v156
	v_pk_add_f32 v[206:207], v[206:207], v[208:209]
	v_pk_fma_f32 v[208:209], v[104:105], v[104:105], v[176:177] op_sel_hi:[1,1,0]
	v_mul_f32_e32 v176, v107, v107
	v_mul_f32_e32 v215, v157, v157
	v_mul_f32_e32 v216, v158, v158
	v_mul_f32_e32 v217, v159, v159
	v_pk_fma_f32 v[210:211], v[106:107], v[106:107], v[176:177] op_sel_hi:[1,1,0]
	v_mov_b32_e32 v209, v214
	v_mov_b32_e32 v211, v215
	v_mov_b32_e32 v191, v216
	v_mov_b32_e32 v189, v217
	v_pk_add_f32 v[208:209], v[208:209], v[210:211]
	v_pk_add_f32 v[188:189], v[190:191], v[188:189]
	s_nop 0
	v_pk_add_f32 v[188:189], v[208:209], v[188:189]
	v_mov_b32_e32 v208, v160
	v_pk_add_f32 v[188:189], v[206:207], v[188:189]
	v_mov_b32_e32 v206, v192
	v_mov_b32_e32 v192, v193
	v_mov_b32_e32 v193, v175
	v_mov_b32_e32 v160, v161
	v_mov_b32_e32 v161, v175
	v_mov_b32_e32 v207, v174
	v_mov_b32_e32 v209, v174
	v_pk_mul_f32 v[160:161], v[192:193], v[160:161]
	v_mov_b32_e32 v192, v186
	v_pk_fma_f32 v[160:161], v[206:207], v[208:209], v[160:161]
	v_mov_b32_e32 v206, v162
	v_mov_b32_e32 v186, v187
	v_mov_b32_e32 v187, v173
	v_mov_b32_e32 v162, v163
	v_mov_b32_e32 v163, v173
	v_mov_b32_e32 v193, v172
	v_mov_b32_e32 v207, v172
	v_pk_mul_f32 v[162:163], v[186:187], v[162:163]
	ds_bpermute_b32 v190, v240, v188
	v_pk_fma_f32 v[162:163], v[192:193], v[206:207], v[162:163]
	ds_bpermute_b32 v191, v240, v189
	v_pk_add_f32 v[160:161], v[160:161], v[162:163]
	v_mul_f32_e32 v162, v175, v149
	v_pk_fma_f32 v[148:149], v[174:175], v[148:149], v[162:163] op_sel_hi:[1,1,0]
	v_mul_f32_e32 v162, v173, v151
	v_pk_fma_f32 v[150:151], v[172:173], v[150:151], v[162:163] op_sel_hi:[1,1,0]
	v_mov_b32_e32 v149, v205
	v_mov_b32_e32 v151, v33
	v_pk_add_f32 v[148:149], v[148:149], v[150:151]
	v_pk_mov_b32 v[150:151], v[152:153], v[180:181] op_sel:[1,0]
	v_mov_b32_e32 v153, v181
	v_pk_mul_f32 v[152:153], v[180:181], v[152:153]
	v_mov_b32_e32 v33, v177
	v_pk_fma_f32 v[150:151], v[180:181], v[150:151], v[152:153] op_sel:[1,0,0] op_sel_hi:[0,1,1]
	v_pk_mov_b32 v[152:153], v[154:155], v[178:179] op_sel:[1,0]
	v_mov_b32_e32 v155, v179
	v_pk_mul_f32 v[154:155], v[178:179], v[154:155]
	v_pk_add_f32 v[148:149], v[148:149], v[32:33]
	v_pk_fma_f32 v[152:153], v[178:179], v[152:153], v[154:155] op_sel:[1,0,0] op_sel_hi:[0,1,1]
	v_pk_add_f32 v[148:149], v[160:161], v[148:149]
	v_pk_add_f32 v[150:151], v[150:151], v[152:153]
	s_waitcnt lgkmcnt(0)
;     __device__ __forceinline__ void fused(f32x4 (&acc)[2][2][4][2], const Unit& u, int wr, int wc, int fr, int fq, PG8_LAS unsigned char* lds, int wid, int lane) const {
;     ...
;                     for (int n = 0; n < 2; ++n) { const f32x4 bs = *(const f32x4*)(base + off + bj * HALF + n * 16), a = acc[ai][bj][m][n], ag = a * gv[bj][n];
;                         s0 += (a[0] * a[0] + a[1] * a[1]) + (a[2] * a[2] + a[3] * a[3]); s1 += (bs[0] * bs[0] + bs[1] * bs[1]) + (bs[2] * bs[2] + bs[3] * bs[3]);
;                         s2 += (bs[0] * ag[0] + bs[1] * ag[1]) + (bs[2] * ag[2] + bs[3] * ag[3]); s3 += (ag[0] * ag[0] + ag[1] * ag[1]) + (ag[2] * ag[2] + ag[3] * ag[3]); }
;                 s0 += __shfl_xor(s0, 16); s0 += __shfl_xor(s0, 32); s1 += __shfl_xor(s1, 16); s1 += __shfl_xor(s1, 32);
;                 s2 += __shfl_xor(s2, 16); s2 += __shfl_xor(s2, 32); s3 += __shfl_xor(s3, 16); s3 += __shfl_xor(s3, 32);
;                 if (fq == 0) P[r * 4 + wc] = (f32x4){s0, s1, s2, s3};
	v_pk_add_f32 v[188:189], v[188:189], v[190:191]
	v_pk_add_f32 v[148:149], v[148:149], v[150:151]
	v_pk_mov_b32 v[150:151], v[156:157], v[184:185] op_sel:[1,0]
	v_mov_b32_e32 v157, v185
	v_pk_mul_f32 v[152:153], v[184:185], v[156:157]
	ds_bpermute_b32 v190, v239, v188
	v_pk_fma_f32 v[150:151], v[184:185], v[150:151], v[152:153] op_sel:[1,0,0] op_sel_hi:[0,1,1]
	v_pk_mov_b32 v[152:153], v[158:159], v[182:183] op_sel:[1,0]
	v_mov_b32_e32 v159, v183
	v_pk_mul_f32 v[154:155], v[182:183], v[158:159]
	ds_bpermute_b32 v191, v239, v189
	v_pk_fma_f32 v[152:153], v[182:183], v[152:153], v[154:155] op_sel:[1,0,0] op_sel_hi:[0,1,1]
	v_pk_add_f32 v[150:151], v[150:151], v[152:153]
	s_nop 0
	v_pk_add_f32 v[148:149], v[148:149], v[150:151]
	ds_bpermute_b32 v150, v240, v148
	ds_bpermute_b32 v151, v240, v149
	s_waitcnt lgkmcnt(0)
	v_pk_add_f32 v[148:149], v[148:149], v[150:151]
	ds_bpermute_b32 v150, v239, v148
	ds_bpermute_b32 v151, v239, v149
	s_and_saveexec_b64 s[6:7], vcc
	s_cbranch_execz .LBB0_1092
	v_lshl_add_u32 v33, v204, 6, s29
	s_waitcnt lgkmcnt(0)
	v_pk_add_f32 v[150:151], v[148:149], v[150:151]
	v_pk_add_f32 v[148:149], v[188:189], v[190:191]
	ds_write_b128 v33, v[148:151]
.LBB0_1092:
	s_or_b64 exec, exec, s[6:7]
	s_mov_b64 s[98:99], 0x80000
	v_lshl_add_u64 v[160:161], v[164:165], 0, s[98:99]
	s_add_i32 m0, s72, 0x1000
	s_nop 0
	global_load_lds_dwordx4 v[160:161], off
	s_mov_b64 s[98:99], 0x80040
	v_lshl_add_u64 v[160:161], v[164:165], 0, s[98:99]
	s_add_i32 m0, s72, 0x1400
	s_nop 0
	global_load_lds_dwordx4 v[160:161], off
	s_mov_b64 s[98:99], 0x80200
	v_lshl_add_u64 v[160:161], v[164:165], 0, s[98:99]
	s_add_i32 m0, s72, 0x1800
	s_nop 0
	global_load_lds_dwordx4 v[160:161], off
	s_mov_b64 s[98:99], 0x80240
	v_lshl_add_u64 v[160:161], v[164:165], 0, s[98:99]
	s_add_i32 m0, s72, 0x1c00
	s_nop 0
	global_load_lds_dwordx4 v[160:161], off
	v_or_b32_e32 v208, 32, v237
	v_add_u32_e32 v174, s17, v208
	v_ashrrev_i32_e32 v175, 31, v174
	v_lshlrev_b64 v[148:149], 12, v[174:175]
	v_lshl_add_u64 v[148:149], s[30:31], 0, v[148:149]
	v_lshl_add_u64 v[172:173], v[34:35], 2, v[148:149]
	s_waitcnt lgkmcnt(0)
	s_add_i32 s98, s72, 0x2000
	s_waitcnt vmcnt(8)
	v_and_b32_e32 v148, 63, v228
	v_lshl_add_u32 v148, v148, 4, s98
	ds_read_b128 v[148:151], v148
	v_and_b32_e32 v160, 63, v228
	v_lshl_add_u32 v160, v160, 4, s98
	ds_read_b128 v[160:163], v160 offset:1024
	v_pk_mul_f32 v[152:153], v[98:99], v[98:99]
	v_pk_mul_f32 v[154:155], v[96:97], v[96:97]
	v_pk_mul_f32 v[190:191], v[94:95], v[142:143]
	v_pk_mov_b32 v[156:157], v[154:155], v[152:153] op_sel:[1,0]
	v_mov_b32_e32 v155, v153
	v_pk_add_f32 v[192:193], v[156:157], v[154:155]
	v_pk_mul_f32 v[178:179], v[96:97], v[144:145]
	v_pk_add_f32 v[192:193], v[192:193], v[192:193] op_sel:[0,1] op_sel_hi:[1,0]
	v_pk_mul_f32 v[206:207], v[92:93], v[140:141]
	v_pk_mul_f32 v[176:177], v[98:99], v[146:147]
	v_mul_f32_e32 v209, v206, v206
	v_mul_f32_e32 v33, v207, v207
	v_pk_mul_f32 v[184:185], v[88:89], v[136:137]
	v_pk_mul_f32 v[182:183], v[90:91], v[138:139]
	v_pk_mul_f32 v[188:189], v[84:85], v[132:133]
	v_pk_mul_f32 v[186:187], v[86:87], v[134:135]
	s_waitcnt lgkmcnt(1)
	v_pk_mul_f32 v[152:153], v[150:151], v[150:151]
	v_pk_mul_f32 v[154:155], v[148:149], v[148:149]
	s_nop 0
	v_pk_mov_b32 v[156:157], v[154:155], v[152:153] op_sel:[1,0]
	v_mov_b32_e32 v155, v153
	v_pk_add_f32 v[152:153], v[156:157], v[154:155]
	v_pk_mul_f32 v[154:155], v[92:93], v[92:93]
	v_pk_add_f32 v[210:211], v[152:153], v[152:153] op_sel_hi:[0,1]
	v_pk_mul_f32 v[152:153], v[94:95], v[94:95]
	v_mul_f32_e32 v210, v84, v84
	v_pk_mov_b32 v[156:157], v[154:155], v[152:153] op_sel:[1,0]
	v_mov_b32_e32 v155, v153
	v_pk_add_f32 v[204:205], v[156:157], v[154:155]
	s_waitcnt lgkmcnt(0)
	v_pk_mul_f32 v[152:153], v[162:163], v[162:163]
	v_pk_mul_f32 v[154:155], v[160:161], v[160:161]
	v_pk_add_f32 v[204:205], v[204:205], v[204:205] op_sel:[0,1] op_sel_hi:[1,0]
	v_pk_mov_b32 v[156:157], v[154:155], v[152:153] op_sel:[1,0]
	v_mov_b32_e32 v155, v153
	v_pk_add_f32 v[152:153], v[156:157], v[154:155]
	s_nop 0
	v_pk_add_f32 v[212:213], v[152:153], v[152:153] op_sel_hi:[0,1]
	v_mul_f32_e32 v152, v190, v190
	v_pk_fma_f32 v[180:181], v[190:191], v[190:191], v[152:153] op_sel_hi:[1,1,0]
	v_and_b32_e32 v152, 63, v228
	v_lshl_add_u32 v152, v152, 4, s98
	ds_read_b128 v[152:155], v152 offset:2048
	v_mul_f32_e32 v212, v85, v85
	v_pk_add_f32 v[210:211], v[210:211], v[212:213]
	v_mul_f32_e32 v180, v89, v89
	s_waitcnt lgkmcnt(0)
	v_mul_f32_e32 v156, v152, v152
	v_pk_fma_f32 v[214:215], v[152:153], v[152:153], v[156:157] op_sel_hi:[1,1,0]
	v_mul_f32_e32 v156, v154, v154
	v_pk_fma_f32 v[216:217], v[154:155], v[154:155], v[156:157] op_sel_hi:[1,1,0]
	v_and_b32_e32 v156, 63, v228
	v_lshl_add_u32 v156, v156, 4, s98
	ds_read_b128 v[156:159], v156 offset:3072
	v_mul_f32_e32 v214, v86, v86
	v_mul_f32_e32 v216, v87, v87
	v_pk_add_f32 v[212:213], v[214:215], v[216:217]
	s_waitcnt lgkmcnt(0)
;     __device__ __forceinline__ void fused(f32x4 (&acc)[2][2][4][2], const Unit& u, int wr, int wc, int fr, int fq, PG8_LAS unsigned char* lds, int wid, int lane) const {
;     ...
;             for (int m = 0; m < 4; ++m) { const int r = ai * HALF + wr * 64 + m * 16 + fr; const size_t off = (size_t)(u.pm * BM + r) * 1024 + col0;
;                 float s0 = 0.f, s1 = 0.f, s2 = 0.f, s3 = 0.f;
; #pragma unroll
;                 for (int bj = 0; bj < 2; ++bj)
; #pragma unroll
;                     for (int n = 0; n < 2; ++n) { const f32x4 bs = *(const f32x4*)(base + off + bj * HALF + n * 16), a = acc[ai][bj][m][n], ag = a * gv[bj][n];
;                         s0 += (a[0] * a[0] + a[1] * a[1]) + (a[2] * a[2] + a[3] * a[3]); s1 += (bs[0] * bs[0] + bs[1] * bs[1]) + (bs[2] * bs[2] + bs[3] * bs[3]);
;                         s2 += (bs[0] * ag[0] + bs[1] * ag[1]) + (bs[2] * ag[2] + bs[3] * ag[3]); s3 += (ag[0] * ag[0] + ag[1] * ag[1]) + (ag[2] * ag[2] + ag[3] * ag[3]); }
;                 s0 += __shfl_xor(s0, 16); s0 += __shfl_xor(s0, 32); s1 += __shfl_xor(s1, 16); s1 += __shfl_xor(s1, 32);
;                 s2 += __shfl_xor(s2, 16); s2 += __shfl_xor(s2, 32); s3 += __shfl_xor(s3, 16); s3 += __shfl_xor(s3, 32);
;                 if (fq == 0) P[r * 4 + wc] = (f32x4){s0, s1, s2, s3};
	v_mul_f32_e32 v218, v156, v156
	v_pk_add_f32 v[210:211], v[210:211], v[212:213]
	v_pk_fma_f32 v[212:213], v[88:89], v[88:89], v[180:181] op_sel_hi:[1,1,0]
	v_mul_f32_e32 v180, v91, v91
	v_mul_f32_e32 v219, v157, v157
	v_mul_f32_e32 v220, v158, v158
	v_mul_f32_e32 v221, v159, v159
	v_pk_fma_f32 v[214:215], v[90:91], v[90:91], v[180:181] op_sel_hi:[1,1,0]
	v_mov_b32_e32 v213, v218
	v_mov_b32_e32 v215, v219
	v_mov_b32_e32 v205, v220
	v_mov_b32_e32 v193, v221
	v_pk_add_f32 v[212:213], v[212:213], v[214:215]
	v_pk_add_f32 v[192:193], v[204:205], v[192:193]
	s_nop 0
	v_pk_add_f32 v[192:193], v[212:213], v[192:193]
	v_mov_b32_e32 v212, v160
	v_pk_add_f32 v[192:193], v[210:211], v[192:193]
	v_mov_b32_e32 v210, v206
	v_mov_b32_e32 v206, v207
	v_mov_b32_e32 v207, v179
	v_mov_b32_e32 v160, v161
	v_mov_b32_e32 v161, v179
	v_mov_b32_e32 v211, v178
	v_mov_b32_e32 v213, v178
	v_pk_mul_f32 v[160:161], v[206:207], v[160:161]
	v_mov_b32_e32 v206, v190
	v_pk_fma_f32 v[160:161], v[210:211], v[212:213], v[160:161]
	v_mov_b32_e32 v210, v162
	v_mov_b32_e32 v190, v191
	v_mov_b32_e32 v191, v177
	v_mov_b32_e32 v162, v163
	v_mov_b32_e32 v163, v177
	v_mov_b32_e32 v207, v176
	v_mov_b32_e32 v211, v176
	v_pk_mul_f32 v[162:163], v[190:191], v[162:163]
	ds_bpermute_b32 v204, v240, v192
	v_pk_fma_f32 v[162:163], v[206:207], v[210:211], v[162:163]
	ds_bpermute_b32 v205, v240, v193
	v_pk_add_f32 v[160:161], v[160:161], v[162:163]
	v_mul_f32_e32 v162, v179, v149
	v_pk_fma_f32 v[148:149], v[178:179], v[148:149], v[162:163] op_sel_hi:[1,1,0]
	v_mul_f32_e32 v162, v177, v151
	v_pk_fma_f32 v[150:151], v[176:177], v[150:151], v[162:163] op_sel_hi:[1,1,0]
	v_mov_b32_e32 v149, v209
	v_mov_b32_e32 v151, v33
	v_pk_add_f32 v[148:149], v[148:149], v[150:151]
	v_pk_mov_b32 v[150:151], v[152:153], v[184:185] op_sel:[1,0]
	v_mov_b32_e32 v153, v185
	v_pk_mul_f32 v[152:153], v[184:185], v[152:153]
	v_mov_b32_e32 v33, v181
	v_pk_fma_f32 v[150:151], v[184:185], v[150:151], v[152:153] op_sel:[1,0,0] op_sel_hi:[0,1,1]
	v_pk_mov_b32 v[152:153], v[154:155], v[182:183] op_sel:[1,0]
	v_mov_b32_e32 v155, v183
	v_pk_mul_f32 v[154:155], v[182:183], v[154:155]
	v_pk_add_f32 v[148:149], v[148:149], v[32:33]
	v_pk_fma_f32 v[152:153], v[182:183], v[152:153], v[154:155] op_sel:[1,0,0] op_sel_hi:[0,1,1]
	v_pk_add_f32 v[148:149], v[160:161], v[148:149]
	v_pk_add_f32 v[150:151], v[150:151], v[152:153]
	s_waitcnt lgkmcnt(0)
	v_pk_add_f32 v[192:193], v[192:193], v[204:205]
	v_pk_add_f32 v[148:149], v[148:149], v[150:151]
	v_pk_mov_b32 v[150:151], v[156:157], v[188:189] op_sel:[1,0]
	v_mov_b32_e32 v157, v189
	v_pk_mul_f32 v[152:153], v[188:189], v[156:157]
	ds_bpermute_b32 v204, v239, v192
	v_pk_fma_f32 v[150:151], v[188:189], v[150:151], v[152:153] op_sel:[1,0,0] op_sel_hi:[0,1,1]
	v_pk_mov_b32 v[152:153], v[158:159], v[186:187] op_sel:[1,0]
	v_mov_b32_e32 v159, v187
	v_pk_mul_f32 v[154:155], v[186:187], v[158:159]
	ds_bpermute_b32 v205, v239, v193
	v_pk_fma_f32 v[152:153], v[186:187], v[152:153], v[154:155] op_sel:[1,0,0] op_sel_hi:[0,1,1]
	v_pk_add_f32 v[150:151], v[150:151], v[152:153]
	s_nop 0
	v_pk_add_f32 v[148:149], v[148:149], v[150:151]
	ds_bpermute_b32 v150, v240, v148
	ds_bpermute_b32 v151, v240, v149
	s_waitcnt lgkmcnt(0)
	v_pk_add_f32 v[148:149], v[148:149], v[150:151]
	ds_bpermute_b32 v150, v239, v148
	ds_bpermute_b32 v151, v239, v149
	s_and_saveexec_b64 s[6:7], vcc
	s_cbranch_execz .LBB0_1094
	v_lshl_add_u32 v33, v208, 6, s29
	s_waitcnt lgkmcnt(0)
	v_pk_add_f32 v[150:151], v[148:149], v[150:151]
	v_pk_add_f32 v[148:149], v[192:193], v[204:205]
	ds_write_b128 v33, v[148:151]
.LBB0_1094:
	s_or_b64 exec, exec, s[6:7]
	s_mov_b64 s[98:99], 0x90000
	v_lshl_add_u64 v[160:161], v[164:165], 0, s[98:99]
	s_add_i32 m0, s72, 0x2000
	s_nop 0
	global_load_lds_dwordx4 v[160:161], off
	s_mov_b64 s[98:99], 0x90040
	v_lshl_add_u64 v[160:161], v[164:165], 0, s[98:99]
	s_add_i32 m0, s72, 0x2400
	s_nop 0
	global_load_lds_dwordx4 v[160:161], off
	s_mov_b64 s[98:99], 0x90200
	v_lshl_add_u64 v[160:161], v[164:165], 0, s[98:99]
	s_add_i32 m0, s72, 0x2800
	s_nop 0
	global_load_lds_dwordx4 v[160:161], off
	s_mov_b64 s[98:99], 0x90240
	v_lshl_add_u64 v[160:161], v[164:165], 0, s[98:99]
	s_add_i32 m0, s72, 0x2c00
	s_nop 0
	global_load_lds_dwordx4 v[160:161], off
	v_or_b32_e32 v212, 48, v237
	v_add_u32_e32 v178, s17, v212
	v_ashrrev_i32_e32 v179, 31, v178
	v_lshlrev_b64 v[148:149], 12, v[178:179]
	v_lshl_add_u64 v[148:149], s[30:31], 0, v[148:149]
	v_lshl_add_u64 v[176:177], v[34:35], 2, v[148:149]
	s_waitcnt lgkmcnt(0)
	s_add_i32 s98, s72, 0x0
	s_waitcnt vmcnt(8)
	v_and_b32_e32 v148, 63, v228
	v_lshl_add_u32 v148, v148, 4, s98
	ds_read_b128 v[148:151], v148
	v_and_b32_e32 v160, 63, v228
	v_lshl_add_u32 v160, v160, 4, s98
	ds_read_b128 v[160:163], v160 offset:1024
	v_pk_mul_f32 v[152:153], v[82:83], v[82:83]
	v_pk_mul_f32 v[154:155], v[80:81], v[80:81]
	v_pk_mul_f32 v[204:205], v[78:79], v[142:143]
	v_pk_mov_b32 v[156:157], v[154:155], v[152:153] op_sel:[1,0]
	v_mov_b32_e32 v155, v153
	v_pk_add_f32 v[206:207], v[156:157], v[154:155]
	v_pk_mul_f32 v[182:183], v[80:81], v[144:145]
	v_pk_add_f32 v[206:207], v[206:207], v[206:207] op_sel:[0,1] op_sel_hi:[1,0]
	v_pk_mul_f32 v[210:211], v[76:77], v[140:141]
	v_pk_mul_f32 v[180:181], v[82:83], v[146:147]
	v_mul_f32_e32 v213, v210, v210
	v_mul_f32_e32 v33, v211, v211
	v_pk_mul_f32 v[188:189], v[72:73], v[136:137]
	v_pk_mul_f32 v[186:187], v[74:75], v[138:139]
	v_pk_mul_f32 v[192:193], v[68:69], v[132:133]
	v_pk_mul_f32 v[190:191], v[70:71], v[134:135]
	s_waitcnt lgkmcnt(1)
;     __device__ __forceinline__ void fused(f32x4 (&acc)[2][2][4][2], const Unit& u, int wr, int wc, int fr, int fq, PG8_LAS unsigned char* lds, int wid, int lane) const {
;     ...
;             for (int m = 0; m < 4; ++m) { const int r = ai * HALF + wr * 64 + m * 16 + fr; const size_t off = (size_t)(u.pm * BM + r) * 1024 + col0;
;                 float s0 = 0.f, s1 = 0.f, s2 = 0.f, s3 = 0.f;
; #pragma unroll
;                 for (int bj = 0; bj < 2; ++bj)
; #pragma unroll
;                     for (int n = 0; n < 2; ++n) { const f32x4 bs = *(const f32x4*)(base + off + bj * HALF + n * 16), a = acc[ai][bj][m][n], ag = a * gv[bj][n];
;                         s0 += (a[0] * a[0] + a[1] * a[1]) + (a[2] * a[2] + a[3] * a[3]); s1 += (bs[0] * bs[0] + bs[1] * bs[1]) + (bs[2] * bs[2] + bs[3] * bs[3]);
;                         s2 += (bs[0] * ag[0] + bs[1] * ag[1]) + (bs[2] * ag[2] + bs[3] * ag[3]); s3 += (ag[0] * ag[0] + ag[1] * ag[1]) + (ag[2] * ag[2] + ag[3] * ag[3]); }
;                 s0 += __shfl_xor(s0, 16); s0 += __shfl_xor(s0, 32); s1 += __shfl_xor(s1, 16); s1 += __shfl_xor(s1, 32);
;                 s2 += __shfl_xor(s2, 16); s2 += __shfl_xor(s2, 32); s3 += __shfl_xor(s3, 16); s3 += __shfl_xor(s3, 32);
;                 if (fq == 0) P[r * 4 + wc] = (f32x4){s0, s1, s2, s3};
	v_pk_mul_f32 v[152:153], v[150:151], v[150:151]
	v_pk_mul_f32 v[154:155], v[148:149], v[148:149]
	s_nop 0
	v_pk_mov_b32 v[156:157], v[154:155], v[152:153] op_sel:[1,0]
	v_mov_b32_e32 v155, v153
	v_pk_add_f32 v[152:153], v[156:157], v[154:155]
	v_pk_mul_f32 v[154:155], v[76:77], v[76:77]
	v_pk_add_f32 v[214:215], v[152:153], v[152:153] op_sel_hi:[0,1]
	v_pk_mul_f32 v[152:153], v[78:79], v[78:79]
	v_mul_f32_e32 v214, v68, v68
	v_pk_mov_b32 v[156:157], v[154:155], v[152:153] op_sel:[1,0]
	v_mov_b32_e32 v155, v153
	v_pk_add_f32 v[208:209], v[156:157], v[154:155]
	s_waitcnt lgkmcnt(0)
	v_pk_mul_f32 v[152:153], v[162:163], v[162:163]
	v_pk_mul_f32 v[154:155], v[160:161], v[160:161]
	v_pk_add_f32 v[208:209], v[208:209], v[208:209] op_sel:[0,1] op_sel_hi:[1,0]
	v_pk_mov_b32 v[156:157], v[154:155], v[152:153] op_sel:[1,0]
	v_mov_b32_e32 v155, v153
	v_pk_add_f32 v[152:153], v[156:157], v[154:155]
	s_nop 0
	v_pk_add_f32 v[216:217], v[152:153], v[152:153] op_sel_hi:[0,1]
	v_mul_f32_e32 v152, v204, v204
	v_pk_fma_f32 v[184:185], v[204:205], v[204:205], v[152:153] op_sel_hi:[1,1,0]
	v_and_b32_e32 v152, 63, v228
	v_lshl_add_u32 v152, v152, 4, s98
	ds_read_b128 v[152:155], v152 offset:2048
	v_mul_f32_e32 v216, v69, v69
	v_pk_add_f32 v[214:215], v[214:215], v[216:217]
	v_mul_f32_e32 v184, v73, v73
	s_waitcnt lgkmcnt(0)
	v_mul_f32_e32 v156, v152, v152
	v_pk_fma_f32 v[218:219], v[152:153], v[152:153], v[156:157] op_sel_hi:[1,1,0]
	v_mul_f32_e32 v156, v154, v154
	v_pk_fma_f32 v[220:221], v[154:155], v[154:155], v[156:157] op_sel_hi:[1,1,0]
	v_and_b32_e32 v156, 63, v228
	v_lshl_add_u32 v156, v156, 4, s98
	ds_read_b128 v[156:159], v156 offset:3072
	v_mul_f32_e32 v218, v70, v70
	v_mul_f32_e32 v220, v71, v71
	v_pk_add_f32 v[216:217], v[218:219], v[220:221]
	s_waitcnt lgkmcnt(0)
	v_mul_f32_e32 v222, v156, v156
	v_pk_add_f32 v[214:215], v[214:215], v[216:217]
	v_pk_fma_f32 v[216:217], v[72:73], v[72:73], v[184:185] op_sel_hi:[1,1,0]
	v_mul_f32_e32 v184, v75, v75
	v_mul_f32_e32 v223, v157, v157
	v_mul_f32_e32 v224, v158, v158
	v_mul_f32_e32 v225, v159, v159
	v_pk_fma_f32 v[218:219], v[74:75], v[74:75], v[184:185] op_sel_hi:[1,1,0]
	v_mov_b32_e32 v217, v222
	v_mov_b32_e32 v219, v223
	v_mov_b32_e32 v209, v224
	v_mov_b32_e32 v207, v225
	v_pk_add_f32 v[216:217], v[216:217], v[218:219]
	v_pk_add_f32 v[206:207], v[208:209], v[206:207]
	s_nop 0
	v_pk_add_f32 v[206:207], v[216:217], v[206:207]
	v_mov_b32_e32 v216, v160
	v_pk_add_f32 v[206:207], v[214:215], v[206:207]
	v_mov_b32_e32 v214, v210
	v_mov_b32_e32 v210, v211
	v_mov_b32_e32 v211, v183
	v_mov_b32_e32 v160, v161
	v_mov_b32_e32 v161, v183
	v_mov_b32_e32 v215, v182
	v_mov_b32_e32 v217, v182
	v_pk_mul_f32 v[160:161], v[210:211], v[160:161]
	v_mov_b32_e32 v210, v204
	v_pk_fma_f32 v[160:161], v[214:215], v[216:217], v[160:161]
	v_mov_b32_e32 v214, v162
	v_mov_b32_e32 v204, v205
	v_mov_b32_e32 v205, v181
	v_mov_b32_e32 v162, v163
	v_mov_b32_e32 v163, v181
	v_mov_b32_e32 v211, v180
	v_mov_b32_e32 v215, v180
	v_pk_mul_f32 v[162:163], v[204:205], v[162:163]
	ds_bpermute_b32 v208, v240, v206
	v_pk_fma_f32 v[162:163], v[210:211], v[214:215], v[162:163]
	ds_bpermute_b32 v209, v240, v207
	v_pk_add_f32 v[160:161], v[160:161], v[162:163]
	v_mul_f32_e32 v162, v183, v149
	v_pk_fma_f32 v[148:149], v[182:183], v[148:149], v[162:163] op_sel_hi:[1,1,0]
	v_mul_f32_e32 v162, v181, v151
	v_pk_fma_f32 v[150:151], v[180:181], v[150:151], v[162:163] op_sel_hi:[1,1,0]
	v_mov_b32_e32 v149, v213
	v_mov_b32_e32 v151, v33
	v_pk_add_f32 v[148:149], v[148:149], v[150:151]
	v_pk_mov_b32 v[150:151], v[152:153], v[188:189] op_sel:[1,0]
	v_mov_b32_e32 v153, v189
	v_pk_mul_f32 v[152:153], v[188:189], v[152:153]
	v_mov_b32_e32 v33, v185
	v_pk_fma_f32 v[150:151], v[188:189], v[150:151], v[152:153] op_sel:[1,0,0] op_sel_hi:[0,1,1]
	v_pk_mov_b32 v[152:153], v[154:155], v[186:187] op_sel:[1,0]
	v_mov_b32_e32 v155, v187
	v_pk_mul_f32 v[154:155], v[186:187], v[154:155]
	v_pk_add_f32 v[148:149], v[148:149], v[32:33]
	v_pk_fma_f32 v[152:153], v[186:187], v[152:153], v[154:155] op_sel:[1,0,0] op_sel_hi:[0,1,1]
	v_pk_add_f32 v[148:149], v[160:161], v[148:149]
	v_pk_add_f32 v[150:151], v[150:151], v[152:153]
	s_waitcnt lgkmcnt(0)
	v_pk_add_f32 v[206:207], v[206:207], v[208:209]
	v_pk_add_f32 v[148:149], v[148:149], v[150:151]
	v_pk_mov_b32 v[150:151], v[156:157], v[192:193] op_sel:[1,0]
	v_mov_b32_e32 v157, v193
	v_pk_mul_f32 v[152:153], v[192:193], v[156:157]
	ds_bpermute_b32 v208, v239, v206
	v_pk_fma_f32 v[150:151], v[192:193], v[150:151], v[152:153] op_sel:[1,0,0] op_sel_hi:[0,1,1]
	v_pk_mov_b32 v[152:153], v[158:159], v[190:191] op_sel:[1,0]
	v_mov_b32_e32 v159, v191
	v_pk_mul_f32 v[154:155], v[190:191], v[158:159]
	ds_bpermute_b32 v209, v239, v207
	v_pk_fma_f32 v[152:153], v[190:191], v[152:153], v[154:155] op_sel:[1,0,0] op_sel_hi:[0,1,1]
	v_pk_add_f32 v[150:151], v[150:151], v[152:153]
	s_nop 0
	v_pk_add_f32 v[148:149], v[148:149], v[150:151]
	ds_bpermute_b32 v150, v240, v148
	ds_bpermute_b32 v151, v240, v149
	s_waitcnt lgkmcnt(0)
	v_pk_add_f32 v[148:149], v[148:149], v[150:151]
	ds_bpermute_b32 v150, v239, v148
	ds_bpermute_b32 v151, v239, v149
	s_and_saveexec_b64 s[6:7], vcc
	s_cbranch_execz .LBB0_1096
	v_lshl_add_u32 v33, v212, 6, s29
	s_waitcnt lgkmcnt(0)
	v_pk_add_f32 v[150:151], v[148:149], v[150:151]
	v_pk_add_f32 v[148:149], v[206:207], v[208:209]
	ds_write_b128 v33, v[148:151]
;     __device__ __forceinline__ void fused(f32x4 (&acc)[2][2][4][2], const Unit& u, int wr, int wc, int fr, int fq, PG8_LAS unsigned char* lds, int wid, int lane) const {
;     ...
;             for (int m = 0; m < 4; ++m) { const int r = ai * HALF + wr * 64 + m * 16 + fr; const size_t off = (size_t)(u.pm * BM + r) * 1024 + col0;
;                 float s0 = 0.f, s1 = 0.f, s2 = 0.f, s3 = 0.f;
; #pragma unroll
;                 for (int bj = 0; bj < 2; ++bj)
; #pragma unroll
;                     for (int n = 0; n < 2; ++n) { const f32x4 bs = *(const f32x4*)(base + off + bj * HALF + n * 16), a = acc[ai][bj][m][n], ag = a * gv[bj][n];
;                         s0 += (a[0] * a[0] + a[1] * a[1]) + (a[2] * a[2] + a[3] * a[3]); s1 += (bs[0] * bs[0] + bs[1] * bs[1]) + (bs[2] * bs[2] + bs[3] * bs[3]);
;                         s2 += (bs[0] * ag[0] + bs[1] * ag[1]) + (bs[2] * ag[2] + bs[3] * ag[3]); s3 += (ag[0] * ag[0] + ag[1] * ag[1]) + (ag[2] * ag[2] + ag[3] * ag[3]); }
;                 s0 += __shfl_xor(s0, 16); s0 += __shfl_xor(s0, 32); s1 += __shfl_xor(s1, 16); s1 += __shfl_xor(s1, 32);
;                 s2 += __shfl_xor(s2, 16); s2 += __shfl_xor(s2, 32); s3 += __shfl_xor(s3, 16); s3 += __shfl_xor(s3, 32);
;                 if (fq == 0) P[r * 4 + wc] = (f32x4){s0, s1, s2, s3};
.LBB0_1096:
	s_or_b64 exec, exec, s[6:7]
	s_mov_b64 s[98:99], 0xa0000
	v_lshl_add_u64 v[160:161], v[164:165], 0, s[98:99]
	s_add_i32 m0, s72, 0x0
	s_nop 0
	global_load_lds_dwordx4 v[160:161], off
	s_mov_b64 s[98:99], 0xa0040
	v_lshl_add_u64 v[160:161], v[164:165], 0, s[98:99]
	s_add_i32 m0, s72, 0x400
	s_nop 0
	global_load_lds_dwordx4 v[160:161], off
	s_mov_b64 s[98:99], 0xa0200
	v_lshl_add_u64 v[160:161], v[164:165], 0, s[98:99]
	s_add_i32 m0, s72, 0x800
	s_nop 0
	global_load_lds_dwordx4 v[160:161], off
	s_mov_b64 s[98:99], 0xa0240
	v_lshl_add_u64 v[160:161], v[164:165], 0, s[98:99]
	s_add_i32 m0, s72, 0xc00
	s_nop 0
	global_load_lds_dwordx4 v[160:161], off
	v_add_u32_e32 v216, 0x80, v237
	v_add_u32_e32 v182, s17, v216
	v_ashrrev_i32_e32 v183, 31, v182
	v_lshlrev_b64 v[148:149], 12, v[182:183]
	v_lshl_add_u64 v[148:149], s[30:31], 0, v[148:149]
	v_lshl_add_u64 v[180:181], v[34:35], 2, v[148:149]
	s_waitcnt lgkmcnt(0)
	s_add_i32 s98, s72, 0x1000
	s_waitcnt vmcnt(8)
	v_and_b32_e32 v148, 63, v228
	v_lshl_add_u32 v148, v148, 4, s98
	ds_read_b128 v[148:151], v148
	v_and_b32_e32 v160, 63, v228
	v_lshl_add_u32 v160, v160, 4, s98
	ds_read_b128 v[160:163], v160 offset:1024
	v_pk_mul_f32 v[152:153], v[66:67], v[66:67]
	v_pk_mul_f32 v[154:155], v[64:65], v[64:65]
	v_pk_mul_f32 v[208:209], v[62:63], v[142:143]
	v_pk_mov_b32 v[156:157], v[154:155], v[152:153] op_sel:[1,0]
	v_mov_b32_e32 v155, v153
	v_pk_add_f32 v[210:211], v[156:157], v[154:155]
	v_pk_mul_f32 v[186:187], v[64:65], v[144:145]
	v_pk_add_f32 v[210:211], v[210:211], v[210:211] op_sel:[0,1] op_sel_hi:[1,0]
	v_pk_mul_f32 v[214:215], v[60:61], v[140:141]
	v_pk_mul_f32 v[184:185], v[66:67], v[146:147]
	v_mul_f32_e32 v217, v214, v214
	v_mul_f32_e32 v33, v215, v215
	v_pk_mul_f32 v[192:193], v[56:57], v[136:137]
	v_pk_mul_f32 v[190:191], v[58:59], v[138:139]
	v_pk_mul_f32 v[206:207], v[52:53], v[132:133]
	v_pk_mul_f32 v[204:205], v[54:55], v[134:135]
	s_waitcnt lgkmcnt(1)
	v_pk_mul_f32 v[152:153], v[150:151], v[150:151]
	v_pk_mul_f32 v[154:155], v[148:149], v[148:149]
	s_nop 0
	v_pk_mov_b32 v[156:157], v[154:155], v[152:153] op_sel:[1,0]
	v_mov_b32_e32 v155, v153
	v_pk_add_f32 v[152:153], v[156:157], v[154:155]
	v_pk_mul_f32 v[154:155], v[60:61], v[60:61]
	v_pk_add_f32 v[218:219], v[152:153], v[152:153] op_sel_hi:[0,1]
	v_pk_mul_f32 v[152:153], v[62:63], v[62:63]
	v_mul_f32_e32 v218, v52, v52
	v_pk_mov_b32 v[156:157], v[154:155], v[152:153] op_sel:[1,0]
	v_mov_b32_e32 v155, v153
	v_pk_add_f32 v[212:213], v[156:157], v[154:155]
	s_waitcnt lgkmcnt(0)
	v_pk_mul_f32 v[152:153], v[162:163], v[162:163]
	v_pk_mul_f32 v[154:155], v[160:161], v[160:161]
	v_pk_add_f32 v[212:213], v[212:213], v[212:213] op_sel:[0,1] op_sel_hi:[1,0]
	v_pk_mov_b32 v[156:157], v[154:155], v[152:153] op_sel:[1,0]
	v_mov_b32_e32 v155, v153
	v_pk_add_f32 v[152:153], v[156:157], v[154:155]
	s_nop 0
	v_pk_add_f32 v[220:221], v[152:153], v[152:153] op_sel_hi:[0,1]
	v_mul_f32_e32 v152, v208, v208
	v_pk_fma_f32 v[188:189], v[208:209], v[208:209], v[152:153] op_sel_hi:[1,1,0]
	v_and_b32_e32 v152, 63, v228
	v_lshl_add_u32 v152, v152, 4, s98
	ds_read_b128 v[152:155], v152 offset:2048
	v_mul_f32_e32 v220, v53, v53
	v_pk_add_f32 v[218:219], v[218:219], v[220:221]
	v_mul_f32_e32 v188, v57, v57
	s_waitcnt lgkmcnt(0)
	v_mul_f32_e32 v156, v152, v152
	v_pk_fma_f32 v[222:223], v[152:153], v[152:153], v[156:157] op_sel_hi:[1,1,0]
	v_mul_f32_e32 v156, v154, v154
	v_pk_fma_f32 v[224:225], v[154:155], v[154:155], v[156:157] op_sel_hi:[1,1,0]
	v_and_b32_e32 v156, 63, v228
	v_lshl_add_u32 v156, v156, 4, s98
	ds_read_b128 v[156:159], v156 offset:3072
	v_mul_f32_e32 v222, v54, v54
	v_mul_f32_e32 v224, v55, v55
	v_pk_add_f32 v[220:221], v[222:223], v[224:225]
	s_waitcnt lgkmcnt(0)
	v_mul_f32_e32 v226, v156, v156
	v_pk_add_f32 v[218:219], v[218:219], v[220:221]
	v_pk_fma_f32 v[220:221], v[56:57], v[56:57], v[188:189] op_sel_hi:[1,1,0]
	v_mul_f32_e32 v188, v59, v59
	v_mul_f32_e32 v227, v157, v157
	v_mul_f32_e32 v230, v158, v158
	v_mul_f32_e32 v241, v159, v159
	v_pk_fma_f32 v[222:223], v[58:59], v[58:59], v[188:189] op_sel_hi:[1,1,0]
	v_mov_b32_e32 v221, v226
	v_mov_b32_e32 v223, v227
	v_mov_b32_e32 v213, v230
	v_mov_b32_e32 v211, v241
	v_pk_add_f32 v[220:221], v[220:221], v[222:223]
	v_pk_add_f32 v[210:211], v[212:213], v[210:211]
	s_nop 0
	v_pk_add_f32 v[210:211], v[220:221], v[210:211]
	v_mov_b32_e32 v220, v160
	v_pk_add_f32 v[210:211], v[218:219], v[210:211]
	v_mov_b32_e32 v218, v214
	v_mov_b32_e32 v214, v215
	v_mov_b32_e32 v215, v187
	v_mov_b32_e32 v160, v161
	v_mov_b32_e32 v161, v187
	v_mov_b32_e32 v219, v186
	v_mov_b32_e32 v221, v186
	v_pk_mul_f32 v[160:161], v[214:215], v[160:161]
	v_mov_b32_e32 v214, v208
	v_pk_fma_f32 v[160:161], v[218:219], v[220:221], v[160:161]
	v_mov_b32_e32 v218, v162
	v_mov_b32_e32 v208, v209
	v_mov_b32_e32 v209, v185
	v_mov_b32_e32 v162, v163
	v_mov_b32_e32 v163, v185
	v_mov_b32_e32 v215, v184
	v_mov_b32_e32 v219, v184
	v_pk_mul_f32 v[162:163], v[208:209], v[162:163]
	ds_bpermute_b32 v212, v240, v210
	v_pk_fma_f32 v[162:163], v[214:215], v[218:219], v[162:163]
	ds_bpermute_b32 v213, v240, v211
	v_pk_add_f32 v[160:161], v[160:161], v[162:163]
	v_mul_f32_e32 v162, v187, v149
	v_pk_fma_f32 v[148:149], v[186:187], v[148:149], v[162:163] op_sel_hi:[1,1,0]
	v_mul_f32_e32 v162, v185, v151
	v_pk_fma_f32 v[150:151], v[184:185], v[150:151], v[162:163] op_sel_hi:[1,1,0]
	v_mov_b32_e32 v149, v217
	v_mov_b32_e32 v151, v33
	v_pk_add_f32 v[148:149], v[148:149], v[150:151]
	v_pk_mov_b32 v[150:151], v[152:153], v[192:193] op_sel:[1,0]
	v_mov_b32_e32 v153, v193
	v_pk_mul_f32 v[152:153], v[192:193], v[152:153]
	v_mov_b32_e32 v33, v189
	v_pk_fma_f32 v[150:151], v[192:193], v[150:151], v[152:153] op_sel:[1,0,0] op_sel_hi:[0,1,1]
	v_pk_mov_b32 v[152:153], v[154:155], v[190:191] op_sel:[1,0]
	v_mov_b32_e32 v155, v191
	v_pk_mul_f32 v[154:155], v[190:191], v[154:155]
	v_pk_add_f32 v[148:149], v[148:149], v[32:33]
	v_pk_fma_f32 v[152:153], v[190:191], v[152:153], v[154:155] op_sel:[1,0,0] op_sel_hi:[0,1,1]
	v_pk_add_f32 v[148:149], v[160:161], v[148:149]
	v_pk_add_f32 v[150:151], v[150:151], v[152:153]
	s_waitcnt lgkmcnt(0)
;     __device__ __forceinline__ void fused(f32x4 (&acc)[2][2][4][2], const Unit& u, int wr, int wc, int fr, int fq, PG8_LAS unsigned char* lds, int wid, int lane) const {
;     ...
;             for (int m = 0; m < 4; ++m) { const int r = ai * HALF + wr * 64 + m * 16 + fr; const size_t off = (size_t)(u.pm * BM + r) * 1024 + col0;
;                 float s0 = 0.f, s1 = 0.f, s2 = 0.f, s3 = 0.f;
; #pragma unroll
;                 for (int bj = 0; bj < 2; ++bj)
; #pragma unroll
;                     for (int n = 0; n < 2; ++n) { const f32x4 bs = *(const f32x4*)(base + off + bj * HALF + n * 16), a = acc[ai][bj][m][n], ag = a * gv[bj][n];
;                         s0 += (a[0] * a[0] + a[1] * a[1]) + (a[2] * a[2] + a[3] * a[3]); s1 += (bs[0] * bs[0] + bs[1] * bs[1]) + (bs[2] * bs[2] + bs[3] * bs[3]);
;                         s2 += (bs[0] * ag[0] + bs[1] * ag[1]) + (bs[2] * ag[2] + bs[3] * ag[3]); s3 += (ag[0] * ag[0] + ag[1] * ag[1]) + (ag[2] * ag[2] + ag[3] * ag[3]); }
;                 s0 += __shfl_xor(s0, 16); s0 += __shfl_xor(s0, 32); s1 += __shfl_xor(s1, 16); s1 += __shfl_xor(s1, 32);
;                 s2 += __shfl_xor(s2, 16); s2 += __shfl_xor(s2, 32); s3 += __shfl_xor(s3, 16); s3 += __shfl_xor(s3, 32);
;                 if (fq == 0) P[r * 4 + wc] = (f32x4){s0, s1, s2, s3};
	v_pk_add_f32 v[210:211], v[210:211], v[212:213]
	v_pk_add_f32 v[148:149], v[148:149], v[150:151]
	v_pk_mov_b32 v[150:151], v[156:157], v[206:207] op_sel:[1,0]
	v_mov_b32_e32 v157, v207
	v_pk_mul_f32 v[152:153], v[206:207], v[156:157]
	ds_bpermute_b32 v212, v239, v210
	v_pk_fma_f32 v[150:151], v[206:207], v[150:151], v[152:153] op_sel:[1,0,0] op_sel_hi:[0,1,1]
	v_pk_mov_b32 v[152:153], v[158:159], v[204:205] op_sel:[1,0]
	v_mov_b32_e32 v159, v205
	v_pk_mul_f32 v[154:155], v[204:205], v[158:159]
	ds_bpermute_b32 v213, v239, v211
	v_pk_fma_f32 v[152:153], v[204:205], v[152:153], v[154:155] op_sel:[1,0,0] op_sel_hi:[0,1,1]
	v_pk_add_f32 v[150:151], v[150:151], v[152:153]
	s_nop 0
	v_pk_add_f32 v[148:149], v[148:149], v[150:151]
	ds_bpermute_b32 v150, v240, v148
	ds_bpermute_b32 v151, v240, v149
	s_waitcnt lgkmcnt(0)
	v_pk_add_f32 v[148:149], v[148:149], v[150:151]
	ds_bpermute_b32 v150, v239, v148
	ds_bpermute_b32 v151, v239, v149
	s_and_saveexec_b64 s[6:7], vcc
	s_cbranch_execz .LBB0_1098
	v_lshl_add_u32 v33, v216, 6, s29
	s_waitcnt lgkmcnt(0)
	v_pk_add_f32 v[150:151], v[148:149], v[150:151]
	v_pk_add_f32 v[148:149], v[210:211], v[212:213]
	ds_write_b128 v33, v[148:151]
.LBB0_1098:
	s_or_b64 exec, exec, s[6:7]
	s_mov_b64 s[98:99], 0xb0000
	v_lshl_add_u64 v[160:161], v[164:165], 0, s[98:99]
	s_add_i32 m0, s72, 0x1000
	s_nop 0
	global_load_lds_dwordx4 v[160:161], off
	s_mov_b64 s[98:99], 0xb0040
	v_lshl_add_u64 v[160:161], v[164:165], 0, s[98:99]
	s_add_i32 m0, s72, 0x1400
	s_nop 0
	global_load_lds_dwordx4 v[160:161], off
	s_mov_b64 s[98:99], 0xb0200
	v_lshl_add_u64 v[160:161], v[164:165], 0, s[98:99]
	s_add_i32 m0, s72, 0x1800
	s_nop 0
	global_load_lds_dwordx4 v[160:161], off
	s_mov_b64 s[98:99], 0xb0240
	v_lshl_add_u64 v[160:161], v[164:165], 0, s[98:99]
	s_add_i32 m0, s72, 0x1c00
	s_nop 0
	global_load_lds_dwordx4 v[160:161], off
	v_add_u32_e32 v220, 0x90, v237
	v_add_u32_e32 v186, s17, v220
	v_ashrrev_i32_e32 v187, 31, v186
	v_lshlrev_b64 v[148:149], 12, v[186:187]
	v_lshl_add_u64 v[148:149], s[30:31], 0, v[148:149]
	v_lshl_add_u64 v[184:185], v[34:35], 2, v[148:149]
	s_waitcnt lgkmcnt(0)
	s_add_i32 s98, s72, 0x2000
	s_waitcnt vmcnt(8)
	v_and_b32_e32 v148, 63, v228
	v_lshl_add_u32 v148, v148, 4, s98
	ds_read_b128 v[148:151], v148
	v_and_b32_e32 v160, 63, v228
	v_lshl_add_u32 v160, v160, 4, s98
	ds_read_b128 v[160:163], v160 offset:1024
	v_pk_mul_f32 v[152:153], v[50:51], v[50:51]
	v_pk_mul_f32 v[154:155], v[48:49], v[48:49]
	v_pk_mul_f32 v[212:213], v[46:47], v[142:143]
	v_pk_mov_b32 v[156:157], v[154:155], v[152:153] op_sel:[1,0]
	v_mov_b32_e32 v155, v153
	v_pk_add_f32 v[214:215], v[156:157], v[154:155]
	v_pk_mul_f32 v[190:191], v[48:49], v[144:145]
	v_pk_add_f32 v[214:215], v[214:215], v[214:215] op_sel:[0,1] op_sel_hi:[1,0]
	v_pk_mul_f32 v[218:219], v[44:45], v[140:141]
	v_pk_mul_f32 v[188:189], v[50:51], v[146:147]
	v_mul_f32_e32 v221, v218, v218
	v_mul_f32_e32 v33, v219, v219
	v_pk_mul_f32 v[206:207], v[40:41], v[136:137]
	v_pk_mul_f32 v[204:205], v[42:43], v[138:139]
	v_pk_mul_f32 v[210:211], v[36:37], v[132:133]
	v_pk_mul_f32 v[208:209], v[38:39], v[134:135]
	s_waitcnt lgkmcnt(1)
	v_pk_mul_f32 v[152:153], v[150:151], v[150:151]
	v_pk_mul_f32 v[154:155], v[148:149], v[148:149]
	s_nop 0
	v_pk_mov_b32 v[156:157], v[154:155], v[152:153] op_sel:[1,0]
	v_mov_b32_e32 v155, v153
	v_pk_add_f32 v[152:153], v[156:157], v[154:155]
	v_pk_mul_f32 v[154:155], v[44:45], v[44:45]
	v_pk_add_f32 v[222:223], v[152:153], v[152:153] op_sel_hi:[0,1]
	v_pk_mul_f32 v[152:153], v[46:47], v[46:47]
	v_mul_f32_e32 v222, v36, v36
	v_pk_mov_b32 v[156:157], v[154:155], v[152:153] op_sel:[1,0]
	v_mov_b32_e32 v155, v153
	v_pk_add_f32 v[216:217], v[156:157], v[154:155]
	s_waitcnt lgkmcnt(0)
	v_pk_mul_f32 v[152:153], v[162:163], v[162:163]
	v_pk_mul_f32 v[154:155], v[160:161], v[160:161]
	v_pk_add_f32 v[216:217], v[216:217], v[216:217] op_sel:[0,1] op_sel_hi:[1,0]
	v_pk_mov_b32 v[156:157], v[154:155], v[152:153] op_sel:[1,0]
	v_mov_b32_e32 v155, v153
	v_pk_add_f32 v[152:153], v[156:157], v[154:155]
	s_nop 0
	v_pk_add_f32 v[224:225], v[152:153], v[152:153] op_sel_hi:[0,1]
	v_mul_f32_e32 v152, v212, v212
	v_pk_fma_f32 v[192:193], v[212:213], v[212:213], v[152:153] op_sel_hi:[1,1,0]
	v_and_b32_e32 v152, 63, v228
	v_lshl_add_u32 v152, v152, 4, s98
	ds_read_b128 v[152:155], v152 offset:2048
	v_mul_f32_e32 v224, v37, v37
	v_pk_add_f32 v[222:223], v[222:223], v[224:225]
	v_mul_f32_e32 v192, v41, v41
	s_waitcnt lgkmcnt(0)
	v_mul_f32_e32 v156, v152, v152
	v_pk_fma_f32 v[226:227], v[152:153], v[152:153], v[156:157] op_sel_hi:[1,1,0]
	v_mul_f32_e32 v156, v154, v154
	v_pk_fma_f32 v[242:243], v[154:155], v[154:155], v[156:157] op_sel_hi:[1,1,0]
	v_and_b32_e32 v156, 63, v228
	v_lshl_add_u32 v156, v156, 4, s98
	ds_read_b128 v[156:159], v156 offset:3072
	v_mul_f32_e32 v226, v38, v38
	v_mul_f32_e32 v242, v39, v39
	v_pk_add_f32 v[224:225], v[226:227], v[242:243]
	s_waitcnt lgkmcnt(0)
;     __device__ __forceinline__ void fused(f32x4 (&acc)[2][2][4][2], const Unit& u, int wr, int wc, int fr, int fq, PG8_LAS unsigned char* lds, int wid, int lane) const {
;     ...
;             for (int m = 0; m < 4; ++m) { const int r = ai * HALF + wr * 64 + m * 16 + fr; const size_t off = (size_t)(u.pm * BM + r) * 1024 + col0;
;                 float s0 = 0.f, s1 = 0.f, s2 = 0.f, s3 = 0.f;
; #pragma unroll
;                 for (int bj = 0; bj < 2; ++bj)
; #pragma unroll
;                     for (int n = 0; n < 2; ++n) { const f32x4 bs = *(const f32x4*)(base + off + bj * HALF + n * 16), a = acc[ai][bj][m][n], ag = a * gv[bj][n];
;                         s0 += (a[0] * a[0] + a[1] * a[1]) + (a[2] * a[2] + a[3] * a[3]); s1 += (bs[0] * bs[0] + bs[1] * bs[1]) + (bs[2] * bs[2] + bs[3] * bs[3]);
;                         s2 += (bs[0] * ag[0] + bs[1] * ag[1]) + (bs[2] * ag[2] + bs[3] * ag[3]); s3 += (ag[0] * ag[0] + ag[1] * ag[1]) + (ag[2] * ag[2] + ag[3] * ag[3]); }
;                 s0 += __shfl_xor(s0, 16); s0 += __shfl_xor(s0, 32); s1 += __shfl_xor(s1, 16); s1 += __shfl_xor(s1, 32);
;                 s2 += __shfl_xor(s2, 16); s2 += __shfl_xor(s2, 32); s3 += __shfl_xor(s3, 16); s3 += __shfl_xor(s3, 32);
;                 if (fq == 0) P[r * 4 + wc] = (f32x4){s0, s1, s2, s3};
	v_mul_f32_e32 v230, v156, v156
	v_pk_add_f32 v[222:223], v[222:223], v[224:225]
	v_pk_fma_f32 v[224:225], v[40:41], v[40:41], v[192:193] op_sel_hi:[1,1,0]
	v_mul_f32_e32 v192, v43, v43
	v_mul_f32_e32 v241, v157, v157
	v_mul_f32_e32 v244, v158, v158
	v_mul_f32_e32 v245, v159, v159
	v_pk_fma_f32 v[226:227], v[42:43], v[42:43], v[192:193] op_sel_hi:[1,1,0]
	v_mov_b32_e32 v225, v230
	v_mov_b32_e32 v227, v241
	v_mov_b32_e32 v217, v244
	v_mov_b32_e32 v215, v245
	v_pk_add_f32 v[224:225], v[224:225], v[226:227]
	v_pk_add_f32 v[214:215], v[216:217], v[214:215]
	s_nop 0
	v_pk_add_f32 v[214:215], v[224:225], v[214:215]
	v_mov_b32_e32 v224, v160
	v_pk_add_f32 v[214:215], v[222:223], v[214:215]
	v_mov_b32_e32 v222, v218
	v_mov_b32_e32 v218, v219
	v_mov_b32_e32 v219, v191
	v_mov_b32_e32 v160, v161
	v_mov_b32_e32 v161, v191
	v_mov_b32_e32 v223, v190
	v_mov_b32_e32 v225, v190
	v_pk_mul_f32 v[160:161], v[218:219], v[160:161]
	v_mov_b32_e32 v218, v212
	v_pk_fma_f32 v[160:161], v[222:223], v[224:225], v[160:161]
	v_mov_b32_e32 v222, v162
	v_mov_b32_e32 v212, v213
	v_mov_b32_e32 v213, v189
	v_mov_b32_e32 v162, v163
	v_mov_b32_e32 v163, v189
	v_mov_b32_e32 v219, v188
	v_mov_b32_e32 v223, v188
	v_pk_mul_f32 v[162:163], v[212:213], v[162:163]
	ds_bpermute_b32 v216, v240, v214
	v_pk_fma_f32 v[162:163], v[218:219], v[222:223], v[162:163]
	ds_bpermute_b32 v217, v240, v215
	v_pk_add_f32 v[160:161], v[160:161], v[162:163]
	v_mul_f32_e32 v162, v191, v149
	v_pk_fma_f32 v[148:149], v[190:191], v[148:149], v[162:163] op_sel_hi:[1,1,0]
	v_mul_f32_e32 v162, v189, v151
	v_pk_fma_f32 v[150:151], v[188:189], v[150:151], v[162:163] op_sel_hi:[1,1,0]
	v_mov_b32_e32 v149, v221
	v_mov_b32_e32 v151, v33
	v_pk_add_f32 v[148:149], v[148:149], v[150:151]
	v_pk_mov_b32 v[150:151], v[152:153], v[206:207] op_sel:[1,0]
	v_mov_b32_e32 v153, v207
	v_pk_mul_f32 v[152:153], v[206:207], v[152:153]
	v_mov_b32_e32 v33, v193
	v_pk_fma_f32 v[150:151], v[206:207], v[150:151], v[152:153] op_sel:[1,0,0] op_sel_hi:[0,1,1]
	v_pk_mov_b32 v[152:153], v[154:155], v[204:205] op_sel:[1,0]
	v_mov_b32_e32 v155, v205
	v_pk_mul_f32 v[154:155], v[204:205], v[154:155]
	v_pk_add_f32 v[148:149], v[148:149], v[32:33]
	v_pk_fma_f32 v[152:153], v[204:205], v[152:153], v[154:155] op_sel:[1,0,0] op_sel_hi:[0,1,1]
	v_pk_add_f32 v[148:149], v[160:161], v[148:149]
	v_pk_add_f32 v[150:151], v[150:151], v[152:153]
	s_waitcnt lgkmcnt(0)
	v_pk_add_f32 v[214:215], v[214:215], v[216:217]
	v_pk_add_f32 v[148:149], v[148:149], v[150:151]
	v_pk_mov_b32 v[150:151], v[156:157], v[210:211] op_sel:[1,0]
	v_mov_b32_e32 v157, v211
	v_pk_mul_f32 v[152:153], v[210:211], v[156:157]
	ds_bpermute_b32 v216, v239, v214
	v_pk_fma_f32 v[150:151], v[210:211], v[150:151], v[152:153] op_sel:[1,0,0] op_sel_hi:[0,1,1]
	v_pk_mov_b32 v[152:153], v[158:159], v[208:209] op_sel:[1,0]
	v_mov_b32_e32 v159, v209
	v_pk_mul_f32 v[154:155], v[208:209], v[158:159]
	ds_bpermute_b32 v217, v239, v215
	v_pk_fma_f32 v[152:153], v[208:209], v[152:153], v[154:155] op_sel:[1,0,0] op_sel_hi:[0,1,1]
	v_pk_add_f32 v[150:151], v[150:151], v[152:153]
	s_nop 0
	v_pk_add_f32 v[148:149], v[148:149], v[150:151]
	ds_bpermute_b32 v150, v240, v148
	ds_bpermute_b32 v151, v240, v149
	s_waitcnt lgkmcnt(0)
	v_pk_add_f32 v[148:149], v[148:149], v[150:151]
	ds_bpermute_b32 v150, v239, v148
	ds_bpermute_b32 v151, v239, v149
	s_and_saveexec_b64 s[6:7], vcc
	s_cbranch_execz .LBB0_1100
	v_lshl_add_u32 v33, v220, 6, s29
	s_waitcnt lgkmcnt(0)
	v_pk_add_f32 v[150:151], v[148:149], v[150:151]
	v_pk_add_f32 v[148:149], v[214:215], v[216:217]
	ds_write_b128 v33, v[148:151]
.LBB0_1100:
	s_or_b64 exec, exec, s[6:7]
	v_add_u32_e32 v224, 0xa0, v237
	v_add_u32_e32 v190, s17, v224
	v_ashrrev_i32_e32 v191, 31, v190
	v_lshlrev_b64 v[148:149], 12, v[190:191]
	v_lshl_add_u64 v[148:149], s[30:31], 0, v[148:149]
	v_lshl_add_u64 v[188:189], v[34:35], 2, v[148:149]
	s_waitcnt lgkmcnt(0)
	s_add_i32 s98, s72, 0x0
	s_waitcnt vmcnt(4)
	v_and_b32_e32 v148, 63, v228
	v_lshl_add_u32 v148, v148, 4, s98
	ds_read_b128 v[148:151], v148
	v_and_b32_e32 v160, 63, v228
	v_lshl_add_u32 v160, v160, 4, s98
	ds_read_b128 v[160:163], v160 offset:1024
	v_pk_mul_f32 v[152:153], v[30:31], v[30:31]
	v_pk_mul_f32 v[154:155], v[28:29], v[28:29]
	v_pk_mul_f32 v[216:217], v[26:27], v[142:143]
	v_pk_mov_b32 v[156:157], v[154:155], v[152:153] op_sel:[1,0]
	v_mov_b32_e32 v155, v153
	v_pk_add_f32 v[218:219], v[156:157], v[154:155]
	v_pk_mul_f32 v[204:205], v[28:29], v[144:145]
	v_pk_add_f32 v[218:219], v[218:219], v[218:219] op_sel:[0,1] op_sel_hi:[1,0]
	v_pk_mul_f32 v[222:223], v[24:25], v[140:141]
	v_pk_mul_f32 v[192:193], v[30:31], v[146:147]
	v_mul_f32_e32 v225, v222, v222
	v_mul_f32_e32 v33, v223, v223
	v_pk_mul_f32 v[210:211], v[20:21], v[136:137]
	v_pk_mul_f32 v[208:209], v[22:23], v[138:139]
	v_pk_mul_f32 v[214:215], v[16:17], v[132:133]
	v_pk_mul_f32 v[212:213], v[18:19], v[134:135]
	s_waitcnt lgkmcnt(1)
	v_pk_mul_f32 v[152:153], v[150:151], v[150:151]
	v_pk_mul_f32 v[154:155], v[148:149], v[148:149]
	s_nop 0
	v_pk_mov_b32 v[156:157], v[154:155], v[152:153] op_sel:[1,0]
	v_mov_b32_e32 v155, v153
	v_pk_add_f32 v[152:153], v[156:157], v[154:155]
	v_pk_mul_f32 v[154:155], v[24:25], v[24:25]
	v_pk_add_f32 v[226:227], v[152:153], v[152:153] op_sel_hi:[0,1]
	v_pk_mul_f32 v[152:153], v[26:27], v[26:27]
	v_mul_f32_e32 v226, v16, v16
	v_pk_mov_b32 v[156:157], v[154:155], v[152:153] op_sel:[1,0]
	v_mov_b32_e32 v155, v153
	v_pk_add_f32 v[220:221], v[156:157], v[154:155]
	s_waitcnt lgkmcnt(0)
;     __device__ __forceinline__ void fused(f32x4 (&acc)[2][2][4][2], const Unit& u, int wr, int wc, int fr, int fq, PG8_LAS unsigned char* lds, int wid, int lane) const {
;     ...
;             for (int m = 0; m < 4; ++m) { const int r = ai * HALF + wr * 64 + m * 16 + fr; const size_t off = (size_t)(u.pm * BM + r) * 1024 + col0;
;                 float s0 = 0.f, s1 = 0.f, s2 = 0.f, s3 = 0.f;
; #pragma unroll
;                 for (int bj = 0; bj < 2; ++bj)
; #pragma unroll
;                     for (int n = 0; n < 2; ++n) { const f32x4 bs = *(const f32x4*)(base + off + bj * HALF + n * 16), a = acc[ai][bj][m][n], ag = a * gv[bj][n];
;                         s0 += (a[0] * a[0] + a[1] * a[1]) + (a[2] * a[2] + a[3] * a[3]); s1 += (bs[0] * bs[0] + bs[1] * bs[1]) + (bs[2] * bs[2] + bs[3] * bs[3]);
;                         s2 += (bs[0] * ag[0] + bs[1] * ag[1]) + (bs[2] * ag[2] + bs[3] * ag[3]); s3 += (ag[0] * ag[0] + ag[1] * ag[1]) + (ag[2] * ag[2] + ag[3] * ag[3]); }
;                 s0 += __shfl_xor(s0, 16); s0 += __shfl_xor(s0, 32); s1 += __shfl_xor(s1, 16); s1 += __shfl_xor(s1, 32);
;                 s2 += __shfl_xor(s2, 16); s2 += __shfl_xor(s2, 32); s3 += __shfl_xor(s3, 16); s3 += __shfl_xor(s3, 32);
;                 if (fq == 0) P[r * 4 + wc] = (f32x4){s0, s1, s2, s3};
	v_pk_mul_f32 v[152:153], v[162:163], v[162:163]
	v_pk_mul_f32 v[154:155], v[160:161], v[160:161]
	v_pk_add_f32 v[220:221], v[220:221], v[220:221] op_sel:[0,1] op_sel_hi:[1,0]
	v_pk_mov_b32 v[156:157], v[154:155], v[152:153] op_sel:[1,0]
	v_mov_b32_e32 v155, v153
	v_pk_add_f32 v[152:153], v[156:157], v[154:155]
	s_nop 0
	v_pk_add_f32 v[242:243], v[152:153], v[152:153] op_sel_hi:[0,1]
	v_mul_f32_e32 v152, v216, v216
	v_pk_fma_f32 v[206:207], v[216:217], v[216:217], v[152:153] op_sel_hi:[1,1,0]
	v_and_b32_e32 v152, 63, v228
	v_lshl_add_u32 v152, v152, 4, s98
	ds_read_b128 v[152:155], v152 offset:2048
	v_mul_f32_e32 v242, v17, v17
	v_pk_add_f32 v[226:227], v[226:227], v[242:243]
	v_mul_f32_e32 v206, v21, v21
	s_waitcnt lgkmcnt(0)
	v_mul_f32_e32 v156, v152, v152
	v_pk_fma_f32 v[244:245], v[152:153], v[152:153], v[156:157] op_sel_hi:[1,1,0]
	v_mul_f32_e32 v156, v154, v154
	v_pk_fma_f32 v[246:247], v[154:155], v[154:155], v[156:157] op_sel_hi:[1,1,0]
	v_and_b32_e32 v156, 63, v228
	v_lshl_add_u32 v156, v156, 4, s98
	ds_read_b128 v[156:159], v156 offset:3072
	v_mul_f32_e32 v244, v18, v18
	v_mul_f32_e32 v246, v19, v19
	v_pk_add_f32 v[242:243], v[244:245], v[246:247]
	s_waitcnt lgkmcnt(0)
	v_mul_f32_e32 v230, v156, v156
	v_pk_add_f32 v[226:227], v[226:227], v[242:243]
	v_pk_fma_f32 v[242:243], v[20:21], v[20:21], v[206:207] op_sel_hi:[1,1,0]
	v_mul_f32_e32 v206, v23, v23
	v_mul_f32_e32 v241, v157, v157
	v_mul_f32_e32 v248, v158, v158
	v_mul_f32_e32 v249, v159, v159
	v_pk_fma_f32 v[244:245], v[22:23], v[22:23], v[206:207] op_sel_hi:[1,1,0]
	v_mov_b32_e32 v243, v230
	v_mov_b32_e32 v245, v241
	v_mov_b32_e32 v221, v248
	v_mov_b32_e32 v219, v249
	v_pk_add_f32 v[242:243], v[242:243], v[244:245]
	v_pk_add_f32 v[218:219], v[220:221], v[218:219]
	s_nop 0
	v_pk_add_f32 v[218:219], v[242:243], v[218:219]
	v_mov_b32_e32 v242, v160
	v_pk_add_f32 v[218:219], v[226:227], v[218:219]
	v_mov_b32_e32 v226, v222
	v_mov_b32_e32 v222, v223
	v_mov_b32_e32 v223, v205
	v_mov_b32_e32 v160, v161
	v_mov_b32_e32 v161, v205
	v_mov_b32_e32 v227, v204
	v_mov_b32_e32 v243, v204
	v_pk_mul_f32 v[160:161], v[222:223], v[160:161]
	v_mov_b32_e32 v222, v216
	v_pk_fma_f32 v[160:161], v[226:227], v[242:243], v[160:161]
	v_mov_b32_e32 v226, v162
	v_mov_b32_e32 v216, v217
	v_mov_b32_e32 v217, v193
	v_mov_b32_e32 v162, v163
	v_mov_b32_e32 v163, v193
	v_mov_b32_e32 v223, v192
	v_mov_b32_e32 v227, v192
	v_pk_mul_f32 v[162:163], v[216:217], v[162:163]
	ds_bpermute_b32 v220, v240, v218
	v_pk_fma_f32 v[162:163], v[222:223], v[226:227], v[162:163]
	ds_bpermute_b32 v221, v240, v219
	v_pk_add_f32 v[160:161], v[160:161], v[162:163]
	v_mul_f32_e32 v162, v205, v149
	v_pk_fma_f32 v[148:149], v[204:205], v[148:149], v[162:163] op_sel_hi:[1,1,0]
	v_mul_f32_e32 v162, v193, v151
	v_pk_fma_f32 v[150:151], v[192:193], v[150:151], v[162:163] op_sel_hi:[1,1,0]
	v_mov_b32_e32 v149, v225
	v_mov_b32_e32 v151, v33
	v_pk_add_f32 v[148:149], v[148:149], v[150:151]
	v_pk_mov_b32 v[150:151], v[152:153], v[210:211] op_sel:[1,0]
	v_mov_b32_e32 v153, v211
	v_pk_mul_f32 v[152:153], v[210:211], v[152:153]
	v_mov_b32_e32 v33, v207
	v_pk_fma_f32 v[150:151], v[210:211], v[150:151], v[152:153] op_sel:[1,0,0] op_sel_hi:[0,1,1]
	v_pk_mov_b32 v[152:153], v[154:155], v[208:209] op_sel:[1,0]
	v_mov_b32_e32 v155, v209
	v_pk_mul_f32 v[154:155], v[208:209], v[154:155]
	v_pk_add_f32 v[148:149], v[148:149], v[32:33]
	v_pk_fma_f32 v[152:153], v[208:209], v[152:153], v[154:155] op_sel:[1,0,0] op_sel_hi:[0,1,1]
	v_pk_add_f32 v[148:149], v[160:161], v[148:149]
	v_pk_add_f32 v[150:151], v[150:151], v[152:153]
	s_waitcnt lgkmcnt(0)
	v_pk_add_f32 v[218:219], v[218:219], v[220:221]
	v_pk_add_f32 v[148:149], v[148:149], v[150:151]
	v_pk_mov_b32 v[150:151], v[156:157], v[214:215] op_sel:[1,0]
	v_mov_b32_e32 v157, v215
	v_pk_mul_f32 v[152:153], v[214:215], v[156:157]
	ds_bpermute_b32 v220, v239, v218
	v_pk_fma_f32 v[150:151], v[214:215], v[150:151], v[152:153] op_sel:[1,0,0] op_sel_hi:[0,1,1]
	v_pk_mov_b32 v[152:153], v[158:159], v[212:213] op_sel:[1,0]
	v_mov_b32_e32 v159, v213
	v_pk_mul_f32 v[154:155], v[212:213], v[158:159]
	ds_bpermute_b32 v221, v239, v219
	v_pk_fma_f32 v[152:153], v[212:213], v[152:153], v[154:155] op_sel:[1,0,0] op_sel_hi:[0,1,1]
	v_pk_add_f32 v[150:151], v[150:151], v[152:153]
	s_nop 0
	v_pk_add_f32 v[148:149], v[148:149], v[150:151]
	ds_bpermute_b32 v150, v240, v148
	ds_bpermute_b32 v151, v240, v149
	s_waitcnt lgkmcnt(0)
	v_pk_add_f32 v[148:149], v[148:149], v[150:151]
	ds_bpermute_b32 v150, v239, v148
	ds_bpermute_b32 v151, v239, v149
	s_and_saveexec_b64 s[6:7], vcc
	s_cbranch_execz .LBB0_1102
	v_lshl_add_u32 v33, v224, 6, s29
	s_waitcnt lgkmcnt(0)
	v_pk_add_f32 v[150:151], v[148:149], v[150:151]
	v_pk_add_f32 v[148:149], v[218:219], v[220:221]
	ds_write_b128 v33, v[148:151]
;     __device__ __forceinline__ void fused(f32x4 (&acc)[2][2][4][2], const Unit& u, int wr, int wc, int fr, int fq, PG8_LAS unsigned char* lds, int wid, int lane) const {
;     ...
;             for (int m = 0; m < 4; ++m) { const int r = ai * HALF + wr * 64 + m * 16 + fr; const size_t off = (size_t)(u.pm * BM + r) * 1024 + col0;
;                 float s0 = 0.f, s1 = 0.f, s2 = 0.f, s3 = 0.f;
; #pragma unroll
;                 for (int bj = 0; bj < 2; ++bj)
; #pragma unroll
;                     for (int n = 0; n < 2; ++n) { const f32x4 bs = *(const f32x4*)(base + off + bj * HALF + n * 16), a = acc[ai][bj][m][n], ag = a * gv[bj][n];
;                         s0 += (a[0] * a[0] + a[1] * a[1]) + (a[2] * a[2] + a[3] * a[3]); s1 += (bs[0] * bs[0] + bs[1] * bs[1]) + (bs[2] * bs[2] + bs[3] * bs[3]);
;                         s2 += (bs[0] * ag[0] + bs[1] * ag[1]) + (bs[2] * ag[2] + bs[3] * ag[3]); s3 += (ag[0] * ag[0] + ag[1] * ag[1]) + (ag[2] * ag[2] + ag[3] * ag[3]); }
;                 s0 += __shfl_xor(s0, 16); s0 += __shfl_xor(s0, 32); s1 += __shfl_xor(s1, 16); s1 += __shfl_xor(s1, 32);
;                 s2 += __shfl_xor(s2, 16); s2 += __shfl_xor(s2, 32); s3 += __shfl_xor(s3, 16); s3 += __shfl_xor(s3, 32);
;                 if (fq == 0) P[r * 4 + wc] = (f32x4){s0, s1, s2, s3};
.LBB0_1102:
	s_or_b64 exec, exec, s[6:7]
	v_add_u32_e32 v241, 0xb0, v237
	v_add_u32_e32 v204, s17, v241
	v_ashrrev_i32_e32 v205, 31, v204
	v_lshlrev_b64 v[148:149], 12, v[204:205]
	v_lshl_add_u64 v[148:149], s[30:31], 0, v[148:149]
	v_lshl_add_u64 v[192:193], v[34:35], 2, v[148:149]
	s_waitcnt lgkmcnt(0)
	s_add_i32 s98, s72, 0x1000
	s_waitcnt vmcnt(0)
	v_and_b32_e32 v148, 63, v228
	v_lshl_add_u32 v148, v148, 4, s98
	ds_read_b128 v[148:151], v148
	v_and_b32_e32 v160, 63, v228
	v_lshl_add_u32 v160, v160, 4, s98
	ds_read_b128 v[160:163], v160 offset:1024
	v_pk_mul_f32 v[152:153], v[14:15], v[14:15]
	v_pk_mul_f32 v[154:155], v[12:13], v[12:13]
	v_pk_mul_f32 v[220:221], v[10:11], v[142:143]
	v_pk_mov_b32 v[156:157], v[154:155], v[152:153] op_sel:[1,0]
	v_mov_b32_e32 v155, v153
	v_pk_add_f32 v[222:223], v[156:157], v[154:155]
	v_pk_mul_f32 v[208:209], v[12:13], v[144:145]
	v_pk_add_f32 v[222:223], v[222:223], v[222:223] op_sel:[0,1] op_sel_hi:[1,0]
	v_pk_mul_f32 v[226:227], v[8:9], v[140:141]
	v_pk_mul_f32 v[206:207], v[14:15], v[146:147]
	v_mul_f32_e32 v242, v226, v226
	v_mul_f32_e32 v33, v227, v227
	v_pk_mul_f32 v[214:215], v[4:5], v[136:137]
	v_pk_mul_f32 v[212:213], v[6:7], v[138:139]
	v_pk_mul_f32 v[218:219], v[0:1], v[132:133]
	v_pk_mul_f32 v[216:217], v[2:3], v[134:135]
	s_waitcnt lgkmcnt(1)
	v_pk_mul_f32 v[152:153], v[150:151], v[150:151]
	v_pk_mul_f32 v[154:155], v[148:149], v[148:149]
	s_nop 0
	v_pk_mov_b32 v[156:157], v[154:155], v[152:153] op_sel:[1,0]
	v_mov_b32_e32 v155, v153
	v_pk_add_f32 v[152:153], v[156:157], v[154:155]
	v_pk_mul_f32 v[154:155], v[8:9], v[8:9]
	v_pk_add_f32 v[244:245], v[152:153], v[152:153] op_sel_hi:[0,1]
	v_pk_mul_f32 v[152:153], v[10:11], v[10:11]
	v_mul_f32_e32 v244, v0, v0
	v_pk_mov_b32 v[156:157], v[154:155], v[152:153] op_sel:[1,0]
	v_mov_b32_e32 v155, v153
	v_pk_add_f32 v[224:225], v[156:157], v[154:155]
	s_waitcnt lgkmcnt(0)
	v_pk_mul_f32 v[152:153], v[162:163], v[162:163]
	v_pk_mul_f32 v[154:155], v[160:161], v[160:161]
	v_pk_add_f32 v[224:225], v[224:225], v[224:225] op_sel:[0,1] op_sel_hi:[1,0]
	v_pk_mov_b32 v[156:157], v[154:155], v[152:153] op_sel:[1,0]
	v_mov_b32_e32 v155, v153
	v_pk_add_f32 v[152:153], v[156:157], v[154:155]
	s_nop 0
	v_pk_add_f32 v[246:247], v[152:153], v[152:153] op_sel_hi:[0,1]
	v_mul_f32_e32 v152, v220, v220
	v_pk_fma_f32 v[210:211], v[220:221], v[220:221], v[152:153] op_sel_hi:[1,1,0]
	v_and_b32_e32 v152, 63, v228
	v_lshl_add_u32 v152, v152, 4, s98
	ds_read_b128 v[152:155], v152 offset:2048
	v_mul_f32_e32 v246, v1, v1
	v_pk_add_f32 v[244:245], v[244:245], v[246:247]
	v_mul_f32_e32 v210, v5, v5
	s_waitcnt lgkmcnt(0)
	v_mul_f32_e32 v156, v152, v152
	v_pk_fma_f32 v[248:249], v[152:153], v[152:153], v[156:157] op_sel_hi:[1,1,0]
	v_mul_f32_e32 v156, v154, v154
	v_pk_fma_f32 v[250:251], v[154:155], v[154:155], v[156:157] op_sel_hi:[1,1,0]
	v_and_b32_e32 v156, 63, v228
	v_lshl_add_u32 v156, v156, 4, s98
	ds_read_b128 v[156:159], v156 offset:3072
	v_mul_f32_e32 v248, v2, v2
	v_mul_f32_e32 v250, v3, v3
	v_pk_add_f32 v[246:247], v[248:249], v[250:251]
	s_waitcnt lgkmcnt(0)
	v_mul_f32_e32 v230, v156, v156
	v_pk_add_f32 v[244:245], v[244:245], v[246:247]
	v_pk_fma_f32 v[246:247], v[4:5], v[4:5], v[210:211] op_sel_hi:[1,1,0]
	v_mul_f32_e32 v210, v7, v7
	v_mul_f32_e32 v243, v157, v157
	v_mul_f32_e32 v252, v158, v158
	v_mul_f32_e32 v253, v159, v159
	v_pk_fma_f32 v[248:249], v[6:7], v[6:7], v[210:211] op_sel_hi:[1,1,0]
	v_mov_b32_e32 v247, v230
	v_mov_b32_e32 v249, v243
	v_mov_b32_e32 v225, v252
	v_mov_b32_e32 v223, v253
	v_pk_add_f32 v[246:247], v[246:247], v[248:249]
	v_pk_add_f32 v[222:223], v[224:225], v[222:223]
	s_nop 0
	v_pk_add_f32 v[222:223], v[246:247], v[222:223]
	v_mov_b32_e32 v246, v160
	v_pk_add_f32 v[222:223], v[244:245], v[222:223]
	v_mov_b32_e32 v244, v226
	v_mov_b32_e32 v226, v227
	v_mov_b32_e32 v227, v209
	v_mov_b32_e32 v160, v161
	v_mov_b32_e32 v161, v209
	v_mov_b32_e32 v245, v208
	v_mov_b32_e32 v247, v208
	v_pk_mul_f32 v[160:161], v[226:227], v[160:161]
	v_mov_b32_e32 v226, v220
	v_pk_fma_f32 v[160:161], v[244:245], v[246:247], v[160:161]
	v_mov_b32_e32 v244, v162
	v_mov_b32_e32 v220, v221
	v_mov_b32_e32 v221, v207
	v_mov_b32_e32 v162, v163
	v_mov_b32_e32 v163, v207
	v_mov_b32_e32 v227, v206
	v_mov_b32_e32 v245, v206
	v_pk_mul_f32 v[162:163], v[220:221], v[162:163]
	ds_bpermute_b32 v224, v240, v222
	v_pk_fma_f32 v[162:163], v[226:227], v[244:245], v[162:163]
	ds_bpermute_b32 v225, v240, v223
	v_pk_add_f32 v[160:161], v[160:161], v[162:163]
	v_mul_f32_e32 v162, v209, v149
	v_pk_fma_f32 v[148:149], v[208:209], v[148:149], v[162:163] op_sel_hi:[1,1,0]
	v_mul_f32_e32 v162, v207, v151
	v_pk_fma_f32 v[150:151], v[206:207], v[150:151], v[162:163] op_sel_hi:[1,1,0]
	v_mov_b32_e32 v149, v242
	v_mov_b32_e32 v151, v33
	v_pk_add_f32 v[148:149], v[148:149], v[150:151]
	v_pk_mov_b32 v[150:151], v[152:153], v[214:215] op_sel:[1,0]
	v_mov_b32_e32 v153, v215
	v_pk_mul_f32 v[152:153], v[214:215], v[152:153]
	v_mov_b32_e32 v33, v211
	v_pk_fma_f32 v[150:151], v[214:215], v[150:151], v[152:153] op_sel:[1,0,0] op_sel_hi:[0,1,1]
	v_pk_mov_b32 v[152:153], v[154:155], v[212:213] op_sel:[1,0]
	v_mov_b32_e32 v155, v213
	v_pk_mul_f32 v[154:155], v[212:213], v[154:155]
	v_pk_add_f32 v[148:149], v[148:149], v[32:33]
	v_pk_fma_f32 v[152:153], v[212:213], v[152:153], v[154:155] op_sel:[1,0,0] op_sel_hi:[0,1,1]
	v_pk_add_f32 v[148:149], v[160:161], v[148:149]
	v_pk_add_f32 v[150:151], v[150:151], v[152:153]
	s_waitcnt lgkmcnt(0)
	v_pk_add_f32 v[222:223], v[222:223], v[224:225]
	v_pk_add_f32 v[148:149], v[148:149], v[150:151]
	v_pk_mov_b32 v[150:151], v[156:157], v[218:219] op_sel:[1,0]
	v_mov_b32_e32 v157, v219
	v_pk_mul_f32 v[152:153], v[218:219], v[156:157]
	ds_bpermute_b32 v224, v239, v222
	v_pk_fma_f32 v[150:151], v[218:219], v[150:151], v[152:153] op_sel:[1,0,0] op_sel_hi:[0,1,1]
	v_pk_mov_b32 v[152:153], v[158:159], v[216:217] op_sel:[1,0]
	v_mov_b32_e32 v159, v217
	v_pk_mul_f32 v[154:155], v[216:217], v[158:159]
	ds_bpermute_b32 v225, v239, v223
	v_pk_fma_f32 v[152:153], v[216:217], v[152:153], v[154:155] op_sel:[1,0,0] op_sel_hi:[0,1,1]
	v_pk_add_f32 v[150:151], v[150:151], v[152:153]
	s_nop 0
	v_pk_add_f32 v[148:149], v[148:149], v[150:151]
	ds_bpermute_b32 v150, v240, v148
	ds_bpermute_b32 v151, v240, v149
	s_waitcnt lgkmcnt(0)
	v_pk_add_f32 v[148:149], v[148:149], v[150:151]
	ds_bpermute_b32 v150, v239, v148
	ds_bpermute_b32 v151, v239, v149
	s_and_saveexec_b64 s[6:7], vcc
	s_cbranch_execz .LBB0_1104
	v_lshl_add_u32 v33, v241, 6, s29
	s_waitcnt lgkmcnt(0)
	v_pk_add_f32 v[150:151], v[148:149], v[150:151]
	v_pk_add_f32 v[148:149], v[222:223], v[224:225]
	ds_write_b128 v33, v[148:151]
